# GEMM K loops: LDS-DMA loads use SGPR-base + 32-bit VGPR offset form, 8 of 16 64-bit VALU address adds per 2 K-tiles dropped (7 GEMM loops)
# speedup vs baseline: 1.0049x; 1.0049x over previous
; #define PG8_STAGE(bufoff, gbase, voff) do { _Pragma("unroll") for (int _i = 0; _i < 2; ++_i) \
;         __builtin_amdgcn_global_load_lds((const unsigned*)((const char*)(gbase) + (voff)[_i]), (PG8_LAS unsigned*)(lds + (bufoff) + ldsw + _i * 8192), 16, 0, 0); } while (0)
; #define PG8_LDA(dst, b, h) do { _Pragma("unroll") for (int m = 0; m < 4; ++m) _Pragma("unroll") for (int k = 0; k < 2; ++k) dst[m][k] = *(const PG8_LAS bf16x8*)(lds + PG8_SA(b, h) + aoff + m * 2048 + k * 1024); } while (0)
; #define PG8_LDB(dst, b, h) do { _Pragma("unroll") for (int n = 0; n < 2; ++n) _Pragma("unroll") for (int k = 0; k < 2; ++k) dst[n][k] = *(const PG8_LAS bf16x8*)(lds + PG8_SB(b, h) + boff + n * 2048 + k * 1024); } while (0)
; #define PG8_MMA(ai, bj, At, Bt) do { __builtin_amdgcn_s_setprio(1); _Pragma("unroll") for (int m = 0; m < 4; ++m) _Pragma("unroll") for (int n = 0; n < 2; ++n) _Pragma("unroll") for (int k = 0; k < 2; ++k) \
;         acc[ai][bj][m][n] = __builtin_amdgcn_mfma_f32_16x16x32_bf16(Bt[n][k], At[m][k], acc[ai][bj][m][n], 0, 0, 0); __builtin_amdgcn_s_setprio(0); } while (0)
; #define PG8_WAIT_V(n) asm volatile("s_waitcnt vmcnt(" #n ")" ::: "memory")
; #define PG8_BAR __builtin_amdgcn_s_barrier()
; template <class Epi, class Sched, bool ALIGN_EPI = false, bool SP2 = false>
; __device__ __forceinline__ void gemm_phase(PG8_LAS unsigned char* lds, const Gemm g, const Sched& S, const Epi& E) {
;     ...
;         for (int t = 0; t < nt; t += 2) {
;             const bool last = (t == nt - 2);
;             const char* a1 = cA + (size_t)(t + 1) * kstep;
;             const char* a2 = last ? nA : cA + (size_t)(t + 2) * kstep; const char* b2 = last ? nB : cB + (size_t)(t + 2) * kstep;
;             const char* a3 = a2 + kstep; const char* b3 = b2 + kstep;
;             if (last && has_next) S.a_ready(nxt);
;             if constexpr (SP2) {
;             PG8_LDB(B0, 0, 0); PG8_LDB(B1, 0, 1); PG8_SCHED; PG8_LDA(At, 0, 0); PG8_STAGE(PG8_SA(1, 1), a1 + hstep, voffA);
;             PG8_WAIT_V(8); PG8_WAIT_L(0); PG8_BAR; PG8_MMA(0, 0, At, B0); PG8_MMA(0, 1, At, B1); PG8_BAR; PG8_SCHED;
;             PG8_LDA(At, 0, 1); PG8_STAGE(PG8_SB(0, 0), b2, voffB); PG8_STAGE(PG8_SB(0, 1), b2 + hstep, voffB); PG8_STAGE(PG8_SA(0, 0), a2, voffA);
;             PG8_WAIT_V(8); PG8_WAIT_L(0); PG8_BAR; PG8_MMA(1, 0, At, B0); PG8_MMA(1, 1, At, B1); PG8_BAR; PG8_SCHED;
.LBB0_120:
	ds_read_b128 v[152:155], v141
	ds_read_b128 v[164:167], v141 offset:1024
	ds_read_b128 v[168:171], v141 offset:2048
	ds_read_b128 v[172:175], v141 offset:3072
	ds_read_b128 v[176:179], v156
	ds_read_b128 v[180:183], v156 offset:1024
	ds_read_b128 v[184:187], v156 offset:2048
	ds_read_b128 v[188:191], v156 offset:3072
	s_add_u32 s36, s84, 0xfff80080
	s_addc_u32 s37, s85, -1
	s_cmp_eq_u32 s97, 28
	s_cselect_b32 s89, s28, s37
	s_cselect_b32 s88, s29, s36
	s_cselect_b32 s87, s73, s83
	s_cselect_b32 s86, s75, s81
	s_add_i32 m0, s9, 0xc000
	ds_read_b128 v[192:195], v157
	ds_read_b128 v[196:199], v157 offset:1024
	ds_read_b128 v[200:203], v157 offset:2048
	ds_read_b128 v[208:211], v157 offset:3072
	ds_read_b128 v[212:215], v157 offset:4096
	ds_read_b128 v[216:219], v157 offset:5120
	ds_read_b128 v[220:223], v157 offset:6144
	ds_read_b128 v[224:227], v157 offset:7168
	global_load_lds_dwordx4 v144, s[84:85]
	s_add_i32 m0, s9, 0xe000
	s_nop 0
	global_load_lds_dwordx4 v146, s[84:85]
	s_waitcnt vmcnt(8)
	s_waitcnt lgkmcnt(0)
	s_barrier
	s_setprio 1
	s_waitcnt lgkmcnt(0)
	v_mfma_f32_16x16x32_bf16 v[126:129], v[152:155], v[192:195], v[126:129]
	v_mfma_f32_16x16x32_bf16 v[122:125], v[168:171], v[192:195], v[122:125]
	v_mfma_f32_16x16x32_bf16 v[110:113], v[152:155], v[200:203], v[110:113]
	v_mfma_f32_16x16x32_bf16 v[106:109], v[168:171], v[200:203], v[106:109]
	v_mfma_f32_16x16x32_bf16 v[94:97], v[152:155], v[212:215], v[94:97]
	v_mfma_f32_16x16x32_bf16 v[90:93], v[168:171], v[212:215], v[90:93]
	v_mfma_f32_16x16x32_bf16 v[78:81], v[152:155], v[220:223], v[78:81]
	v_mfma_f32_16x16x32_bf16 v[74:77], v[168:171], v[220:223], v[74:77]
	v_mfma_f32_16x16x32_bf16 v[126:129], v[164:167], v[196:199], v[126:129]
	v_mfma_f32_16x16x32_bf16 v[122:125], v[172:175], v[196:199], v[122:125]
	v_mfma_f32_16x16x32_bf16 v[110:113], v[164:167], v[208:211], v[110:113]
	v_mfma_f32_16x16x32_bf16 v[106:109], v[172:175], v[208:211], v[106:109]
	v_mfma_f32_16x16x32_bf16 v[94:97], v[164:167], v[216:219], v[94:97]
	v_mfma_f32_16x16x32_bf16 v[90:93], v[172:175], v[216:219], v[90:93]
	v_mfma_f32_16x16x32_bf16 v[78:81], v[164:167], v[224:227], v[78:81]
	v_mfma_f32_16x16x32_bf16 v[74:77], v[172:175], v[224:227], v[74:77]
	s_setprio 0
	s_setprio 1
	v_mfma_f32_16x16x32_bf16 v[118:121], v[176:179], v[192:195], v[118:121]
	v_mfma_f32_16x16x32_bf16 v[114:117], v[184:187], v[192:195], v[114:117]
	v_mfma_f32_16x16x32_bf16 v[102:105], v[176:179], v[200:203], v[102:105]
	v_mfma_f32_16x16x32_bf16 v[98:101], v[184:187], v[200:203], v[98:101]
	v_mfma_f32_16x16x32_bf16 v[86:89], v[176:179], v[212:215], v[86:89]
	v_mfma_f32_16x16x32_bf16 v[82:85], v[184:187], v[212:215], v[82:85]
	v_mfma_f32_16x16x32_bf16 v[70:73], v[176:179], v[220:223], v[70:73]
	v_mfma_f32_16x16x32_bf16 v[66:69], v[184:187], v[220:223], v[66:69]
	v_mfma_f32_16x16x32_bf16 v[118:121], v[180:183], v[196:199], v[118:121]
	v_mfma_f32_16x16x32_bf16 v[114:117], v[188:191], v[196:199], v[114:117]
	v_mfma_f32_16x16x32_bf16 v[102:105], v[180:183], v[208:211], v[102:105]
	v_mfma_f32_16x16x32_bf16 v[98:101], v[188:191], v[208:211], v[98:101]
	v_mfma_f32_16x16x32_bf16 v[86:89], v[180:183], v[216:219], v[86:89]
	v_mfma_f32_16x16x32_bf16 v[82:85], v[188:191], v[216:219], v[82:85]
	v_mfma_f32_16x16x32_bf16 v[70:73], v[180:183], v[224:227], v[70:73]
	v_mfma_f32_16x16x32_bf16 v[66:69], v[188:191], v[224:227], v[66:69]
	s_setprio 0
	s_barrier
	s_add_i32 s36, s58, s8
	v_lshl_add_u64 v[204:205], s[86:87], 0, v[132:133]
	s_mov_b32 m0, s36
	ds_read_b128 v[192:195], v157 offset:16384
	ds_read_b128 v[196:199], v157 offset:17408
	ds_read_b128 v[200:203], v157 offset:18432
	ds_read_b128 v[208:211], v157 offset:19456
	ds_read_b128 v[212:215], v157 offset:20480
	ds_read_b128 v[216:219], v157 offset:21504
	ds_read_b128 v[220:223], v157 offset:22528
	ds_read_b128 v[224:227], v157 offset:23552
	global_load_lds_dwordx4 v[204:205], off
	s_add_i32 m0, s36, 0x2000
	s_add_u32 s36, s86, 0x80000
	v_lshl_add_u64 v[228:229], s[86:87], 0, v[136:137]
	s_addc_u32 s37, s87, 0
	s_add_i32 s40, s59, s8
	global_load_lds_dwordx4 v[228:229], off
	s_mov_b32 m0, s40
	v_lshl_add_u64 v[232:233], s[88:89], 0, v[134:135]
	global_load_lds_dwordx4 v132, s[36:37]
	s_add_i32 m0, s40, 0x2000
	s_nop 0
	global_load_lds_dwordx4 v136, s[36:37]
	v_lshl_add_u64 v[230:231], s[88:89], 0, v[130:131]
	s_mov_b32 m0, s9
	s_nop 0
	global_load_lds_dwordx4 v[230:231], off
	s_mov_b32 m0, s12
	s_nop 0
	global_load_lds_dwordx4 v[232:233], off
	s_waitcnt vmcnt(8)
	s_waitcnt lgkmcnt(0)
	s_barrier
; #define PG8_STAGE(bufoff, gbase, voff) do { _Pragma("unroll") for (int _i = 0; _i < 2; ++_i) \
;         __builtin_amdgcn_global_load_lds((const unsigned*)((const char*)(gbase) + (voff)[_i]), (PG8_LAS unsigned*)(lds + (bufoff) + ldsw + _i * 8192), 16, 0, 0); } while (0)
; #define PG8_LDA(dst, b, h) do { _Pragma("unroll") for (int m = 0; m < 4; ++m) _Pragma("unroll") for (int k = 0; k < 2; ++k) dst[m][k] = *(const PG8_LAS bf16x8*)(lds + PG8_SA(b, h) + aoff + m * 2048 + k * 1024); } while (0)
; #define PG8_LDB(dst, b, h) do { _Pragma("unroll") for (int n = 0; n < 2; ++n) _Pragma("unroll") for (int k = 0; k < 2; ++k) dst[n][k] = *(const PG8_LAS bf16x8*)(lds + PG8_SB(b, h) + boff + n * 2048 + k * 1024); } while (0)
; #define PG8_MMA(ai, bj, At, Bt) do { __builtin_amdgcn_s_setprio(1); _Pragma("unroll") for (int m = 0; m < 4; ++m) _Pragma("unroll") for (int n = 0; n < 2; ++n) _Pragma("unroll") for (int k = 0; k < 2; ++k) \
;         acc[ai][bj][m][n] = __builtin_amdgcn_mfma_f32_16x16x32_bf16(Bt[n][k], At[m][k], acc[ai][bj][m][n], 0, 0, 0); __builtin_amdgcn_s_setprio(0); } while (0)
; #define PG8_WAIT_V(n) asm volatile("s_waitcnt vmcnt(" #n ")" ::: "memory")
; #define PG8_WAIT_L(n) asm volatile("s_waitcnt lgkmcnt(" #n ")" ::: "memory")
; #define PG8_BAR __builtin_amdgcn_s_barrier()
; #define PG8_SCHED __builtin_amdgcn_sched_barrier(0)
; template <class Epi, class Sched, bool ALIGN_EPI = false, bool SP2 = false>
; __device__ __forceinline__ void gemm_phase(PG8_LAS unsigned char* lds, const Gemm g, const Sched& S, const Epi& E) {
;     ...
;             PG8_WAIT_V(8); PG8_WAIT_L(0); PG8_BAR; PG8_MMA(1, 0, At, B0); PG8_MMA(1, 1, At, B1); PG8_BAR; PG8_SCHED;
;             PG8_LDB(B0, 1, 0); PG8_LDB(B1, 1, 1); PG8_SCHED; PG8_LDA(At, 1, 0); PG8_STAGE(PG8_SA(0, 1), a2 + hstep, voffA);
;             PG8_WAIT_V(8); PG8_WAIT_L(0); PG8_BAR; PG8_MMA(0, 0, At, B0); PG8_MMA(0, 1, At, B1); PG8_BAR; PG8_SCHED;
;             PG8_LDA(At, 1, 1); PG8_STAGE(PG8_SB(1, 0), b3, voffB); PG8_STAGE(PG8_SB(1, 1), b3 + hstep, voffB); PG8_STAGE(PG8_SA(1, 0), a3, voffA);
	s_setprio 1
	s_waitcnt lgkmcnt(0)
	v_mfma_f32_16x16x32_bf16 v[62:65], v[152:155], v[192:195], v[62:65]
	v_mfma_f32_16x16x32_bf16 v[58:61], v[168:171], v[192:195], v[58:61]
	v_mfma_f32_16x16x32_bf16 v[46:49], v[152:155], v[200:203], v[46:49]
	v_mfma_f32_16x16x32_bf16 v[42:45], v[168:171], v[200:203], v[42:45]
	v_mfma_f32_16x16x32_bf16 v[30:33], v[152:155], v[212:215], v[30:33]
	v_mfma_f32_16x16x32_bf16 v[26:29], v[168:171], v[212:215], v[26:29]
	v_mfma_f32_16x16x32_bf16 v[14:17], v[152:155], v[220:223], v[14:17]
	v_mfma_f32_16x16x32_bf16 v[10:13], v[168:171], v[220:223], v[10:13]
	v_mfma_f32_16x16x32_bf16 v[62:65], v[164:167], v[196:199], v[62:65]
	v_mfma_f32_16x16x32_bf16 v[58:61], v[172:175], v[196:199], v[58:61]
	v_mfma_f32_16x16x32_bf16 v[46:49], v[164:167], v[208:211], v[46:49]
	v_mfma_f32_16x16x32_bf16 v[42:45], v[172:175], v[208:211], v[42:45]
	v_mfma_f32_16x16x32_bf16 v[30:33], v[164:167], v[216:219], v[30:33]
	v_mfma_f32_16x16x32_bf16 v[26:29], v[172:175], v[216:219], v[26:29]
	v_mfma_f32_16x16x32_bf16 v[14:17], v[164:167], v[224:227], v[14:17]
	v_mfma_f32_16x16x32_bf16 v[10:13], v[172:175], v[224:227], v[10:13]
	s_setprio 0
	s_setprio 1
	v_mfma_f32_16x16x32_bf16 v[54:57], v[176:179], v[192:195], v[54:57]
	v_mfma_f32_16x16x32_bf16 v[50:53], v[184:187], v[192:195], v[50:53]
	v_mfma_f32_16x16x32_bf16 v[38:41], v[176:179], v[200:203], v[38:41]
	v_mfma_f32_16x16x32_bf16 v[34:37], v[184:187], v[200:203], v[34:37]
	v_mfma_f32_16x16x32_bf16 v[22:25], v[176:179], v[212:215], v[22:25]
	v_mfma_f32_16x16x32_bf16 v[18:21], v[184:187], v[212:215], v[18:21]
	v_mfma_f32_16x16x32_bf16 v[6:9], v[176:179], v[220:223], v[6:9]
	v_mfma_f32_16x16x32_bf16 v[2:5], v[184:187], v[220:223], v[2:5]
	v_mfma_f32_16x16x32_bf16 v[54:57], v[180:183], v[196:199], v[54:57]
	v_mfma_f32_16x16x32_bf16 v[50:53], v[188:191], v[196:199], v[50:53]
	v_mfma_f32_16x16x32_bf16 v[38:41], v[180:183], v[208:211], v[38:41]
	v_mfma_f32_16x16x32_bf16 v[34:37], v[188:191], v[208:211], v[34:37]
	v_mfma_f32_16x16x32_bf16 v[22:25], v[180:183], v[216:219], v[22:25]
	v_mfma_f32_16x16x32_bf16 v[18:21], v[188:191], v[216:219], v[18:21]
	v_mfma_f32_16x16x32_bf16 v[6:9], v[180:183], v[224:227], v[6:9]
	v_mfma_f32_16x16x32_bf16 v[2:5], v[188:191], v[224:227], v[2:5]
	s_setprio 0
	s_barrier
	ds_read_b128 v[152:155], v158
	ds_read_b128 v[164:167], v158 offset:1024
	ds_read_b128 v[168:171], v158 offset:2048
	ds_read_b128 v[172:175], v158 offset:3072
	ds_read_b128 v[176:179], v159
	ds_read_b128 v[180:183], v159 offset:1024
	ds_read_b128 v[184:187], v159 offset:2048
	ds_read_b128 v[188:191], v159 offset:3072
	s_add_u32 s36, s88, 0x80000
	s_addc_u32 s37, s89, 0
	s_mov_b32 m0, s13
	ds_read_b128 v[192:195], v157 offset:32768
	ds_read_b128 v[196:199], v157 offset:33792
	ds_read_b128 v[200:203], v157 offset:34816
	ds_read_b128 v[208:211], v157 offset:35840
	ds_read_b128 v[212:215], v157 offset:36864
	ds_read_b128 v[216:219], v157 offset:37888
	ds_read_b128 v[220:223], v157 offset:38912
	ds_read_b128 v[224:227], v157 offset:39936
	global_load_lds_dwordx4 v130, s[36:37]
	s_mov_b32 m0, s14
	s_nop 0
	global_load_lds_dwordx4 v134, s[36:37]
	s_waitcnt vmcnt(8)
	s_waitcnt lgkmcnt(0)
	s_barrier
	s_setprio 1
	s_waitcnt lgkmcnt(0)
	v_mfma_f32_16x16x32_bf16 v[126:129], v[152:155], v[192:195], v[126:129]
	v_mfma_f32_16x16x32_bf16 v[122:125], v[168:171], v[192:195], v[122:125]
	v_mfma_f32_16x16x32_bf16 v[110:113], v[152:155], v[200:203], v[110:113]
	v_mfma_f32_16x16x32_bf16 v[106:109], v[168:171], v[200:203], v[106:109]
	v_mfma_f32_16x16x32_bf16 v[94:97], v[152:155], v[212:215], v[94:97]
	v_mfma_f32_16x16x32_bf16 v[90:93], v[168:171], v[212:215], v[90:93]
	v_mfma_f32_16x16x32_bf16 v[78:81], v[152:155], v[220:223], v[78:81]
	v_mfma_f32_16x16x32_bf16 v[74:77], v[168:171], v[220:223], v[74:77]
	v_mfma_f32_16x16x32_bf16 v[126:129], v[164:167], v[196:199], v[126:129]
	v_mfma_f32_16x16x32_bf16 v[122:125], v[172:175], v[196:199], v[122:125]
	v_mfma_f32_16x16x32_bf16 v[110:113], v[164:167], v[208:211], v[110:113]
	v_mfma_f32_16x16x32_bf16 v[106:109], v[172:175], v[208:211], v[106:109]
	v_mfma_f32_16x16x32_bf16 v[94:97], v[164:167], v[216:219], v[94:97]
	v_mfma_f32_16x16x32_bf16 v[90:93], v[172:175], v[216:219], v[90:93]
	v_mfma_f32_16x16x32_bf16 v[78:81], v[164:167], v[224:227], v[78:81]
	v_mfma_f32_16x16x32_bf16 v[74:77], v[172:175], v[224:227], v[74:77]
	s_setprio 0
	s_setprio 1
	v_mfma_f32_16x16x32_bf16 v[118:121], v[176:179], v[192:195], v[118:121]
	v_mfma_f32_16x16x32_bf16 v[114:117], v[184:187], v[192:195], v[114:117]
	v_mfma_f32_16x16x32_bf16 v[102:105], v[176:179], v[200:203], v[102:105]
	v_mfma_f32_16x16x32_bf16 v[98:101], v[184:187], v[200:203], v[98:101]
	v_mfma_f32_16x16x32_bf16 v[86:89], v[176:179], v[212:215], v[86:89]
	v_mfma_f32_16x16x32_bf16 v[82:85], v[184:187], v[212:215], v[82:85]
	v_mfma_f32_16x16x32_bf16 v[70:73], v[176:179], v[220:223], v[70:73]
	v_mfma_f32_16x16x32_bf16 v[66:69], v[184:187], v[220:223], v[66:69]
	v_mfma_f32_16x16x32_bf16 v[118:121], v[180:183], v[196:199], v[118:121]
	v_mfma_f32_16x16x32_bf16 v[114:117], v[188:191], v[196:199], v[114:117]
	v_mfma_f32_16x16x32_bf16 v[102:105], v[180:183], v[208:211], v[102:105]
	v_mfma_f32_16x16x32_bf16 v[98:101], v[188:191], v[208:211], v[98:101]
	v_mfma_f32_16x16x32_bf16 v[86:89], v[180:183], v[216:219], v[86:89]
	v_mfma_f32_16x16x32_bf16 v[82:85], v[188:191], v[216:219], v[82:85]
	v_mfma_f32_16x16x32_bf16 v[70:73], v[180:183], v[224:227], v[70:73]
	v_mfma_f32_16x16x32_bf16 v[66:69], v[188:191], v[224:227], v[66:69]
	s_setprio 0
	s_barrier
; #define PG8_STAGE(bufoff, gbase, voff) do { _Pragma("unroll") for (int _i = 0; _i < 2; ++_i) \
;         __builtin_amdgcn_global_load_lds((const unsigned*)((const char*)(gbase) + (voff)[_i]), (PG8_LAS unsigned*)(lds + (bufoff) + ldsw + _i * 8192), 16, 0, 0); } while (0)
; #define PG8_LDA(dst, b, h) do { _Pragma("unroll") for (int m = 0; m < 4; ++m) _Pragma("unroll") for (int k = 0; k < 2; ++k) dst[m][k] = *(const PG8_LAS bf16x8*)(lds + PG8_SA(b, h) + aoff + m * 2048 + k * 1024); } while (0)
; #define PG8_MMA(ai, bj, At, Bt) do { __builtin_amdgcn_s_setprio(1); _Pragma("unroll") for (int m = 0; m < 4; ++m) _Pragma("unroll") for (int n = 0; n < 2; ++n) _Pragma("unroll") for (int k = 0; k < 2; ++k) \
;         acc[ai][bj][m][n] = __builtin_amdgcn_mfma_f32_16x16x32_bf16(Bt[n][k], At[m][k], acc[ai][bj][m][n], 0, 0, 0); __builtin_amdgcn_s_setprio(0); } while (0)
; #define PG8_WAIT_V(n) asm volatile("s_waitcnt vmcnt(" #n ")" ::: "memory")
; #define PG8_WAIT_L(n) asm volatile("s_waitcnt lgkmcnt(" #n ")" ::: "memory")
; #define PG8_BAR __builtin_amdgcn_s_barrier()
; #define PG8_SCHED __builtin_amdgcn_sched_barrier(0)
; template <class Epi, class Sched, bool ALIGN_EPI = false, bool SP2 = false>
; __device__ __forceinline__ void gemm_phase(PG8_LAS unsigned char* lds, const Gemm g, const Sched& S, const Epi& E) {
;     ...
;         for (int t = 0; t < nt; t += 2) {
;             const bool last = (t == nt - 2);
;             const char* a1 = cA + (size_t)(t + 1) * kstep;
;             const char* a2 = last ? nA : cA + (size_t)(t + 2) * kstep; const char* b2 = last ? nB : cB + (size_t)(t + 2) * kstep;
;     ...
;             PG8_LDA(At, 1, 1); PG8_STAGE(PG8_SB(1, 0), b3, voffB); PG8_STAGE(PG8_SB(1, 1), b3 + hstep, voffB); PG8_STAGE(PG8_SA(1, 0), a3, voffA);
;             PG8_WAIT_V(8); PG8_WAIT_L(0); PG8_BAR; PG8_MMA(1, 0, At, B0); PG8_MMA(1, 1, At, B1); PG8_BAR; PG8_SCHED;
	s_add_i32 s36, s61, s8
	v_lshl_add_u64 v[204:205], v[204:205], 0, s[22:23]
	s_mov_b32 m0, s36
	ds_read_b128 v[192:195], v157 offset:49152
	ds_read_b128 v[196:199], v157 offset:50176
	ds_read_b128 v[200:203], v157 offset:51200
	ds_read_b128 v[208:211], v157 offset:52224
	ds_read_b128 v[212:215], v157 offset:53248
	ds_read_b128 v[216:219], v157 offset:54272
	ds_read_b128 v[220:223], v157 offset:55296
	ds_read_b128 v[224:227], v157 offset:56320
	global_load_lds_dwordx4 v[204:205], off
	s_add_i32 m0, s36, 0x2000
	s_add_u32 s36, s86, 0x80080
	v_lshl_add_u64 v[204:205], v[228:229], 0, s[22:23]
	s_addc_u32 s37, s87, 0
	s_add_i32 s40, s62, s8
	global_load_lds_dwordx4 v[204:205], off
	s_mov_b32 m0, s40
	s_nop 0
	global_load_lds_dwordx4 v132, s[36:37]
	s_add_i32 m0, s40, 0x2000
	s_nop 0
	global_load_lds_dwordx4 v136, s[36:37]
	v_lshl_add_u64 v[204:205], v[230:231], 0, s[22:23]
	s_mov_b32 m0, s15
	s_nop 0
	global_load_lds_dwordx4 v[204:205], off
	v_lshl_add_u64 v[204:205], v[232:233], 0, s[22:23]
	s_mov_b32 m0, s16
	s_nop 0
	global_load_lds_dwordx4 v[204:205], off
	s_waitcnt vmcnt(8)
	s_waitcnt lgkmcnt(0)
	s_barrier
	s_setprio 1
	s_waitcnt lgkmcnt(0)
	v_mfma_f32_16x16x32_bf16 v[62:65], v[152:155], v[192:195], v[62:65]
	v_mfma_f32_16x16x32_bf16 v[58:61], v[168:171], v[192:195], v[58:61]
	v_mfma_f32_16x16x32_bf16 v[46:49], v[152:155], v[200:203], v[46:49]
	v_mfma_f32_16x16x32_bf16 v[42:45], v[168:171], v[200:203], v[42:45]
	v_mfma_f32_16x16x32_bf16 v[30:33], v[152:155], v[212:215], v[30:33]
	v_mfma_f32_16x16x32_bf16 v[26:29], v[168:171], v[212:215], v[26:29]
	v_mfma_f32_16x16x32_bf16 v[14:17], v[152:155], v[220:223], v[14:17]
	v_mfma_f32_16x16x32_bf16 v[10:13], v[168:171], v[220:223], v[10:13]
	v_mfma_f32_16x16x32_bf16 v[62:65], v[164:167], v[196:199], v[62:65]
	v_mfma_f32_16x16x32_bf16 v[58:61], v[172:175], v[196:199], v[58:61]
	v_mfma_f32_16x16x32_bf16 v[46:49], v[164:167], v[208:211], v[46:49]
	v_mfma_f32_16x16x32_bf16 v[42:45], v[172:175], v[208:211], v[42:45]
	v_mfma_f32_16x16x32_bf16 v[30:33], v[164:167], v[216:219], v[30:33]
	v_mfma_f32_16x16x32_bf16 v[26:29], v[172:175], v[216:219], v[26:29]
	v_mfma_f32_16x16x32_bf16 v[14:17], v[164:167], v[224:227], v[14:17]
	v_mfma_f32_16x16x32_bf16 v[10:13], v[172:175], v[224:227], v[10:13]
	s_setprio 0
	s_setprio 1
	v_mfma_f32_16x16x32_bf16 v[54:57], v[176:179], v[192:195], v[54:57]
	v_mfma_f32_16x16x32_bf16 v[50:53], v[184:187], v[192:195], v[50:53]
	v_mfma_f32_16x16x32_bf16 v[38:41], v[176:179], v[200:203], v[38:41]
	v_mfma_f32_16x16x32_bf16 v[34:37], v[184:187], v[200:203], v[34:37]
	v_mfma_f32_16x16x32_bf16 v[22:25], v[176:179], v[212:215], v[22:25]
	v_mfma_f32_16x16x32_bf16 v[18:21], v[184:187], v[212:215], v[18:21]
	v_mfma_f32_16x16x32_bf16 v[6:9], v[176:179], v[220:223], v[6:9]
	v_mfma_f32_16x16x32_bf16 v[2:5], v[184:187], v[220:223], v[2:5]
	v_mfma_f32_16x16x32_bf16 v[54:57], v[180:183], v[196:199], v[54:57]
	v_mfma_f32_16x16x32_bf16 v[50:53], v[188:191], v[196:199], v[50:53]
	v_mfma_f32_16x16x32_bf16 v[38:41], v[180:183], v[208:211], v[38:41]
	v_mfma_f32_16x16x32_bf16 v[34:37], v[188:191], v[208:211], v[34:37]
	v_mfma_f32_16x16x32_bf16 v[22:25], v[180:183], v[216:219], v[22:25]
	v_mfma_f32_16x16x32_bf16 v[18:21], v[188:191], v[216:219], v[18:21]
	v_mfma_f32_16x16x32_bf16 v[6:9], v[180:183], v[224:227], v[6:9]
	v_mfma_f32_16x16x32_bf16 v[2:5], v[188:191], v[224:227], v[2:5]
	s_setprio 0
	s_barrier
	s_add_i32 s97, s97, 2
	s_add_u32 s84, s84, 0x100
	s_addc_u32 s85, s85, 0
	s_add_u32 s81, s81, 0x100
	s_addc_u32 s83, s83, 0
	s_cmp_gt_u32 s97, 29
	s_cbranch_scc0 .LBB0_120
	s_and_b64 vcc, exec, s[50:51]
	s_cbranch_vccnz .LBB0_125
	v_lshl_add_u32 v152, s82, 8, v1
	s_cmp_gt_i32 s80, 2
	s_mov_b64 s[82:83], -1
	s_cbranch_scc1 .LBB0_126

; #define PG8_STAGE(bufoff, gbase, voff) do { _Pragma("unroll") for (int _i = 0; _i < 2; ++_i) \
;         __builtin_amdgcn_global_load_lds((const unsigned*)((const char*)(gbase) + (voff)[_i]), (PG8_LAS unsigned*)(lds + (bufoff) + ldsw + _i * 8192), 16, 0, 0); } while (0)
; #define PG8_LDA(dst, b, h) do { _Pragma("unroll") for (int m = 0; m < 4; ++m) _Pragma("unroll") for (int k = 0; k < 2; ++k) dst[m][k] = *(const PG8_LAS bf16x8*)(lds + PG8_SA(b, h) + aoff + m * 2048 + k * 1024); } while (0)
; #define PG8_LDB(dst, b, h) do { _Pragma("unroll") for (int n = 0; n < 2; ++n) _Pragma("unroll") for (int k = 0; k < 2; ++k) dst[n][k] = *(const PG8_LAS bf16x8*)(lds + PG8_SB(b, h) + boff + n * 2048 + k * 1024); } while (0)
; #define PG8_MMA(ai, bj, At, Bt) do { __builtin_amdgcn_s_setprio(1); _Pragma("unroll") for (int m = 0; m < 4; ++m) _Pragma("unroll") for (int n = 0; n < 2; ++n) _Pragma("unroll") for (int k = 0; k < 2; ++k) \
;         acc[ai][bj][m][n] = __builtin_amdgcn_mfma_f32_16x16x32_bf16(Bt[n][k], At[m][k], acc[ai][bj][m][n], 0, 0, 0); __builtin_amdgcn_s_setprio(0); } while (0)
; #define PG8_WAIT_V(n) asm volatile("s_waitcnt vmcnt(" #n ")" ::: "memory")
; #define PG8_BAR __builtin_amdgcn_s_barrier()
; template <class Epi, class Sched, bool ALIGN_EPI = false, bool SP2 = false>
; __device__ __forceinline__ void gemm_phase(PG8_LAS unsigned char* lds, const Gemm g, const Sched& S, const Epi& E) {
;     ...
;         for (int t = 0; t < nt; t += 2) {
;             const bool last = (t == nt - 2);
;             const char* a1 = cA + (size_t)(t + 1) * kstep;
;             const char* a2 = last ? nA : cA + (size_t)(t + 2) * kstep; const char* b2 = last ? nB : cB + (size_t)(t + 2) * kstep;
;             const char* a3 = a2 + kstep; const char* b3 = b2 + kstep;
;             if (last && has_next) S.a_ready(nxt);
;             if constexpr (SP2) {
;             PG8_LDB(B0, 0, 0); PG8_LDB(B1, 0, 1); PG8_SCHED; PG8_LDA(At, 0, 0); PG8_STAGE(PG8_SA(1, 1), a1 + hstep, voffA);
;             PG8_WAIT_V(8); PG8_WAIT_L(0); PG8_BAR; PG8_MMA(0, 0, At, B0); PG8_MMA(0, 1, At, B1); PG8_BAR; PG8_SCHED;
;             PG8_LDA(At, 0, 1); PG8_STAGE(PG8_SB(0, 0), b2, voffB); PG8_STAGE(PG8_SB(0, 1), b2 + hstep, voffB); PG8_STAGE(PG8_SA(0, 0), a2, voffA);
;             PG8_WAIT_V(8); PG8_WAIT_L(0); PG8_BAR; PG8_MMA(1, 0, At, B0); PG8_MMA(1, 1, At, B1); PG8_BAR; PG8_SCHED;
.LBB0_716:
	ds_read_b128 v[148:151], v154
	ds_read_b128 v[164:167], v154 offset:1024
	ds_read_b128 v[168:171], v154 offset:2048
	ds_read_b128 v[172:175], v154 offset:3072
	ds_read_b128 v[176:179], v155
	ds_read_b128 v[180:183], v155 offset:1024
	ds_read_b128 v[184:187], v155 offset:2048
	ds_read_b128 v[188:191], v155 offset:3072
	s_add_u32 s68, s66, 0xfff80080
	s_addc_u32 s69, s67, -1
	s_cmp_eq_u32 s78, 28
	s_cselect_b32 s71, s47, s69
	s_cselect_b32 s70, s74, s68
	s_cselect_b32 s69, s45, s77
	s_cselect_b32 s68, s75, s76
	s_add_i32 m0, s13, 0xc000
	ds_read_b128 v[192:195], v156
	ds_read_b128 v[196:199], v156 offset:1024
	ds_read_b128 v[200:203], v156 offset:2048
	ds_read_b128 v[208:211], v156 offset:3072
	ds_read_b128 v[212:215], v156 offset:4096
	ds_read_b128 v[216:219], v156 offset:5120
	ds_read_b128 v[220:223], v156 offset:6144
	ds_read_b128 v[224:227], v156 offset:7168
	global_load_lds_dwordx4 v140, s[66:67]
	s_add_i32 m0, s13, 0xe000
	s_nop 0
	global_load_lds_dwordx4 v142, s[66:67]
	s_waitcnt vmcnt(8)
	s_waitcnt lgkmcnt(0)
	s_barrier
	s_setprio 1
	s_waitcnt lgkmcnt(0)
	v_mfma_f32_16x16x32_bf16 v[126:129], v[148:151], v[192:195], v[126:129]
	v_mfma_f32_16x16x32_bf16 v[122:125], v[168:171], v[192:195], v[122:125]
	v_mfma_f32_16x16x32_bf16 v[110:113], v[148:151], v[200:203], v[110:113]
	v_mfma_f32_16x16x32_bf16 v[106:109], v[168:171], v[200:203], v[106:109]
	v_mfma_f32_16x16x32_bf16 v[94:97], v[148:151], v[212:215], v[94:97]
	v_mfma_f32_16x16x32_bf16 v[90:93], v[168:171], v[212:215], v[90:93]
	v_mfma_f32_16x16x32_bf16 v[78:81], v[148:151], v[220:223], v[78:81]
	v_mfma_f32_16x16x32_bf16 v[74:77], v[168:171], v[220:223], v[74:77]
	v_mfma_f32_16x16x32_bf16 v[126:129], v[164:167], v[196:199], v[126:129]
	v_mfma_f32_16x16x32_bf16 v[122:125], v[172:175], v[196:199], v[122:125]
	v_mfma_f32_16x16x32_bf16 v[110:113], v[164:167], v[208:211], v[110:113]
	v_mfma_f32_16x16x32_bf16 v[106:109], v[172:175], v[208:211], v[106:109]
	v_mfma_f32_16x16x32_bf16 v[94:97], v[164:167], v[216:219], v[94:97]
	v_mfma_f32_16x16x32_bf16 v[90:93], v[172:175], v[216:219], v[90:93]
	v_mfma_f32_16x16x32_bf16 v[78:81], v[164:167], v[224:227], v[78:81]
	v_mfma_f32_16x16x32_bf16 v[74:77], v[172:175], v[224:227], v[74:77]
	s_setprio 0
	s_setprio 1
	v_mfma_f32_16x16x32_bf16 v[118:121], v[176:179], v[192:195], v[118:121]
	v_mfma_f32_16x16x32_bf16 v[114:117], v[184:187], v[192:195], v[114:117]
	v_mfma_f32_16x16x32_bf16 v[102:105], v[176:179], v[200:203], v[102:105]
	v_mfma_f32_16x16x32_bf16 v[98:101], v[184:187], v[200:203], v[98:101]
	v_mfma_f32_16x16x32_bf16 v[86:89], v[176:179], v[212:215], v[86:89]
	v_mfma_f32_16x16x32_bf16 v[82:85], v[184:187], v[212:215], v[82:85]
	v_mfma_f32_16x16x32_bf16 v[70:73], v[176:179], v[220:223], v[70:73]
	v_mfma_f32_16x16x32_bf16 v[66:69], v[184:187], v[220:223], v[66:69]
	v_mfma_f32_16x16x32_bf16 v[118:121], v[180:183], v[196:199], v[118:121]
	v_mfma_f32_16x16x32_bf16 v[114:117], v[188:191], v[196:199], v[114:117]
	v_mfma_f32_16x16x32_bf16 v[102:105], v[180:183], v[208:211], v[102:105]
	v_mfma_f32_16x16x32_bf16 v[98:101], v[188:191], v[208:211], v[98:101]
	v_mfma_f32_16x16x32_bf16 v[86:89], v[180:183], v[216:219], v[86:89]
	v_mfma_f32_16x16x32_bf16 v[82:85], v[188:191], v[216:219], v[82:85]
	v_mfma_f32_16x16x32_bf16 v[70:73], v[180:183], v[224:227], v[70:73]
	v_mfma_f32_16x16x32_bf16 v[66:69], v[188:191], v[224:227], v[66:69]
	s_setprio 0
	s_barrier
	s_add_i32 s79, s58, s12
	v_lshl_add_u64 v[152:153], s[68:69], 0, v[132:133]
	s_mov_b32 m0, s79
	ds_read_b128 v[192:195], v156 offset:16384
	ds_read_b128 v[196:199], v156 offset:17408
	ds_read_b128 v[200:203], v156 offset:18432
	ds_read_b128 v[208:211], v156 offset:19456
	ds_read_b128 v[212:215], v156 offset:20480
	ds_read_b128 v[216:219], v156 offset:21504
	ds_read_b128 v[220:223], v156 offset:22528
	ds_read_b128 v[224:227], v156 offset:23552
	global_load_lds_dwordx4 v[152:153], off
	s_add_i32 m0, s79, 0x2000
	s_add_u32 s80, s68, 0x80000
	v_lshl_add_u64 v[160:161], s[68:69], 0, v[136:137]
	s_addc_u32 s81, s69, 0
	s_add_i32 s79, s59, s12
	global_load_lds_dwordx4 v[160:161], off
	s_mov_b32 m0, s79
	v_lshl_add_u64 v[228:229], s[70:71], 0, v[134:135]
	global_load_lds_dwordx4 v132, s[80:81]
	s_add_i32 m0, s79, 0x2000
	s_nop 0
	global_load_lds_dwordx4 v136, s[80:81]
	v_lshl_add_u64 v[204:205], s[70:71], 0, v[130:131]
	s_mov_b32 m0, s13
	s_nop 0
	global_load_lds_dwordx4 v[204:205], off
	s_mov_b32 m0, s14
	s_nop 0
	global_load_lds_dwordx4 v[228:229], off
	s_waitcnt vmcnt(8)
	s_waitcnt lgkmcnt(0)
	s_barrier
; #define PG8_STAGE(bufoff, gbase, voff) do { _Pragma("unroll") for (int _i = 0; _i < 2; ++_i) \
;         __builtin_amdgcn_global_load_lds((const unsigned*)((const char*)(gbase) + (voff)[_i]), (PG8_LAS unsigned*)(lds + (bufoff) + ldsw + _i * 8192), 16, 0, 0); } while (0)
; #define PG8_LDA(dst, b, h) do { _Pragma("unroll") for (int m = 0; m < 4; ++m) _Pragma("unroll") for (int k = 0; k < 2; ++k) dst[m][k] = *(const PG8_LAS bf16x8*)(lds + PG8_SA(b, h) + aoff + m * 2048 + k * 1024); } while (0)
; #define PG8_LDB(dst, b, h) do { _Pragma("unroll") for (int n = 0; n < 2; ++n) _Pragma("unroll") for (int k = 0; k < 2; ++k) dst[n][k] = *(const PG8_LAS bf16x8*)(lds + PG8_SB(b, h) + boff + n * 2048 + k * 1024); } while (0)
; #define PG8_MMA(ai, bj, At, Bt) do { __builtin_amdgcn_s_setprio(1); _Pragma("unroll") for (int m = 0; m < 4; ++m) _Pragma("unroll") for (int n = 0; n < 2; ++n) _Pragma("unroll") for (int k = 0; k < 2; ++k) \
;         acc[ai][bj][m][n] = __builtin_amdgcn_mfma_f32_16x16x32_bf16(Bt[n][k], At[m][k], acc[ai][bj][m][n], 0, 0, 0); __builtin_amdgcn_s_setprio(0); } while (0)
; #define PG8_WAIT_V(n) asm volatile("s_waitcnt vmcnt(" #n ")" ::: "memory")
; #define PG8_WAIT_L(n) asm volatile("s_waitcnt lgkmcnt(" #n ")" ::: "memory")
; #define PG8_BAR __builtin_amdgcn_s_barrier()
; #define PG8_SCHED __builtin_amdgcn_sched_barrier(0)
; template <class Epi, class Sched, bool ALIGN_EPI = false, bool SP2 = false>
; __device__ __forceinline__ void gemm_phase(PG8_LAS unsigned char* lds, const Gemm g, const Sched& S, const Epi& E) {
;     ...
;             PG8_WAIT_V(8); PG8_WAIT_L(0); PG8_BAR; PG8_MMA(1, 0, At, B0); PG8_MMA(1, 1, At, B1); PG8_BAR; PG8_SCHED;
;             PG8_LDB(B0, 1, 0); PG8_LDB(B1, 1, 1); PG8_SCHED; PG8_LDA(At, 1, 0); PG8_STAGE(PG8_SA(0, 1), a2 + hstep, voffA);
;             PG8_WAIT_V(8); PG8_WAIT_L(0); PG8_BAR; PG8_MMA(0, 0, At, B0); PG8_MMA(0, 1, At, B1); PG8_BAR; PG8_SCHED;
;             PG8_LDA(At, 1, 1); PG8_STAGE(PG8_SB(1, 0), b3, voffB); PG8_STAGE(PG8_SB(1, 1), b3 + hstep, voffB); PG8_STAGE(PG8_SA(1, 0), a3, voffA);
	s_setprio 1
	s_waitcnt lgkmcnt(0)
	v_mfma_f32_16x16x32_bf16 v[62:65], v[148:151], v[192:195], v[62:65]
	v_mfma_f32_16x16x32_bf16 v[58:61], v[168:171], v[192:195], v[58:61]
	v_mfma_f32_16x16x32_bf16 v[46:49], v[148:151], v[200:203], v[46:49]
	v_mfma_f32_16x16x32_bf16 v[42:45], v[168:171], v[200:203], v[42:45]
	v_mfma_f32_16x16x32_bf16 v[30:33], v[148:151], v[212:215], v[30:33]
	v_mfma_f32_16x16x32_bf16 v[26:29], v[168:171], v[212:215], v[26:29]
	v_mfma_f32_16x16x32_bf16 v[14:17], v[148:151], v[220:223], v[14:17]
	v_mfma_f32_16x16x32_bf16 v[10:13], v[168:171], v[220:223], v[10:13]
	v_mfma_f32_16x16x32_bf16 v[62:65], v[164:167], v[196:199], v[62:65]
	v_mfma_f32_16x16x32_bf16 v[58:61], v[172:175], v[196:199], v[58:61]
	v_mfma_f32_16x16x32_bf16 v[46:49], v[164:167], v[208:211], v[46:49]
	v_mfma_f32_16x16x32_bf16 v[42:45], v[172:175], v[208:211], v[42:45]
	v_mfma_f32_16x16x32_bf16 v[30:33], v[164:167], v[216:219], v[30:33]
	v_mfma_f32_16x16x32_bf16 v[26:29], v[172:175], v[216:219], v[26:29]
	v_mfma_f32_16x16x32_bf16 v[14:17], v[164:167], v[224:227], v[14:17]
	v_mfma_f32_16x16x32_bf16 v[10:13], v[172:175], v[224:227], v[10:13]
	s_setprio 0
	s_setprio 1
	v_mfma_f32_16x16x32_bf16 v[54:57], v[176:179], v[192:195], v[54:57]
	v_mfma_f32_16x16x32_bf16 v[50:53], v[184:187], v[192:195], v[50:53]
	v_mfma_f32_16x16x32_bf16 v[38:41], v[176:179], v[200:203], v[38:41]
	v_mfma_f32_16x16x32_bf16 v[34:37], v[184:187], v[200:203], v[34:37]
	v_mfma_f32_16x16x32_bf16 v[22:25], v[176:179], v[212:215], v[22:25]
	v_mfma_f32_16x16x32_bf16 v[18:21], v[184:187], v[212:215], v[18:21]
	v_mfma_f32_16x16x32_bf16 v[6:9], v[176:179], v[220:223], v[6:9]
	v_mfma_f32_16x16x32_bf16 v[2:5], v[184:187], v[220:223], v[2:5]
	v_mfma_f32_16x16x32_bf16 v[54:57], v[180:183], v[196:199], v[54:57]
	v_mfma_f32_16x16x32_bf16 v[50:53], v[188:191], v[196:199], v[50:53]
	v_mfma_f32_16x16x32_bf16 v[38:41], v[180:183], v[208:211], v[38:41]
	v_mfma_f32_16x16x32_bf16 v[34:37], v[188:191], v[208:211], v[34:37]
	v_mfma_f32_16x16x32_bf16 v[22:25], v[180:183], v[216:219], v[22:25]
	v_mfma_f32_16x16x32_bf16 v[18:21], v[188:191], v[216:219], v[18:21]
	v_mfma_f32_16x16x32_bf16 v[6:9], v[180:183], v[224:227], v[6:9]
	v_mfma_f32_16x16x32_bf16 v[2:5], v[188:191], v[224:227], v[2:5]
	s_setprio 0
	s_barrier
	ds_read_b128 v[148:151], v157
	ds_read_b128 v[164:167], v157 offset:1024
	ds_read_b128 v[168:171], v157 offset:2048
	ds_read_b128 v[172:175], v157 offset:3072
	ds_read_b128 v[176:179], v158
	ds_read_b128 v[180:183], v158 offset:1024
	ds_read_b128 v[184:187], v158 offset:2048
	ds_read_b128 v[188:191], v158 offset:3072
	s_add_u32 s70, s70, 0x80000
	s_addc_u32 s71, s71, 0
	s_mov_b32 m0, s15
	ds_read_b128 v[192:195], v156 offset:32768
	ds_read_b128 v[196:199], v156 offset:33792
	ds_read_b128 v[200:203], v156 offset:34816
	ds_read_b128 v[208:211], v156 offset:35840
	ds_read_b128 v[212:215], v156 offset:36864
	ds_read_b128 v[216:219], v156 offset:37888
	ds_read_b128 v[220:223], v156 offset:38912
	ds_read_b128 v[224:227], v156 offset:39936
	global_load_lds_dwordx4 v130, s[70:71]
	s_mov_b32 m0, s16
	s_nop 0
	global_load_lds_dwordx4 v134, s[70:71]
	s_waitcnt vmcnt(8)
	s_waitcnt lgkmcnt(0)
	s_barrier
	s_setprio 1
	s_waitcnt lgkmcnt(0)
	v_mfma_f32_16x16x32_bf16 v[126:129], v[148:151], v[192:195], v[126:129]
	v_mfma_f32_16x16x32_bf16 v[122:125], v[168:171], v[192:195], v[122:125]
	v_mfma_f32_16x16x32_bf16 v[110:113], v[148:151], v[200:203], v[110:113]
	v_mfma_f32_16x16x32_bf16 v[106:109], v[168:171], v[200:203], v[106:109]
	v_mfma_f32_16x16x32_bf16 v[94:97], v[148:151], v[212:215], v[94:97]
	v_mfma_f32_16x16x32_bf16 v[90:93], v[168:171], v[212:215], v[90:93]
	v_mfma_f32_16x16x32_bf16 v[78:81], v[148:151], v[220:223], v[78:81]
	v_mfma_f32_16x16x32_bf16 v[74:77], v[168:171], v[220:223], v[74:77]
	v_mfma_f32_16x16x32_bf16 v[126:129], v[164:167], v[196:199], v[126:129]
	v_mfma_f32_16x16x32_bf16 v[122:125], v[172:175], v[196:199], v[122:125]
	v_mfma_f32_16x16x32_bf16 v[110:113], v[164:167], v[208:211], v[110:113]
	v_mfma_f32_16x16x32_bf16 v[106:109], v[172:175], v[208:211], v[106:109]
	v_mfma_f32_16x16x32_bf16 v[94:97], v[164:167], v[216:219], v[94:97]
	v_mfma_f32_16x16x32_bf16 v[90:93], v[172:175], v[216:219], v[90:93]
	v_mfma_f32_16x16x32_bf16 v[78:81], v[164:167], v[224:227], v[78:81]
	v_mfma_f32_16x16x32_bf16 v[74:77], v[172:175], v[224:227], v[74:77]
	s_setprio 0
	s_setprio 1
	v_mfma_f32_16x16x32_bf16 v[118:121], v[176:179], v[192:195], v[118:121]
	v_mfma_f32_16x16x32_bf16 v[114:117], v[184:187], v[192:195], v[114:117]
	v_mfma_f32_16x16x32_bf16 v[102:105], v[176:179], v[200:203], v[102:105]
	v_mfma_f32_16x16x32_bf16 v[98:101], v[184:187], v[200:203], v[98:101]
	v_mfma_f32_16x16x32_bf16 v[86:89], v[176:179], v[212:215], v[86:89]
	v_mfma_f32_16x16x32_bf16 v[82:85], v[184:187], v[212:215], v[82:85]
	v_mfma_f32_16x16x32_bf16 v[70:73], v[176:179], v[220:223], v[70:73]
	v_mfma_f32_16x16x32_bf16 v[66:69], v[184:187], v[220:223], v[66:69]
	v_mfma_f32_16x16x32_bf16 v[118:121], v[180:183], v[196:199], v[118:121]
	v_mfma_f32_16x16x32_bf16 v[114:117], v[188:191], v[196:199], v[114:117]
	v_mfma_f32_16x16x32_bf16 v[102:105], v[180:183], v[208:211], v[102:105]
	v_mfma_f32_16x16x32_bf16 v[98:101], v[188:191], v[208:211], v[98:101]
	v_mfma_f32_16x16x32_bf16 v[86:89], v[180:183], v[216:219], v[86:89]
	v_mfma_f32_16x16x32_bf16 v[82:85], v[188:191], v[216:219], v[82:85]
	v_mfma_f32_16x16x32_bf16 v[70:73], v[180:183], v[224:227], v[70:73]
	v_mfma_f32_16x16x32_bf16 v[66:69], v[188:191], v[224:227], v[66:69]
	s_setprio 0
	s_barrier
; #define PG8_STAGE(bufoff, gbase, voff) do { _Pragma("unroll") for (int _i = 0; _i < 2; ++_i) \
;         __builtin_amdgcn_global_load_lds((const unsigned*)((const char*)(gbase) + (voff)[_i]), (PG8_LAS unsigned*)(lds + (bufoff) + ldsw + _i * 8192), 16, 0, 0); } while (0)
; #define PG8_LDA(dst, b, h) do { _Pragma("unroll") for (int m = 0; m < 4; ++m) _Pragma("unroll") for (int k = 0; k < 2; ++k) dst[m][k] = *(const PG8_LAS bf16x8*)(lds + PG8_SA(b, h) + aoff + m * 2048 + k * 1024); } while (0)
; #define PG8_MMA(ai, bj, At, Bt) do { __builtin_amdgcn_s_setprio(1); _Pragma("unroll") for (int m = 0; m < 4; ++m) _Pragma("unroll") for (int n = 0; n < 2; ++n) _Pragma("unroll") for (int k = 0; k < 2; ++k) \
;         acc[ai][bj][m][n] = __builtin_amdgcn_mfma_f32_16x16x32_bf16(Bt[n][k], At[m][k], acc[ai][bj][m][n], 0, 0, 0); __builtin_amdgcn_s_setprio(0); } while (0)
; #define PG8_WAIT_V(n) asm volatile("s_waitcnt vmcnt(" #n ")" ::: "memory")
; #define PG8_WAIT_L(n) asm volatile("s_waitcnt lgkmcnt(" #n ")" ::: "memory")
; #define PG8_BAR __builtin_amdgcn_s_barrier()
; #define PG8_SCHED __builtin_amdgcn_sched_barrier(0)
; template <class Epi, class Sched, bool ALIGN_EPI = false, bool SP2 = false>
; __device__ __forceinline__ void gemm_phase(PG8_LAS unsigned char* lds, const Gemm g, const Sched& S, const Epi& E) {
;     ...
;         for (int t = 0; t < nt; t += 2) {
;             const bool last = (t == nt - 2);
;             const char* a1 = cA + (size_t)(t + 1) * kstep;
;             const char* a2 = last ? nA : cA + (size_t)(t + 2) * kstep; const char* b2 = last ? nB : cB + (size_t)(t + 2) * kstep;
;     ...
;             PG8_LDA(At, 1, 1); PG8_STAGE(PG8_SB(1, 0), b3, voffB); PG8_STAGE(PG8_SB(1, 1), b3 + hstep, voffB); PG8_STAGE(PG8_SA(1, 0), a3, voffA);
;             PG8_WAIT_V(8); PG8_WAIT_L(0); PG8_BAR; PG8_MMA(1, 0, At, B0); PG8_MMA(1, 1, At, B1); PG8_BAR; PG8_SCHED;
	s_add_i32 s70, s61, s12
	v_lshl_add_u64 v[152:153], v[152:153], 0, s[6:7]
	s_mov_b32 m0, s70
	ds_read_b128 v[192:195], v156 offset:49152
	ds_read_b128 v[196:199], v156 offset:50176
	ds_read_b128 v[200:203], v156 offset:51200
	ds_read_b128 v[208:211], v156 offset:52224
	ds_read_b128 v[212:215], v156 offset:53248
	ds_read_b128 v[216:219], v156 offset:54272
	ds_read_b128 v[220:223], v156 offset:55296
	ds_read_b128 v[224:227], v156 offset:56320
	global_load_lds_dwordx4 v[152:153], off
	s_add_i32 m0, s70, 0x2000
	s_add_u32 s68, s68, 0x80080
	v_lshl_add_u64 v[152:153], v[160:161], 0, s[6:7]
	s_addc_u32 s69, s69, 0
	s_add_i32 s70, s62, s12
	global_load_lds_dwordx4 v[152:153], off
	s_mov_b32 m0, s70
	s_nop 0
	global_load_lds_dwordx4 v132, s[68:69]
	s_add_i32 m0, s70, 0x2000
	s_nop 0
	global_load_lds_dwordx4 v136, s[68:69]
	v_lshl_add_u64 v[152:153], v[204:205], 0, s[6:7]
	s_mov_b32 m0, s17
	s_nop 0
	global_load_lds_dwordx4 v[152:153], off
	v_lshl_add_u64 v[152:153], v[228:229], 0, s[6:7]
	s_mov_b32 m0, s33
	s_nop 0
	global_load_lds_dwordx4 v[152:153], off
	s_waitcnt vmcnt(8)
	s_waitcnt lgkmcnt(0)
	s_barrier
	s_setprio 1
	s_waitcnt lgkmcnt(0)
	v_mfma_f32_16x16x32_bf16 v[62:65], v[148:151], v[192:195], v[62:65]
	v_mfma_f32_16x16x32_bf16 v[58:61], v[168:171], v[192:195], v[58:61]
	v_mfma_f32_16x16x32_bf16 v[46:49], v[148:151], v[200:203], v[46:49]
	v_mfma_f32_16x16x32_bf16 v[42:45], v[168:171], v[200:203], v[42:45]
	v_mfma_f32_16x16x32_bf16 v[30:33], v[148:151], v[212:215], v[30:33]
	v_mfma_f32_16x16x32_bf16 v[26:29], v[168:171], v[212:215], v[26:29]
	v_mfma_f32_16x16x32_bf16 v[14:17], v[148:151], v[220:223], v[14:17]
	v_mfma_f32_16x16x32_bf16 v[10:13], v[168:171], v[220:223], v[10:13]
	v_mfma_f32_16x16x32_bf16 v[62:65], v[164:167], v[196:199], v[62:65]
	v_mfma_f32_16x16x32_bf16 v[58:61], v[172:175], v[196:199], v[58:61]
	v_mfma_f32_16x16x32_bf16 v[46:49], v[164:167], v[208:211], v[46:49]
	v_mfma_f32_16x16x32_bf16 v[42:45], v[172:175], v[208:211], v[42:45]
	v_mfma_f32_16x16x32_bf16 v[30:33], v[164:167], v[216:219], v[30:33]
	v_mfma_f32_16x16x32_bf16 v[26:29], v[172:175], v[216:219], v[26:29]
	v_mfma_f32_16x16x32_bf16 v[14:17], v[164:167], v[224:227], v[14:17]
	v_mfma_f32_16x16x32_bf16 v[10:13], v[172:175], v[224:227], v[10:13]
	s_setprio 0
	s_setprio 1
	v_mfma_f32_16x16x32_bf16 v[54:57], v[176:179], v[192:195], v[54:57]
	v_mfma_f32_16x16x32_bf16 v[50:53], v[184:187], v[192:195], v[50:53]
	v_mfma_f32_16x16x32_bf16 v[38:41], v[176:179], v[200:203], v[38:41]
	v_mfma_f32_16x16x32_bf16 v[34:37], v[184:187], v[200:203], v[34:37]
	v_mfma_f32_16x16x32_bf16 v[22:25], v[176:179], v[212:215], v[22:25]
	v_mfma_f32_16x16x32_bf16 v[18:21], v[184:187], v[212:215], v[18:21]
	v_mfma_f32_16x16x32_bf16 v[6:9], v[176:179], v[220:223], v[6:9]
	v_mfma_f32_16x16x32_bf16 v[2:5], v[184:187], v[220:223], v[2:5]
	v_mfma_f32_16x16x32_bf16 v[54:57], v[180:183], v[196:199], v[54:57]
	v_mfma_f32_16x16x32_bf16 v[50:53], v[188:191], v[196:199], v[50:53]
	v_mfma_f32_16x16x32_bf16 v[38:41], v[180:183], v[208:211], v[38:41]
	v_mfma_f32_16x16x32_bf16 v[34:37], v[188:191], v[208:211], v[34:37]
	v_mfma_f32_16x16x32_bf16 v[22:25], v[180:183], v[216:219], v[22:25]
	v_mfma_f32_16x16x32_bf16 v[18:21], v[188:191], v[216:219], v[18:21]
	v_mfma_f32_16x16x32_bf16 v[6:9], v[180:183], v[224:227], v[6:9]
	v_mfma_f32_16x16x32_bf16 v[2:5], v[188:191], v[224:227], v[2:5]
	s_setprio 0
	s_barrier
	s_add_i32 s78, s78, 2
	s_add_u32 s66, s66, 0x100
	s_addc_u32 s67, s67, 0
	s_add_u32 s76, s76, 0x100
	s_addc_u32 s77, s77, 0
	s_cmp_gt_u32 s78, 29
	s_cbranch_scc0 .LBB0_716
	s_and_b64 vcc, exec, s[36:37]
	s_cbranch_vccz .LBB0_719
	s_barrier

; #define PG8_STAGE(bufoff, gbase, voff) do { _Pragma("unroll") for (int _i = 0; _i < 2; ++_i) \
;         __builtin_amdgcn_global_load_lds((const unsigned*)((const char*)(gbase) + (voff)[_i]), (PG8_LAS unsigned*)(lds + (bufoff) + ldsw + _i * 8192), 16, 0, 0); } while (0)
; #define PG8_LDA(dst, b, h) do { _Pragma("unroll") for (int m = 0; m < 4; ++m) _Pragma("unroll") for (int k = 0; k < 2; ++k) dst[m][k] = *(const PG8_LAS bf16x8*)(lds + PG8_SA(b, h) + aoff + m * 2048 + k * 1024); } while (0)
; #define PG8_LDB(dst, b, h) do { _Pragma("unroll") for (int n = 0; n < 2; ++n) _Pragma("unroll") for (int k = 0; k < 2; ++k) dst[n][k] = *(const PG8_LAS bf16x8*)(lds + PG8_SB(b, h) + boff + n * 2048 + k * 1024); } while (0)
; #define PG8_MMA(ai, bj, At, Bt) do { __builtin_amdgcn_s_setprio(1); _Pragma("unroll") for (int m = 0; m < 4; ++m) _Pragma("unroll") for (int n = 0; n < 2; ++n) _Pragma("unroll") for (int k = 0; k < 2; ++k) \
;         acc[ai][bj][m][n] = __builtin_amdgcn_mfma_f32_16x16x32_bf16(Bt[n][k], At[m][k], acc[ai][bj][m][n], 0, 0, 0); __builtin_amdgcn_s_setprio(0); } while (0)
; #define PG8_WAIT_V(n) asm volatile("s_waitcnt vmcnt(" #n ")" ::: "memory")
; #define PG8_BAR __builtin_amdgcn_s_barrier()
; template <class Epi, class Sched, bool ALIGN_EPI = false, bool SP2 = false>
; __device__ __forceinline__ void gemm_phase(PG8_LAS unsigned char* lds, const Gemm g, const Sched& S, const Epi& E) {
;     ...
;         for (int t = 0; t < nt; t += 2) {
;             const bool last = (t == nt - 2);
;             const char* a1 = cA + (size_t)(t + 1) * kstep;
;             const char* a2 = last ? nA : cA + (size_t)(t + 2) * kstep; const char* b2 = last ? nB : cB + (size_t)(t + 2) * kstep;
;             const char* a3 = a2 + kstep; const char* b3 = b2 + kstep;
;             if (last && has_next) S.a_ready(nxt);
;             if constexpr (SP2) {
;             PG8_LDB(B0, 0, 0); PG8_LDB(B1, 0, 1); PG8_SCHED; PG8_LDA(At, 0, 0); PG8_STAGE(PG8_SA(1, 1), a1 + hstep, voffA);
;             PG8_WAIT_V(8); PG8_WAIT_L(0); PG8_BAR; PG8_MMA(0, 0, At, B0); PG8_MMA(0, 1, At, B1); PG8_BAR; PG8_SCHED;
;             PG8_LDA(At, 0, 1); PG8_STAGE(PG8_SB(0, 0), b2, voffB); PG8_STAGE(PG8_SB(0, 1), b2 + hstep, voffB); PG8_STAGE(PG8_SA(0, 0), a2, voffA);
;             PG8_WAIT_V(8); PG8_WAIT_L(0); PG8_BAR; PG8_MMA(1, 0, At, B0); PG8_MMA(1, 1, At, B1); PG8_BAR; PG8_SCHED;
.LBB0_757:
	ds_read_b128 v[146:149], v159
	ds_read_b128 v[166:169], v159 offset:1024
	ds_read_b128 v[170:173], v159 offset:2048
	ds_read_b128 v[174:177], v159 offset:3072
	ds_read_b128 v[178:181], v160
	ds_read_b128 v[182:185], v160 offset:1024
	ds_read_b128 v[186:189], v160 offset:2048
	ds_read_b128 v[190:193], v160 offset:3072
	s_add_u32 s66, s64, 0xfff80080
	s_addc_u32 s67, s65, -1
	s_cmp_eq_u32 s71, 28
	s_cselect_b32 s69, s45, s67
	s_cselect_b32 s68, s61, s66
	s_cselect_b32 s67, s43, s70
	s_cselect_b32 s66, s62, s63
	s_add_i32 m0, s9, 0xc000
	ds_read_b128 v[194:197], v161
	ds_read_b128 v[198:201], v161 offset:1024
	ds_read_b128 v[202:205], v161 offset:2048
	ds_read_b128 v[208:211], v161 offset:3072
	ds_read_b128 v[212:215], v161 offset:4096
	ds_read_b128 v[216:219], v161 offset:5120
	ds_read_b128 v[220:223], v161 offset:6144
	ds_read_b128 v[224:227], v161 offset:7168
	global_load_lds_dwordx4 v138, s[64:65]
	s_add_i32 m0, s9, 0xe000
	s_nop 0
	global_load_lds_dwordx4 v140, s[64:65]
	s_waitcnt vmcnt(8)
	s_waitcnt lgkmcnt(0)
	s_barrier
	s_setprio 1
	s_waitcnt lgkmcnt(0)
	v_mfma_f32_16x16x32_bf16 v[126:129], v[146:149], v[194:197], v[126:129]
	v_mfma_f32_16x16x32_bf16 v[122:125], v[170:173], v[194:197], v[122:125]
	v_mfma_f32_16x16x32_bf16 v[110:113], v[146:149], v[202:205], v[110:113]
	v_mfma_f32_16x16x32_bf16 v[106:109], v[170:173], v[202:205], v[106:109]
	v_mfma_f32_16x16x32_bf16 v[94:97], v[146:149], v[212:215], v[94:97]
	v_mfma_f32_16x16x32_bf16 v[90:93], v[170:173], v[212:215], v[90:93]
	v_mfma_f32_16x16x32_bf16 v[78:81], v[146:149], v[220:223], v[78:81]
	v_mfma_f32_16x16x32_bf16 v[74:77], v[170:173], v[220:223], v[74:77]
	v_mfma_f32_16x16x32_bf16 v[126:129], v[166:169], v[198:201], v[126:129]
	v_mfma_f32_16x16x32_bf16 v[122:125], v[174:177], v[198:201], v[122:125]
	v_mfma_f32_16x16x32_bf16 v[110:113], v[166:169], v[208:211], v[110:113]
	v_mfma_f32_16x16x32_bf16 v[106:109], v[174:177], v[208:211], v[106:109]
	v_mfma_f32_16x16x32_bf16 v[94:97], v[166:169], v[216:219], v[94:97]
	v_mfma_f32_16x16x32_bf16 v[90:93], v[174:177], v[216:219], v[90:93]
	v_mfma_f32_16x16x32_bf16 v[78:81], v[166:169], v[224:227], v[78:81]
	v_mfma_f32_16x16x32_bf16 v[74:77], v[174:177], v[224:227], v[74:77]
	s_setprio 0
	s_setprio 1
	v_mfma_f32_16x16x32_bf16 v[118:121], v[178:181], v[194:197], v[118:121]
	v_mfma_f32_16x16x32_bf16 v[114:117], v[186:189], v[194:197], v[114:117]
	v_mfma_f32_16x16x32_bf16 v[102:105], v[178:181], v[202:205], v[102:105]
	v_mfma_f32_16x16x32_bf16 v[98:101], v[186:189], v[202:205], v[98:101]
	v_mfma_f32_16x16x32_bf16 v[86:89], v[178:181], v[212:215], v[86:89]
	v_mfma_f32_16x16x32_bf16 v[82:85], v[186:189], v[212:215], v[82:85]
	v_mfma_f32_16x16x32_bf16 v[70:73], v[178:181], v[220:223], v[70:73]
	v_mfma_f32_16x16x32_bf16 v[66:69], v[186:189], v[220:223], v[66:69]
	v_mfma_f32_16x16x32_bf16 v[118:121], v[182:185], v[198:201], v[118:121]
	v_mfma_f32_16x16x32_bf16 v[114:117], v[190:193], v[198:201], v[114:117]
	v_mfma_f32_16x16x32_bf16 v[102:105], v[182:185], v[208:211], v[102:105]
	v_mfma_f32_16x16x32_bf16 v[98:101], v[190:193], v[208:211], v[98:101]
	v_mfma_f32_16x16x32_bf16 v[86:89], v[182:185], v[216:219], v[86:89]
	v_mfma_f32_16x16x32_bf16 v[82:85], v[190:193], v[216:219], v[82:85]
	v_mfma_f32_16x16x32_bf16 v[70:73], v[182:185], v[224:227], v[70:73]
	v_mfma_f32_16x16x32_bf16 v[66:69], v[190:193], v[224:227], v[66:69]
	s_setprio 0
	s_barrier
	s_add_i32 s72, s35, s8
	v_lshl_add_u64 v[228:229], s[66:67], 0, v[132:133]
	s_mov_b32 m0, s72
	ds_read_b128 v[194:197], v161 offset:16384
	ds_read_b128 v[198:201], v161 offset:17408
	ds_read_b128 v[202:205], v161 offset:18432
	ds_read_b128 v[208:211], v161 offset:19456
	ds_read_b128 v[212:215], v161 offset:20480
	ds_read_b128 v[216:219], v161 offset:21504
	ds_read_b128 v[220:223], v161 offset:22528
	ds_read_b128 v[224:227], v161 offset:23552
	global_load_lds_dwordx4 v[228:229], off
	s_add_i32 m0, s72, 0x2000
	s_add_u32 s72, s66, 0x80000
	v_lshl_add_u64 v[230:231], s[66:67], 0, v[136:137]
	s_addc_u32 s73, s67, 0
	s_add_i32 s74, s51, s8
	global_load_lds_dwordx4 v[230:231], off
	s_mov_b32 m0, s74
	v_lshl_add_u64 v[234:235], s[68:69], 0, v[134:135]
	global_load_lds_dwordx4 v132, s[72:73]
	s_add_i32 m0, s74, 0x2000
	s_nop 0
	global_load_lds_dwordx4 v136, s[72:73]
	v_lshl_add_u64 v[232:233], s[68:69], 0, v[130:131]
	s_mov_b32 m0, s9
	s_nop 0
	global_load_lds_dwordx4 v[232:233], off
	s_mov_b32 m0, s12
	s_nop 0
	global_load_lds_dwordx4 v[234:235], off
	s_waitcnt vmcnt(8)
	s_waitcnt lgkmcnt(0)
	s_barrier
; #define PG8_STAGE(bufoff, gbase, voff) do { _Pragma("unroll") for (int _i = 0; _i < 2; ++_i) \
;         __builtin_amdgcn_global_load_lds((const unsigned*)((const char*)(gbase) + (voff)[_i]), (PG8_LAS unsigned*)(lds + (bufoff) + ldsw + _i * 8192), 16, 0, 0); } while (0)
; #define PG8_LDA(dst, b, h) do { _Pragma("unroll") for (int m = 0; m < 4; ++m) _Pragma("unroll") for (int k = 0; k < 2; ++k) dst[m][k] = *(const PG8_LAS bf16x8*)(lds + PG8_SA(b, h) + aoff + m * 2048 + k * 1024); } while (0)
; #define PG8_LDB(dst, b, h) do { _Pragma("unroll") for (int n = 0; n < 2; ++n) _Pragma("unroll") for (int k = 0; k < 2; ++k) dst[n][k] = *(const PG8_LAS bf16x8*)(lds + PG8_SB(b, h) + boff + n * 2048 + k * 1024); } while (0)
; #define PG8_MMA(ai, bj, At, Bt) do { __builtin_amdgcn_s_setprio(1); _Pragma("unroll") for (int m = 0; m < 4; ++m) _Pragma("unroll") for (int n = 0; n < 2; ++n) _Pragma("unroll") for (int k = 0; k < 2; ++k) \
;         acc[ai][bj][m][n] = __builtin_amdgcn_mfma_f32_16x16x32_bf16(Bt[n][k], At[m][k], acc[ai][bj][m][n], 0, 0, 0); __builtin_amdgcn_s_setprio(0); } while (0)
; #define PG8_WAIT_V(n) asm volatile("s_waitcnt vmcnt(" #n ")" ::: "memory")
; #define PG8_WAIT_L(n) asm volatile("s_waitcnt lgkmcnt(" #n ")" ::: "memory")
; #define PG8_BAR __builtin_amdgcn_s_barrier()
; #define PG8_SCHED __builtin_amdgcn_sched_barrier(0)
; template <class Epi, class Sched, bool ALIGN_EPI = false, bool SP2 = false>
; __device__ __forceinline__ void gemm_phase(PG8_LAS unsigned char* lds, const Gemm g, const Sched& S, const Epi& E) {
;     ...
;             PG8_WAIT_V(8); PG8_WAIT_L(0); PG8_BAR; PG8_MMA(1, 0, At, B0); PG8_MMA(1, 1, At, B1); PG8_BAR; PG8_SCHED;
;             PG8_LDB(B0, 1, 0); PG8_LDB(B1, 1, 1); PG8_SCHED; PG8_LDA(At, 1, 0); PG8_STAGE(PG8_SA(0, 1), a2 + hstep, voffA);
;             PG8_WAIT_V(8); PG8_WAIT_L(0); PG8_BAR; PG8_MMA(0, 0, At, B0); PG8_MMA(0, 1, At, B1); PG8_BAR; PG8_SCHED;
;             PG8_LDA(At, 1, 1); PG8_STAGE(PG8_SB(1, 0), b3, voffB); PG8_STAGE(PG8_SB(1, 1), b3 + hstep, voffB); PG8_STAGE(PG8_SA(1, 0), a3, voffA);
	s_setprio 1
	s_waitcnt lgkmcnt(0)
	v_mfma_f32_16x16x32_bf16 v[62:65], v[146:149], v[194:197], v[62:65]
	v_mfma_f32_16x16x32_bf16 v[58:61], v[170:173], v[194:197], v[58:61]
	v_mfma_f32_16x16x32_bf16 v[46:49], v[146:149], v[202:205], v[46:49]
	v_mfma_f32_16x16x32_bf16 v[42:45], v[170:173], v[202:205], v[42:45]
	v_mfma_f32_16x16x32_bf16 v[30:33], v[146:149], v[212:215], v[30:33]
	v_mfma_f32_16x16x32_bf16 v[26:29], v[170:173], v[212:215], v[26:29]
	v_mfma_f32_16x16x32_bf16 v[14:17], v[146:149], v[220:223], v[14:17]
	v_mfma_f32_16x16x32_bf16 v[10:13], v[170:173], v[220:223], v[10:13]
	v_mfma_f32_16x16x32_bf16 v[62:65], v[166:169], v[198:201], v[62:65]
	v_mfma_f32_16x16x32_bf16 v[58:61], v[174:177], v[198:201], v[58:61]
	v_mfma_f32_16x16x32_bf16 v[46:49], v[166:169], v[208:211], v[46:49]
	v_mfma_f32_16x16x32_bf16 v[42:45], v[174:177], v[208:211], v[42:45]
	v_mfma_f32_16x16x32_bf16 v[30:33], v[166:169], v[216:219], v[30:33]
	v_mfma_f32_16x16x32_bf16 v[26:29], v[174:177], v[216:219], v[26:29]
	v_mfma_f32_16x16x32_bf16 v[14:17], v[166:169], v[224:227], v[14:17]
	v_mfma_f32_16x16x32_bf16 v[10:13], v[174:177], v[224:227], v[10:13]
	s_setprio 0
	s_setprio 1
	v_mfma_f32_16x16x32_bf16 v[54:57], v[178:181], v[194:197], v[54:57]
	v_mfma_f32_16x16x32_bf16 v[50:53], v[186:189], v[194:197], v[50:53]
	v_mfma_f32_16x16x32_bf16 v[38:41], v[178:181], v[202:205], v[38:41]
	v_mfma_f32_16x16x32_bf16 v[34:37], v[186:189], v[202:205], v[34:37]
	v_mfma_f32_16x16x32_bf16 v[22:25], v[178:181], v[212:215], v[22:25]
	v_mfma_f32_16x16x32_bf16 v[18:21], v[186:189], v[212:215], v[18:21]
	v_mfma_f32_16x16x32_bf16 v[6:9], v[178:181], v[220:223], v[6:9]
	v_mfma_f32_16x16x32_bf16 v[2:5], v[186:189], v[220:223], v[2:5]
	v_mfma_f32_16x16x32_bf16 v[54:57], v[182:185], v[198:201], v[54:57]
	v_mfma_f32_16x16x32_bf16 v[50:53], v[190:193], v[198:201], v[50:53]
	v_mfma_f32_16x16x32_bf16 v[38:41], v[182:185], v[208:211], v[38:41]
	v_mfma_f32_16x16x32_bf16 v[34:37], v[190:193], v[208:211], v[34:37]
	v_mfma_f32_16x16x32_bf16 v[22:25], v[182:185], v[216:219], v[22:25]
	v_mfma_f32_16x16x32_bf16 v[18:21], v[190:193], v[216:219], v[18:21]
	v_mfma_f32_16x16x32_bf16 v[6:9], v[182:185], v[224:227], v[6:9]
	v_mfma_f32_16x16x32_bf16 v[2:5], v[190:193], v[224:227], v[2:5]
	s_setprio 0
	s_barrier
	ds_read_b128 v[146:149], v163
	ds_read_b128 v[166:169], v163 offset:1024
	ds_read_b128 v[170:173], v163 offset:2048
	ds_read_b128 v[174:177], v163 offset:3072
	ds_read_b128 v[178:181], v164
	ds_read_b128 v[182:185], v164 offset:1024
	ds_read_b128 v[186:189], v164 offset:2048
	ds_read_b128 v[190:193], v164 offset:3072
	s_add_u32 s68, s68, 0x80000
	s_addc_u32 s69, s69, 0
	s_mov_b32 m0, s13
	ds_read_b128 v[194:197], v161 offset:32768
	ds_read_b128 v[198:201], v161 offset:33792
	ds_read_b128 v[202:205], v161 offset:34816
	ds_read_b128 v[208:211], v161 offset:35840
	ds_read_b128 v[212:215], v161 offset:36864
	ds_read_b128 v[216:219], v161 offset:37888
	ds_read_b128 v[220:223], v161 offset:38912
	ds_read_b128 v[224:227], v161 offset:39936
	global_load_lds_dwordx4 v130, s[68:69]
	s_mov_b32 m0, s14
	s_nop 0
	global_load_lds_dwordx4 v134, s[68:69]
	s_waitcnt vmcnt(8)
	s_waitcnt lgkmcnt(0)
	s_barrier
	s_setprio 1
	s_waitcnt lgkmcnt(0)
	v_mfma_f32_16x16x32_bf16 v[126:129], v[146:149], v[194:197], v[126:129]
	v_mfma_f32_16x16x32_bf16 v[122:125], v[170:173], v[194:197], v[122:125]
	v_mfma_f32_16x16x32_bf16 v[110:113], v[146:149], v[202:205], v[110:113]
	v_mfma_f32_16x16x32_bf16 v[106:109], v[170:173], v[202:205], v[106:109]
	v_mfma_f32_16x16x32_bf16 v[94:97], v[146:149], v[212:215], v[94:97]
	v_mfma_f32_16x16x32_bf16 v[90:93], v[170:173], v[212:215], v[90:93]
	v_mfma_f32_16x16x32_bf16 v[78:81], v[146:149], v[220:223], v[78:81]
	v_mfma_f32_16x16x32_bf16 v[74:77], v[170:173], v[220:223], v[74:77]
	v_mfma_f32_16x16x32_bf16 v[126:129], v[166:169], v[198:201], v[126:129]
	v_mfma_f32_16x16x32_bf16 v[122:125], v[174:177], v[198:201], v[122:125]
	v_mfma_f32_16x16x32_bf16 v[110:113], v[166:169], v[208:211], v[110:113]
	v_mfma_f32_16x16x32_bf16 v[106:109], v[174:177], v[208:211], v[106:109]
	v_mfma_f32_16x16x32_bf16 v[94:97], v[166:169], v[216:219], v[94:97]
	v_mfma_f32_16x16x32_bf16 v[90:93], v[174:177], v[216:219], v[90:93]
	v_mfma_f32_16x16x32_bf16 v[78:81], v[166:169], v[224:227], v[78:81]
	v_mfma_f32_16x16x32_bf16 v[74:77], v[174:177], v[224:227], v[74:77]
	s_setprio 0
	s_setprio 1
	v_mfma_f32_16x16x32_bf16 v[118:121], v[178:181], v[194:197], v[118:121]
	v_mfma_f32_16x16x32_bf16 v[114:117], v[186:189], v[194:197], v[114:117]
	v_mfma_f32_16x16x32_bf16 v[102:105], v[178:181], v[202:205], v[102:105]
	v_mfma_f32_16x16x32_bf16 v[98:101], v[186:189], v[202:205], v[98:101]
	v_mfma_f32_16x16x32_bf16 v[86:89], v[178:181], v[212:215], v[86:89]
	v_mfma_f32_16x16x32_bf16 v[82:85], v[186:189], v[212:215], v[82:85]
	v_mfma_f32_16x16x32_bf16 v[70:73], v[178:181], v[220:223], v[70:73]
	v_mfma_f32_16x16x32_bf16 v[66:69], v[186:189], v[220:223], v[66:69]
	v_mfma_f32_16x16x32_bf16 v[118:121], v[182:185], v[198:201], v[118:121]
	v_mfma_f32_16x16x32_bf16 v[114:117], v[190:193], v[198:201], v[114:117]
	v_mfma_f32_16x16x32_bf16 v[102:105], v[182:185], v[208:211], v[102:105]
	v_mfma_f32_16x16x32_bf16 v[98:101], v[190:193], v[208:211], v[98:101]
	v_mfma_f32_16x16x32_bf16 v[86:89], v[182:185], v[216:219], v[86:89]
	v_mfma_f32_16x16x32_bf16 v[82:85], v[190:193], v[216:219], v[82:85]
	v_mfma_f32_16x16x32_bf16 v[70:73], v[182:185], v[224:227], v[70:73]
	v_mfma_f32_16x16x32_bf16 v[66:69], v[190:193], v[224:227], v[66:69]
	s_setprio 0
	s_barrier
; #define PG8_STAGE(bufoff, gbase, voff) do { _Pragma("unroll") for (int _i = 0; _i < 2; ++_i) \
;         __builtin_amdgcn_global_load_lds((const unsigned*)((const char*)(gbase) + (voff)[_i]), (PG8_LAS unsigned*)(lds + (bufoff) + ldsw + _i * 8192), 16, 0, 0); } while (0)
; #define PG8_LDA(dst, b, h) do { _Pragma("unroll") for (int m = 0; m < 4; ++m) _Pragma("unroll") for (int k = 0; k < 2; ++k) dst[m][k] = *(const PG8_LAS bf16x8*)(lds + PG8_SA(b, h) + aoff + m * 2048 + k * 1024); } while (0)
; #define PG8_MMA(ai, bj, At, Bt) do { __builtin_amdgcn_s_setprio(1); _Pragma("unroll") for (int m = 0; m < 4; ++m) _Pragma("unroll") for (int n = 0; n < 2; ++n) _Pragma("unroll") for (int k = 0; k < 2; ++k) \
;         acc[ai][bj][m][n] = __builtin_amdgcn_mfma_f32_16x16x32_bf16(Bt[n][k], At[m][k], acc[ai][bj][m][n], 0, 0, 0); __builtin_amdgcn_s_setprio(0); } while (0)
; #define PG8_WAIT_V(n) asm volatile("s_waitcnt vmcnt(" #n ")" ::: "memory")
; #define PG8_WAIT_L(n) asm volatile("s_waitcnt lgkmcnt(" #n ")" ::: "memory")
; #define PG8_BAR __builtin_amdgcn_s_barrier()
; #define PG8_SCHED __builtin_amdgcn_sched_barrier(0)
; template <class Epi, class Sched, bool ALIGN_EPI = false, bool SP2 = false>
; __device__ __forceinline__ void gemm_phase(PG8_LAS unsigned char* lds, const Gemm g, const Sched& S, const Epi& E) {
;     ...
;         for (int t = 0; t < nt; t += 2) {
;             const bool last = (t == nt - 2);
;             const char* a1 = cA + (size_t)(t + 1) * kstep;
;             const char* a2 = last ? nA : cA + (size_t)(t + 2) * kstep; const char* b2 = last ? nB : cB + (size_t)(t + 2) * kstep;
;     ...
;             PG8_LDA(At, 1, 1); PG8_STAGE(PG8_SB(1, 0), b3, voffB); PG8_STAGE(PG8_SB(1, 1), b3 + hstep, voffB); PG8_STAGE(PG8_SA(1, 0), a3, voffA);
;             PG8_WAIT_V(8); PG8_WAIT_L(0); PG8_BAR; PG8_MMA(1, 0, At, B0); PG8_MMA(1, 1, At, B1); PG8_BAR; PG8_SCHED;
	s_add_i32 s68, s57, s8
	v_lshl_add_u64 v[228:229], v[228:229], 0, s[36:37]
	s_mov_b32 m0, s68
	ds_read_b128 v[194:197], v161 offset:49152
	ds_read_b128 v[198:201], v161 offset:50176
	ds_read_b128 v[202:205], v161 offset:51200
	ds_read_b128 v[208:211], v161 offset:52224
	ds_read_b128 v[212:215], v161 offset:53248
	ds_read_b128 v[216:219], v161 offset:54272
	ds_read_b128 v[220:223], v161 offset:55296
	ds_read_b128 v[224:227], v161 offset:56320
	global_load_lds_dwordx4 v[228:229], off
	s_add_i32 m0, s68, 0x2000
	s_add_u32 s66, s66, 0x80080
	v_lshl_add_u64 v[228:229], v[230:231], 0, s[36:37]
	s_addc_u32 s67, s67, 0
	s_add_i32 s68, s58, s8
	global_load_lds_dwordx4 v[228:229], off
	s_mov_b32 m0, s68
	s_nop 0
	global_load_lds_dwordx4 v132, s[66:67]
	s_add_i32 m0, s68, 0x2000
	s_nop 0
	global_load_lds_dwordx4 v136, s[66:67]
	v_lshl_add_u64 v[228:229], v[232:233], 0, s[36:37]
	s_mov_b32 m0, s15
	s_nop 0
	global_load_lds_dwordx4 v[228:229], off
	v_lshl_add_u64 v[228:229], v[234:235], 0, s[36:37]
	s_mov_b32 m0, s16
	s_nop 0
	global_load_lds_dwordx4 v[228:229], off
	s_waitcnt vmcnt(8)
	s_waitcnt lgkmcnt(0)
	s_barrier
	s_setprio 1
	s_waitcnt lgkmcnt(0)
	v_mfma_f32_16x16x32_bf16 v[62:65], v[146:149], v[194:197], v[62:65]
	v_mfma_f32_16x16x32_bf16 v[58:61], v[170:173], v[194:197], v[58:61]
	v_mfma_f32_16x16x32_bf16 v[46:49], v[146:149], v[202:205], v[46:49]
	v_mfma_f32_16x16x32_bf16 v[42:45], v[170:173], v[202:205], v[42:45]
	v_mfma_f32_16x16x32_bf16 v[30:33], v[146:149], v[212:215], v[30:33]
	v_mfma_f32_16x16x32_bf16 v[26:29], v[170:173], v[212:215], v[26:29]
	v_mfma_f32_16x16x32_bf16 v[14:17], v[146:149], v[220:223], v[14:17]
	v_mfma_f32_16x16x32_bf16 v[10:13], v[170:173], v[220:223], v[10:13]
	v_mfma_f32_16x16x32_bf16 v[62:65], v[166:169], v[198:201], v[62:65]
	v_mfma_f32_16x16x32_bf16 v[58:61], v[174:177], v[198:201], v[58:61]
	v_mfma_f32_16x16x32_bf16 v[46:49], v[166:169], v[208:211], v[46:49]
	v_mfma_f32_16x16x32_bf16 v[42:45], v[174:177], v[208:211], v[42:45]
	v_mfma_f32_16x16x32_bf16 v[30:33], v[166:169], v[216:219], v[30:33]
	v_mfma_f32_16x16x32_bf16 v[26:29], v[174:177], v[216:219], v[26:29]
	v_mfma_f32_16x16x32_bf16 v[14:17], v[166:169], v[224:227], v[14:17]
	v_mfma_f32_16x16x32_bf16 v[10:13], v[174:177], v[224:227], v[10:13]
	s_setprio 0
	s_setprio 1
	v_mfma_f32_16x16x32_bf16 v[54:57], v[178:181], v[194:197], v[54:57]
	v_mfma_f32_16x16x32_bf16 v[50:53], v[186:189], v[194:197], v[50:53]
	v_mfma_f32_16x16x32_bf16 v[38:41], v[178:181], v[202:205], v[38:41]
	v_mfma_f32_16x16x32_bf16 v[34:37], v[186:189], v[202:205], v[34:37]
	v_mfma_f32_16x16x32_bf16 v[22:25], v[178:181], v[212:215], v[22:25]
	v_mfma_f32_16x16x32_bf16 v[18:21], v[186:189], v[212:215], v[18:21]
	v_mfma_f32_16x16x32_bf16 v[6:9], v[178:181], v[220:223], v[6:9]
	v_mfma_f32_16x16x32_bf16 v[2:5], v[186:189], v[220:223], v[2:5]
	v_mfma_f32_16x16x32_bf16 v[54:57], v[182:185], v[198:201], v[54:57]
	v_mfma_f32_16x16x32_bf16 v[50:53], v[190:193], v[198:201], v[50:53]
	v_mfma_f32_16x16x32_bf16 v[38:41], v[182:185], v[208:211], v[38:41]
	v_mfma_f32_16x16x32_bf16 v[34:37], v[190:193], v[208:211], v[34:37]
	v_mfma_f32_16x16x32_bf16 v[22:25], v[182:185], v[216:219], v[22:25]
	v_mfma_f32_16x16x32_bf16 v[18:21], v[190:193], v[216:219], v[18:21]
	v_mfma_f32_16x16x32_bf16 v[6:9], v[182:185], v[224:227], v[6:9]
	v_mfma_f32_16x16x32_bf16 v[2:5], v[190:193], v[224:227], v[2:5]
	s_setprio 0
	s_barrier
	s_add_i32 s71, s71, 2
	s_add_u32 s64, s64, 0x100
	s_addc_u32 s65, s65, 0
	s_add_u32 s63, s63, 0x100
	s_addc_u32 s70, s70, 0
	s_cmp_gt_u32 s71, 29
	s_cbranch_scc0 .LBB0_757
	s_and_b64 vcc, exec, s[40:41]
	s_cbranch_vccz .LBB0_760
	s_barrier

; #define PG8_STAGE(bufoff, gbase, voff) do { _Pragma("unroll") for (int _i = 0; _i < 2; ++_i) \
;         __builtin_amdgcn_global_load_lds((const unsigned*)((const char*)(gbase) + (voff)[_i]), (PG8_LAS unsigned*)(lds + (bufoff) + ldsw + _i * 8192), 16, 0, 0); } while (0)
; #define PG8_LDA(dst, b, h) do { _Pragma("unroll") for (int m = 0; m < 4; ++m) _Pragma("unroll") for (int k = 0; k < 2; ++k) dst[m][k] = *(const PG8_LAS bf16x8*)(lds + PG8_SA(b, h) + aoff + m * 2048 + k * 1024); } while (0)
; #define PG8_LDB(dst, b, h) do { _Pragma("unroll") for (int n = 0; n < 2; ++n) _Pragma("unroll") for (int k = 0; k < 2; ++k) dst[n][k] = *(const PG8_LAS bf16x8*)(lds + PG8_SB(b, h) + boff + n * 2048 + k * 1024); } while (0)
; #define PG8_MMA(ai, bj, At, Bt) do { __builtin_amdgcn_s_setprio(1); _Pragma("unroll") for (int m = 0; m < 4; ++m) _Pragma("unroll") for (int n = 0; n < 2; ++n) _Pragma("unroll") for (int k = 0; k < 2; ++k) \
;         acc[ai][bj][m][n] = __builtin_amdgcn_mfma_f32_16x16x32_bf16(Bt[n][k], At[m][k], acc[ai][bj][m][n], 0, 0, 0); __builtin_amdgcn_s_setprio(0); } while (0)
; #define PG8_WAIT_V(n) asm volatile("s_waitcnt vmcnt(" #n ")" ::: "memory")
; #define PG8_BAR __builtin_amdgcn_s_barrier()
; template <class Epi, class Sched, bool ALIGN_EPI = false, bool SP2 = false>
; __device__ __forceinline__ void gemm_phase(PG8_LAS unsigned char* lds, const Gemm g, const Sched& S, const Epi& E) {
;     ...
;         for (int t = 0; t < nt; t += 2) {
;             const bool last = (t == nt - 2);
;             const char* a1 = cA + (size_t)(t + 1) * kstep;
;             const char* a2 = last ? nA : cA + (size_t)(t + 2) * kstep; const char* b2 = last ? nB : cB + (size_t)(t + 2) * kstep;
;             const char* a3 = a2 + kstep; const char* b3 = b2 + kstep;
;             if (last && has_next) S.a_ready(nxt);
;             if constexpr (SP2) {
;             PG8_LDB(B0, 0, 0); PG8_LDB(B1, 0, 1); PG8_SCHED; PG8_LDA(At, 0, 0); PG8_STAGE(PG8_SA(1, 1), a1 + hstep, voffA);
;             PG8_WAIT_V(8); PG8_WAIT_L(0); PG8_BAR; PG8_MMA(0, 0, At, B0); PG8_MMA(0, 1, At, B1); PG8_BAR; PG8_SCHED;
;             PG8_LDA(At, 0, 1); PG8_STAGE(PG8_SB(0, 0), b2, voffB); PG8_STAGE(PG8_SB(0, 1), b2 + hstep, voffB); PG8_STAGE(PG8_SA(0, 0), a2, voffA);
;             PG8_WAIT_V(8); PG8_WAIT_L(0); PG8_BAR; PG8_MMA(1, 0, At, B0); PG8_MMA(1, 1, At, B1); PG8_BAR; PG8_SCHED;
.LBB0_781:
	ds_read_b128 v[146:149], v155
	ds_read_b128 v[150:153], v155 offset:1024
	ds_read_b128 v[164:167], v155 offset:2048
	ds_read_b128 v[168:171], v155 offset:3072
	ds_read_b128 v[172:175], v156
	ds_read_b128 v[176:179], v156 offset:1024
	ds_read_b128 v[180:183], v156 offset:2048
	ds_read_b128 v[184:187], v156 offset:3072
	s_add_u32 s64, s50, 0xfff80080
	s_addc_u32 s65, s51, -1
	s_cmp_eq_u32 s69, 28
	s_cselect_b32 s67, s43, s65
	s_cselect_b32 s66, s61, s64
	s_cselect_b32 s65, s41, s68
	s_cselect_b32 s64, s62, s63
	s_add_i32 m0, s9, 0xc000
	ds_read_b128 v[188:191], v157
	ds_read_b128 v[192:195], v157 offset:1024
	ds_read_b128 v[196:199], v157 offset:2048
	ds_read_b128 v[200:203], v157 offset:3072
	ds_read_b128 v[208:211], v157 offset:4096
	ds_read_b128 v[212:215], v157 offset:5120
	ds_read_b128 v[216:219], v157 offset:6144
	ds_read_b128 v[220:223], v157 offset:7168
	global_load_lds_dwordx4 v138, s[50:51]
	s_add_i32 m0, s9, 0xe000
	s_nop 0
	global_load_lds_dwordx4 v140, s[50:51]
	s_waitcnt vmcnt(8)
	s_waitcnt lgkmcnt(0)
	s_barrier
	s_setprio 1
	s_waitcnt lgkmcnt(0)
	v_mfma_f32_16x16x32_bf16 v[126:129], v[146:149], v[188:191], v[126:129]
	v_mfma_f32_16x16x32_bf16 v[122:125], v[164:167], v[188:191], v[122:125]
	v_mfma_f32_16x16x32_bf16 v[110:113], v[146:149], v[196:199], v[110:113]
	v_mfma_f32_16x16x32_bf16 v[106:109], v[164:167], v[196:199], v[106:109]
	v_mfma_f32_16x16x32_bf16 v[94:97], v[146:149], v[208:211], v[94:97]
	v_mfma_f32_16x16x32_bf16 v[90:93], v[164:167], v[208:211], v[90:93]
	v_mfma_f32_16x16x32_bf16 v[78:81], v[146:149], v[216:219], v[78:81]
	v_mfma_f32_16x16x32_bf16 v[74:77], v[164:167], v[216:219], v[74:77]
	v_mfma_f32_16x16x32_bf16 v[126:129], v[150:153], v[192:195], v[126:129]
	v_mfma_f32_16x16x32_bf16 v[122:125], v[168:171], v[192:195], v[122:125]
	v_mfma_f32_16x16x32_bf16 v[110:113], v[150:153], v[200:203], v[110:113]
	v_mfma_f32_16x16x32_bf16 v[106:109], v[168:171], v[200:203], v[106:109]
	v_mfma_f32_16x16x32_bf16 v[94:97], v[150:153], v[212:215], v[94:97]
	v_mfma_f32_16x16x32_bf16 v[90:93], v[168:171], v[212:215], v[90:93]
	v_mfma_f32_16x16x32_bf16 v[78:81], v[150:153], v[220:223], v[78:81]
	v_mfma_f32_16x16x32_bf16 v[74:77], v[168:171], v[220:223], v[74:77]
	s_setprio 0
	s_setprio 1
	v_mfma_f32_16x16x32_bf16 v[118:121], v[172:175], v[188:191], v[118:121]
	v_mfma_f32_16x16x32_bf16 v[114:117], v[180:183], v[188:191], v[114:117]
	v_mfma_f32_16x16x32_bf16 v[102:105], v[172:175], v[196:199], v[102:105]
	v_mfma_f32_16x16x32_bf16 v[98:101], v[180:183], v[196:199], v[98:101]
	v_mfma_f32_16x16x32_bf16 v[86:89], v[172:175], v[208:211], v[86:89]
	v_mfma_f32_16x16x32_bf16 v[82:85], v[180:183], v[208:211], v[82:85]
	v_mfma_f32_16x16x32_bf16 v[70:73], v[172:175], v[216:219], v[70:73]
	v_mfma_f32_16x16x32_bf16 v[66:69], v[180:183], v[216:219], v[66:69]
	v_mfma_f32_16x16x32_bf16 v[118:121], v[176:179], v[192:195], v[118:121]
	v_mfma_f32_16x16x32_bf16 v[114:117], v[184:187], v[192:195], v[114:117]
	v_mfma_f32_16x16x32_bf16 v[102:105], v[176:179], v[200:203], v[102:105]
	v_mfma_f32_16x16x32_bf16 v[98:101], v[184:187], v[200:203], v[98:101]
	v_mfma_f32_16x16x32_bf16 v[86:89], v[176:179], v[212:215], v[86:89]
	v_mfma_f32_16x16x32_bf16 v[82:85], v[184:187], v[212:215], v[82:85]
	v_mfma_f32_16x16x32_bf16 v[70:73], v[176:179], v[220:223], v[70:73]
	v_mfma_f32_16x16x32_bf16 v[66:69], v[184:187], v[220:223], v[66:69]
	s_setprio 0
	s_barrier
	s_add_i32 s70, s35, s8
	v_lshl_add_u64 v[160:161], s[64:65], 0, v[132:133]
	s_mov_b32 m0, s70
	ds_read_b128 v[188:191], v157 offset:16384
	ds_read_b128 v[192:195], v157 offset:17408
	ds_read_b128 v[196:199], v157 offset:18432
	ds_read_b128 v[200:203], v157 offset:19456
	ds_read_b128 v[208:211], v157 offset:20480
	ds_read_b128 v[212:215], v157 offset:21504
	ds_read_b128 v[216:219], v157 offset:22528
	ds_read_b128 v[220:223], v157 offset:23552
	global_load_lds_dwordx4 v[160:161], off
	s_add_i32 m0, s70, 0x2000
	s_add_u32 s70, s64, 0x80000
	v_lshl_add_u64 v[204:205], s[64:65], 0, v[136:137]
	s_addc_u32 s71, s65, 0
	s_add_i32 s72, s49, s8
	global_load_lds_dwordx4 v[204:205], off
	s_mov_b32 m0, s72
	v_lshl_add_u64 v[226:227], s[66:67], 0, v[134:135]
	global_load_lds_dwordx4 v132, s[70:71]
	s_add_i32 m0, s72, 0x2000
	s_nop 0
	global_load_lds_dwordx4 v136, s[70:71]
	v_lshl_add_u64 v[224:225], s[66:67], 0, v[130:131]
	s_mov_b32 m0, s9
	s_nop 0
	global_load_lds_dwordx4 v[224:225], off
	s_mov_b32 m0, s12
	s_nop 0
	global_load_lds_dwordx4 v[226:227], off
	s_waitcnt vmcnt(8)
	s_waitcnt lgkmcnt(0)
	s_barrier
; #define PG8_STAGE(bufoff, gbase, voff) do { _Pragma("unroll") for (int _i = 0; _i < 2; ++_i) \
;         __builtin_amdgcn_global_load_lds((const unsigned*)((const char*)(gbase) + (voff)[_i]), (PG8_LAS unsigned*)(lds + (bufoff) + ldsw + _i * 8192), 16, 0, 0); } while (0)
; #define PG8_LDA(dst, b, h) do { _Pragma("unroll") for (int m = 0; m < 4; ++m) _Pragma("unroll") for (int k = 0; k < 2; ++k) dst[m][k] = *(const PG8_LAS bf16x8*)(lds + PG8_SA(b, h) + aoff + m * 2048 + k * 1024); } while (0)
; #define PG8_LDB(dst, b, h) do { _Pragma("unroll") for (int n = 0; n < 2; ++n) _Pragma("unroll") for (int k = 0; k < 2; ++k) dst[n][k] = *(const PG8_LAS bf16x8*)(lds + PG8_SB(b, h) + boff + n * 2048 + k * 1024); } while (0)
; #define PG8_MMA(ai, bj, At, Bt) do { __builtin_amdgcn_s_setprio(1); _Pragma("unroll") for (int m = 0; m < 4; ++m) _Pragma("unroll") for (int n = 0; n < 2; ++n) _Pragma("unroll") for (int k = 0; k < 2; ++k) \
;         acc[ai][bj][m][n] = __builtin_amdgcn_mfma_f32_16x16x32_bf16(Bt[n][k], At[m][k], acc[ai][bj][m][n], 0, 0, 0); __builtin_amdgcn_s_setprio(0); } while (0)
; #define PG8_WAIT_V(n) asm volatile("s_waitcnt vmcnt(" #n ")" ::: "memory")
; #define PG8_WAIT_L(n) asm volatile("s_waitcnt lgkmcnt(" #n ")" ::: "memory")
; #define PG8_BAR __builtin_amdgcn_s_barrier()
; #define PG8_SCHED __builtin_amdgcn_sched_barrier(0)
; template <class Epi, class Sched, bool ALIGN_EPI = false, bool SP2 = false>
; __device__ __forceinline__ void gemm_phase(PG8_LAS unsigned char* lds, const Gemm g, const Sched& S, const Epi& E) {
;     ...
;             PG8_WAIT_V(8); PG8_WAIT_L(0); PG8_BAR; PG8_MMA(1, 0, At, B0); PG8_MMA(1, 1, At, B1); PG8_BAR; PG8_SCHED;
;             PG8_LDB(B0, 1, 0); PG8_LDB(B1, 1, 1); PG8_SCHED; PG8_LDA(At, 1, 0); PG8_STAGE(PG8_SA(0, 1), a2 + hstep, voffA);
;             PG8_WAIT_V(8); PG8_WAIT_L(0); PG8_BAR; PG8_MMA(0, 0, At, B0); PG8_MMA(0, 1, At, B1); PG8_BAR; PG8_SCHED;
;             PG8_LDA(At, 1, 1); PG8_STAGE(PG8_SB(1, 0), b3, voffB); PG8_STAGE(PG8_SB(1, 1), b3 + hstep, voffB); PG8_STAGE(PG8_SA(1, 0), a3, voffA);
	s_setprio 1
	s_waitcnt lgkmcnt(0)
	v_mfma_f32_16x16x32_bf16 v[62:65], v[146:149], v[188:191], v[62:65]
	v_mfma_f32_16x16x32_bf16 v[58:61], v[164:167], v[188:191], v[58:61]
	v_mfma_f32_16x16x32_bf16 v[46:49], v[146:149], v[196:199], v[46:49]
	v_mfma_f32_16x16x32_bf16 v[42:45], v[164:167], v[196:199], v[42:45]
	v_mfma_f32_16x16x32_bf16 v[30:33], v[146:149], v[208:211], v[30:33]
	v_mfma_f32_16x16x32_bf16 v[26:29], v[164:167], v[208:211], v[26:29]
	v_mfma_f32_16x16x32_bf16 v[14:17], v[146:149], v[216:219], v[14:17]
	v_mfma_f32_16x16x32_bf16 v[10:13], v[164:167], v[216:219], v[10:13]
	v_mfma_f32_16x16x32_bf16 v[62:65], v[150:153], v[192:195], v[62:65]
	v_mfma_f32_16x16x32_bf16 v[58:61], v[168:171], v[192:195], v[58:61]
	v_mfma_f32_16x16x32_bf16 v[46:49], v[150:153], v[200:203], v[46:49]
	v_mfma_f32_16x16x32_bf16 v[42:45], v[168:171], v[200:203], v[42:45]
	v_mfma_f32_16x16x32_bf16 v[30:33], v[150:153], v[212:215], v[30:33]
	v_mfma_f32_16x16x32_bf16 v[26:29], v[168:171], v[212:215], v[26:29]
	v_mfma_f32_16x16x32_bf16 v[14:17], v[150:153], v[220:223], v[14:17]
	v_mfma_f32_16x16x32_bf16 v[10:13], v[168:171], v[220:223], v[10:13]
	s_setprio 0
	s_setprio 1
	v_mfma_f32_16x16x32_bf16 v[54:57], v[172:175], v[188:191], v[54:57]
	v_mfma_f32_16x16x32_bf16 v[50:53], v[180:183], v[188:191], v[50:53]
	v_mfma_f32_16x16x32_bf16 v[38:41], v[172:175], v[196:199], v[38:41]
	v_mfma_f32_16x16x32_bf16 v[34:37], v[180:183], v[196:199], v[34:37]
	v_mfma_f32_16x16x32_bf16 v[22:25], v[172:175], v[208:211], v[22:25]
	v_mfma_f32_16x16x32_bf16 v[18:21], v[180:183], v[208:211], v[18:21]
	v_mfma_f32_16x16x32_bf16 v[6:9], v[172:175], v[216:219], v[6:9]
	v_mfma_f32_16x16x32_bf16 v[2:5], v[180:183], v[216:219], v[2:5]
	v_mfma_f32_16x16x32_bf16 v[54:57], v[176:179], v[192:195], v[54:57]
	v_mfma_f32_16x16x32_bf16 v[50:53], v[184:187], v[192:195], v[50:53]
	v_mfma_f32_16x16x32_bf16 v[38:41], v[176:179], v[200:203], v[38:41]
	v_mfma_f32_16x16x32_bf16 v[34:37], v[184:187], v[200:203], v[34:37]
	v_mfma_f32_16x16x32_bf16 v[22:25], v[176:179], v[212:215], v[22:25]
	v_mfma_f32_16x16x32_bf16 v[18:21], v[184:187], v[212:215], v[18:21]
	v_mfma_f32_16x16x32_bf16 v[6:9], v[176:179], v[220:223], v[6:9]
	v_mfma_f32_16x16x32_bf16 v[2:5], v[184:187], v[220:223], v[2:5]
	s_setprio 0
	s_barrier
	ds_read_b128 v[146:149], v158
	ds_read_b128 v[150:153], v158 offset:1024
	ds_read_b128 v[164:167], v158 offset:2048
	ds_read_b128 v[168:171], v158 offset:3072
	ds_read_b128 v[172:175], v159
	ds_read_b128 v[176:179], v159 offset:1024
	ds_read_b128 v[180:183], v159 offset:2048
	ds_read_b128 v[184:187], v159 offset:3072
	s_add_u32 s66, s66, 0x80000
	s_addc_u32 s67, s67, 0
	s_mov_b32 m0, s13
	ds_read_b128 v[188:191], v157 offset:32768
	ds_read_b128 v[192:195], v157 offset:33792
	ds_read_b128 v[196:199], v157 offset:34816
	ds_read_b128 v[200:203], v157 offset:35840
	ds_read_b128 v[208:211], v157 offset:36864
	ds_read_b128 v[212:215], v157 offset:37888
	ds_read_b128 v[216:219], v157 offset:38912
	ds_read_b128 v[220:223], v157 offset:39936
	global_load_lds_dwordx4 v130, s[66:67]
	s_mov_b32 m0, s14
	s_nop 0
	global_load_lds_dwordx4 v134, s[66:67]
	s_waitcnt vmcnt(8)
	s_waitcnt lgkmcnt(0)
	s_barrier
	s_setprio 1
	s_waitcnt lgkmcnt(0)
	v_mfma_f32_16x16x32_bf16 v[126:129], v[146:149], v[188:191], v[126:129]
	v_mfma_f32_16x16x32_bf16 v[122:125], v[164:167], v[188:191], v[122:125]
	v_mfma_f32_16x16x32_bf16 v[110:113], v[146:149], v[196:199], v[110:113]
	v_mfma_f32_16x16x32_bf16 v[106:109], v[164:167], v[196:199], v[106:109]
	v_mfma_f32_16x16x32_bf16 v[94:97], v[146:149], v[208:211], v[94:97]
	v_mfma_f32_16x16x32_bf16 v[90:93], v[164:167], v[208:211], v[90:93]
	v_mfma_f32_16x16x32_bf16 v[78:81], v[146:149], v[216:219], v[78:81]
	v_mfma_f32_16x16x32_bf16 v[74:77], v[164:167], v[216:219], v[74:77]
	v_mfma_f32_16x16x32_bf16 v[126:129], v[150:153], v[192:195], v[126:129]
	v_mfma_f32_16x16x32_bf16 v[122:125], v[168:171], v[192:195], v[122:125]
	v_mfma_f32_16x16x32_bf16 v[110:113], v[150:153], v[200:203], v[110:113]
	v_mfma_f32_16x16x32_bf16 v[106:109], v[168:171], v[200:203], v[106:109]
	v_mfma_f32_16x16x32_bf16 v[94:97], v[150:153], v[212:215], v[94:97]
	v_mfma_f32_16x16x32_bf16 v[90:93], v[168:171], v[212:215], v[90:93]
	v_mfma_f32_16x16x32_bf16 v[78:81], v[150:153], v[220:223], v[78:81]
	v_mfma_f32_16x16x32_bf16 v[74:77], v[168:171], v[220:223], v[74:77]
	s_setprio 0
	s_setprio 1
	v_mfma_f32_16x16x32_bf16 v[118:121], v[172:175], v[188:191], v[118:121]
	v_mfma_f32_16x16x32_bf16 v[114:117], v[180:183], v[188:191], v[114:117]
	v_mfma_f32_16x16x32_bf16 v[102:105], v[172:175], v[196:199], v[102:105]
	v_mfma_f32_16x16x32_bf16 v[98:101], v[180:183], v[196:199], v[98:101]
	v_mfma_f32_16x16x32_bf16 v[86:89], v[172:175], v[208:211], v[86:89]
	v_mfma_f32_16x16x32_bf16 v[82:85], v[180:183], v[208:211], v[82:85]
	v_mfma_f32_16x16x32_bf16 v[70:73], v[172:175], v[216:219], v[70:73]
	v_mfma_f32_16x16x32_bf16 v[66:69], v[180:183], v[216:219], v[66:69]
	v_mfma_f32_16x16x32_bf16 v[118:121], v[176:179], v[192:195], v[118:121]
	v_mfma_f32_16x16x32_bf16 v[114:117], v[184:187], v[192:195], v[114:117]
	v_mfma_f32_16x16x32_bf16 v[102:105], v[176:179], v[200:203], v[102:105]
	v_mfma_f32_16x16x32_bf16 v[98:101], v[184:187], v[200:203], v[98:101]
	v_mfma_f32_16x16x32_bf16 v[86:89], v[176:179], v[212:215], v[86:89]
	v_mfma_f32_16x16x32_bf16 v[82:85], v[184:187], v[212:215], v[82:85]
	v_mfma_f32_16x16x32_bf16 v[70:73], v[176:179], v[220:223], v[70:73]
	v_mfma_f32_16x16x32_bf16 v[66:69], v[184:187], v[220:223], v[66:69]
	s_setprio 0
	s_barrier
; #define PG8_STAGE(bufoff, gbase, voff) do { _Pragma("unroll") for (int _i = 0; _i < 2; ++_i) \
;         __builtin_amdgcn_global_load_lds((const unsigned*)((const char*)(gbase) + (voff)[_i]), (PG8_LAS unsigned*)(lds + (bufoff) + ldsw + _i * 8192), 16, 0, 0); } while (0)
; #define PG8_LDA(dst, b, h) do { _Pragma("unroll") for (int m = 0; m < 4; ++m) _Pragma("unroll") for (int k = 0; k < 2; ++k) dst[m][k] = *(const PG8_LAS bf16x8*)(lds + PG8_SA(b, h) + aoff + m * 2048 + k * 1024); } while (0)
; #define PG8_MMA(ai, bj, At, Bt) do { __builtin_amdgcn_s_setprio(1); _Pragma("unroll") for (int m = 0; m < 4; ++m) _Pragma("unroll") for (int n = 0; n < 2; ++n) _Pragma("unroll") for (int k = 0; k < 2; ++k) \
;         acc[ai][bj][m][n] = __builtin_amdgcn_mfma_f32_16x16x32_bf16(Bt[n][k], At[m][k], acc[ai][bj][m][n], 0, 0, 0); __builtin_amdgcn_s_setprio(0); } while (0)
; #define PG8_WAIT_V(n) asm volatile("s_waitcnt vmcnt(" #n ")" ::: "memory")
; #define PG8_WAIT_L(n) asm volatile("s_waitcnt lgkmcnt(" #n ")" ::: "memory")
; #define PG8_BAR __builtin_amdgcn_s_barrier()
; #define PG8_SCHED __builtin_amdgcn_sched_barrier(0)
; template <class Epi, class Sched, bool ALIGN_EPI = false, bool SP2 = false>
; __device__ __forceinline__ void gemm_phase(PG8_LAS unsigned char* lds, const Gemm g, const Sched& S, const Epi& E) {
;     ...
;         for (int t = 0; t < nt; t += 2) {
;             const bool last = (t == nt - 2);
;             const char* a1 = cA + (size_t)(t + 1) * kstep;
;             const char* a2 = last ? nA : cA + (size_t)(t + 2) * kstep; const char* b2 = last ? nB : cB + (size_t)(t + 2) * kstep;
;     ...
;             PG8_LDA(At, 1, 1); PG8_STAGE(PG8_SB(1, 0), b3, voffB); PG8_STAGE(PG8_SB(1, 1), b3 + hstep, voffB); PG8_STAGE(PG8_SA(1, 0), a3, voffA);
;             PG8_WAIT_V(8); PG8_WAIT_L(0); PG8_BAR; PG8_MMA(1, 0, At, B0); PG8_MMA(1, 1, At, B1); PG8_BAR; PG8_SCHED;
	s_add_i32 s66, s57, s8
	v_lshl_add_u64 v[160:161], v[160:161], 0, s[22:23]
	s_mov_b32 m0, s66
	ds_read_b128 v[188:191], v157 offset:49152
	ds_read_b128 v[192:195], v157 offset:50176
	ds_read_b128 v[196:199], v157 offset:51200
	ds_read_b128 v[200:203], v157 offset:52224
	ds_read_b128 v[208:211], v157 offset:53248
	ds_read_b128 v[212:215], v157 offset:54272
	ds_read_b128 v[216:219], v157 offset:55296
	ds_read_b128 v[220:223], v157 offset:56320
	global_load_lds_dwordx4 v[160:161], off
	s_add_i32 m0, s66, 0x2000
	s_add_u32 s64, s64, 0x80080
	v_lshl_add_u64 v[160:161], v[204:205], 0, s[22:23]
	s_addc_u32 s65, s65, 0
	s_add_i32 s66, s58, s8
	global_load_lds_dwordx4 v[160:161], off
	s_mov_b32 m0, s66
	s_nop 0
	global_load_lds_dwordx4 v132, s[64:65]
	s_add_i32 m0, s66, 0x2000
	s_nop 0
	global_load_lds_dwordx4 v136, s[64:65]
	v_lshl_add_u64 v[160:161], v[224:225], 0, s[22:23]
	s_mov_b32 m0, s15
	s_nop 0
	global_load_lds_dwordx4 v[160:161], off
	v_lshl_add_u64 v[160:161], v[226:227], 0, s[22:23]
	s_mov_b32 m0, s16
	s_nop 0
	global_load_lds_dwordx4 v[160:161], off
	s_waitcnt vmcnt(8)
	s_waitcnt lgkmcnt(0)
	s_barrier
	s_setprio 1
	s_waitcnt lgkmcnt(0)
	v_mfma_f32_16x16x32_bf16 v[62:65], v[146:149], v[188:191], v[62:65]
	v_mfma_f32_16x16x32_bf16 v[58:61], v[164:167], v[188:191], v[58:61]
	v_mfma_f32_16x16x32_bf16 v[46:49], v[146:149], v[196:199], v[46:49]
	v_mfma_f32_16x16x32_bf16 v[42:45], v[164:167], v[196:199], v[42:45]
	v_mfma_f32_16x16x32_bf16 v[30:33], v[146:149], v[208:211], v[30:33]
	v_mfma_f32_16x16x32_bf16 v[26:29], v[164:167], v[208:211], v[26:29]
	v_mfma_f32_16x16x32_bf16 v[14:17], v[146:149], v[216:219], v[14:17]
	v_mfma_f32_16x16x32_bf16 v[10:13], v[164:167], v[216:219], v[10:13]
	v_mfma_f32_16x16x32_bf16 v[62:65], v[150:153], v[192:195], v[62:65]
	v_mfma_f32_16x16x32_bf16 v[58:61], v[168:171], v[192:195], v[58:61]
	v_mfma_f32_16x16x32_bf16 v[46:49], v[150:153], v[200:203], v[46:49]
	v_mfma_f32_16x16x32_bf16 v[42:45], v[168:171], v[200:203], v[42:45]
	v_mfma_f32_16x16x32_bf16 v[30:33], v[150:153], v[212:215], v[30:33]
	v_mfma_f32_16x16x32_bf16 v[26:29], v[168:171], v[212:215], v[26:29]
	v_mfma_f32_16x16x32_bf16 v[14:17], v[150:153], v[220:223], v[14:17]
	v_mfma_f32_16x16x32_bf16 v[10:13], v[168:171], v[220:223], v[10:13]
	s_setprio 0
	s_setprio 1
	v_mfma_f32_16x16x32_bf16 v[54:57], v[172:175], v[188:191], v[54:57]
	v_mfma_f32_16x16x32_bf16 v[50:53], v[180:183], v[188:191], v[50:53]
	v_mfma_f32_16x16x32_bf16 v[38:41], v[172:175], v[196:199], v[38:41]
	v_mfma_f32_16x16x32_bf16 v[34:37], v[180:183], v[196:199], v[34:37]
	v_mfma_f32_16x16x32_bf16 v[22:25], v[172:175], v[208:211], v[22:25]
	v_mfma_f32_16x16x32_bf16 v[18:21], v[180:183], v[208:211], v[18:21]
	v_mfma_f32_16x16x32_bf16 v[6:9], v[172:175], v[216:219], v[6:9]
	v_mfma_f32_16x16x32_bf16 v[2:5], v[180:183], v[216:219], v[2:5]
	v_mfma_f32_16x16x32_bf16 v[54:57], v[176:179], v[192:195], v[54:57]
	v_mfma_f32_16x16x32_bf16 v[50:53], v[184:187], v[192:195], v[50:53]
	v_mfma_f32_16x16x32_bf16 v[38:41], v[176:179], v[200:203], v[38:41]
	v_mfma_f32_16x16x32_bf16 v[34:37], v[184:187], v[200:203], v[34:37]
	v_mfma_f32_16x16x32_bf16 v[22:25], v[176:179], v[212:215], v[22:25]
	v_mfma_f32_16x16x32_bf16 v[18:21], v[184:187], v[212:215], v[18:21]
	v_mfma_f32_16x16x32_bf16 v[6:9], v[176:179], v[220:223], v[6:9]
	v_mfma_f32_16x16x32_bf16 v[2:5], v[184:187], v[220:223], v[2:5]
	s_setprio 0
	s_barrier
	s_add_i32 s69, s69, 2
	s_add_u32 s50, s50, 0x100
	s_addc_u32 s51, s51, 0
	s_add_u32 s63, s63, 0x100
	s_addc_u32 s68, s68, 0
	s_cmp_gt_u32 s69, 29
	s_cbranch_scc0 .LBB0_781
	s_and_b64 vcc, exec, s[36:37]
	s_cbranch_vccz .LBB0_784
	s_barrier

; #define PG8_STAGE(bufoff, gbase, voff) do { _Pragma("unroll") for (int _i = 0; _i < 2; ++_i) \
;         __builtin_amdgcn_global_load_lds((const unsigned*)((const char*)(gbase) + (voff)[_i]), (PG8_LAS unsigned*)(lds + (bufoff) + ldsw + _i * 8192), 16, 0, 0); } while (0)
; #define PG8_LDA(dst, b, h) do { _Pragma("unroll") for (int m = 0; m < 4; ++m) _Pragma("unroll") for (int k = 0; k < 2; ++k) dst[m][k] = *(const PG8_LAS bf16x8*)(lds + PG8_SA(b, h) + aoff + m * 2048 + k * 1024); } while (0)
; #define PG8_LDB(dst, b, h) do { _Pragma("unroll") for (int n = 0; n < 2; ++n) _Pragma("unroll") for (int k = 0; k < 2; ++k) dst[n][k] = *(const PG8_LAS bf16x8*)(lds + PG8_SB(b, h) + boff + n * 2048 + k * 1024); } while (0)
; #define PG8_MMA(ai, bj, At, Bt) do { __builtin_amdgcn_s_setprio(1); _Pragma("unroll") for (int m = 0; m < 4; ++m) _Pragma("unroll") for (int n = 0; n < 2; ++n) _Pragma("unroll") for (int k = 0; k < 2; ++k) \
;         acc[ai][bj][m][n] = __builtin_amdgcn_mfma_f32_16x16x32_bf16(Bt[n][k], At[m][k], acc[ai][bj][m][n], 0, 0, 0); __builtin_amdgcn_s_setprio(0); } while (0)
; #define PG8_WAIT_V(n) asm volatile("s_waitcnt vmcnt(" #n ")" ::: "memory")
; #define PG8_BAR __builtin_amdgcn_s_barrier()
; template <class Epi, class Sched, bool ALIGN_EPI = false, bool SP2 = false>
; __device__ __forceinline__ void gemm_phase(PG8_LAS unsigned char* lds, const Gemm g, const Sched& S, const Epi& E) {
;     ...
;         for (int t = 0; t < nt; t += 2) {
;             const bool last = (t == nt - 2);
;             const char* a1 = cA + (size_t)(t + 1) * kstep;
;             const char* a2 = last ? nA : cA + (size_t)(t + 2) * kstep; const char* b2 = last ? nB : cB + (size_t)(t + 2) * kstep;
;             const char* a3 = a2 + kstep; const char* b3 = b2 + kstep;
;             if (last && has_next) S.a_ready(nxt);
;             if constexpr (SP2) {
;             PG8_LDB(B0, 0, 0); PG8_LDB(B1, 0, 1); PG8_SCHED; PG8_LDA(At, 0, 0); PG8_STAGE(PG8_SA(1, 1), a1 + hstep, voffA);
;             PG8_WAIT_V(8); PG8_WAIT_L(0); PG8_BAR; PG8_MMA(0, 0, At, B0); PG8_MMA(0, 1, At, B1); PG8_BAR; PG8_SCHED;
;             PG8_LDA(At, 0, 1); PG8_STAGE(PG8_SB(0, 0), b2, voffB); PG8_STAGE(PG8_SB(0, 1), b2 + hstep, voffB); PG8_STAGE(PG8_SA(0, 0), a2, voffA);
;             PG8_WAIT_V(8); PG8_WAIT_L(0); PG8_BAR; PG8_MMA(1, 0, At, B0); PG8_MMA(1, 1, At, B1); PG8_BAR; PG8_SCHED;
.LBB0_824:
	ds_read_b128 v[146:149], v151
	ds_read_b128 v[158:161], v151 offset:1024
	ds_read_b128 v[164:167], v151 offset:2048
	ds_read_b128 v[168:171], v151 offset:3072
	ds_read_b128 v[172:175], v152
	ds_read_b128 v[176:179], v152 offset:1024
	ds_read_b128 v[180:183], v152 offset:2048
	ds_read_b128 v[184:187], v152 offset:3072
	s_add_u32 s64, s50, 0xfff80080
	s_addc_u32 s65, s51, -1
	s_cmp_eq_u32 s69, 28
	s_cselect_b32 s67, s43, s65
	s_cselect_b32 s66, s49, s64
	s_cselect_b32 s65, s41, s68
	s_cselect_b32 s64, s62, s63
	s_add_i32 m0, s8, 0xc000
	ds_read_b128 v[188:191], v153
	ds_read_b128 v[192:195], v153 offset:1024
	ds_read_b128 v[196:199], v153 offset:2048
	ds_read_b128 v[200:203], v153 offset:3072
	ds_read_b128 v[208:211], v153 offset:4096
	ds_read_b128 v[212:215], v153 offset:5120
	ds_read_b128 v[216:219], v153 offset:6144
	ds_read_b128 v[220:223], v153 offset:7168
	global_load_lds_dwordx4 v138, s[50:51]
	s_add_i32 m0, s8, 0xe000
	s_nop 0
	global_load_lds_dwordx4 v140, s[50:51]
	s_waitcnt vmcnt(8)
	s_waitcnt lgkmcnt(0)
	s_barrier
	s_setprio 1
	s_waitcnt lgkmcnt(0)
	v_mfma_f32_16x16x32_bf16 v[126:129], v[146:149], v[188:191], v[126:129]
	v_mfma_f32_16x16x32_bf16 v[122:125], v[164:167], v[188:191], v[122:125]
	v_mfma_f32_16x16x32_bf16 v[110:113], v[146:149], v[196:199], v[110:113]
	v_mfma_f32_16x16x32_bf16 v[106:109], v[164:167], v[196:199], v[106:109]
	v_mfma_f32_16x16x32_bf16 v[94:97], v[146:149], v[208:211], v[94:97]
	v_mfma_f32_16x16x32_bf16 v[90:93], v[164:167], v[208:211], v[90:93]
	v_mfma_f32_16x16x32_bf16 v[78:81], v[146:149], v[216:219], v[78:81]
	v_mfma_f32_16x16x32_bf16 v[74:77], v[164:167], v[216:219], v[74:77]
	v_mfma_f32_16x16x32_bf16 v[126:129], v[158:161], v[192:195], v[126:129]
	v_mfma_f32_16x16x32_bf16 v[122:125], v[168:171], v[192:195], v[122:125]
	v_mfma_f32_16x16x32_bf16 v[110:113], v[158:161], v[200:203], v[110:113]
	v_mfma_f32_16x16x32_bf16 v[106:109], v[168:171], v[200:203], v[106:109]
	v_mfma_f32_16x16x32_bf16 v[94:97], v[158:161], v[212:215], v[94:97]
	v_mfma_f32_16x16x32_bf16 v[90:93], v[168:171], v[212:215], v[90:93]
	v_mfma_f32_16x16x32_bf16 v[78:81], v[158:161], v[220:223], v[78:81]
	v_mfma_f32_16x16x32_bf16 v[74:77], v[168:171], v[220:223], v[74:77]
	s_setprio 0
	s_setprio 1
	v_mfma_f32_16x16x32_bf16 v[118:121], v[172:175], v[188:191], v[118:121]
	v_mfma_f32_16x16x32_bf16 v[114:117], v[180:183], v[188:191], v[114:117]
	v_mfma_f32_16x16x32_bf16 v[102:105], v[172:175], v[196:199], v[102:105]
	v_mfma_f32_16x16x32_bf16 v[98:101], v[180:183], v[196:199], v[98:101]
	v_mfma_f32_16x16x32_bf16 v[86:89], v[172:175], v[208:211], v[86:89]
	v_mfma_f32_16x16x32_bf16 v[82:85], v[180:183], v[208:211], v[82:85]
	v_mfma_f32_16x16x32_bf16 v[70:73], v[172:175], v[216:219], v[70:73]
	v_mfma_f32_16x16x32_bf16 v[66:69], v[180:183], v[216:219], v[66:69]
	v_mfma_f32_16x16x32_bf16 v[118:121], v[176:179], v[192:195], v[118:121]
	v_mfma_f32_16x16x32_bf16 v[114:117], v[184:187], v[192:195], v[114:117]
	v_mfma_f32_16x16x32_bf16 v[102:105], v[176:179], v[200:203], v[102:105]
	v_mfma_f32_16x16x32_bf16 v[98:101], v[184:187], v[200:203], v[98:101]
	v_mfma_f32_16x16x32_bf16 v[86:89], v[176:179], v[212:215], v[86:89]
	v_mfma_f32_16x16x32_bf16 v[82:85], v[184:187], v[212:215], v[82:85]
	v_mfma_f32_16x16x32_bf16 v[70:73], v[176:179], v[220:223], v[70:73]
	v_mfma_f32_16x16x32_bf16 v[66:69], v[184:187], v[220:223], v[66:69]
	s_setprio 0
	s_barrier
	s_add_i32 s70, s35, s2
	v_lshl_add_u64 v[204:205], s[64:65], 0, v[132:133]
	s_mov_b32 m0, s70
	ds_read_b128 v[188:191], v153 offset:16384
	ds_read_b128 v[192:195], v153 offset:17408
	ds_read_b128 v[196:199], v153 offset:18432
	ds_read_b128 v[200:203], v153 offset:19456
	ds_read_b128 v[208:211], v153 offset:20480
	ds_read_b128 v[212:215], v153 offset:21504
	ds_read_b128 v[216:219], v153 offset:22528
	ds_read_b128 v[220:223], v153 offset:23552
	global_load_lds_dwordx4 v[204:205], off
	s_add_i32 m0, s70, 0x2000
	s_add_u32 s70, s64, 0x80000
	v_lshl_add_u64 v[224:225], s[64:65], 0, v[136:137]
	s_addc_u32 s71, s65, 0
	s_add_i32 s72, s57, s2
	global_load_lds_dwordx4 v[224:225], off
	s_mov_b32 m0, s72
	v_lshl_add_u64 v[228:229], s[66:67], 0, v[134:135]
	global_load_lds_dwordx4 v132, s[70:71]
	s_add_i32 m0, s72, 0x2000
	s_nop 0
	global_load_lds_dwordx4 v136, s[70:71]
	v_lshl_add_u64 v[226:227], s[66:67], 0, v[130:131]
	s_mov_b32 m0, s8
	s_nop 0
	global_load_lds_dwordx4 v[226:227], off
	s_mov_b32 m0, s9
	s_nop 0
	global_load_lds_dwordx4 v[228:229], off
	s_waitcnt vmcnt(8)
	s_waitcnt lgkmcnt(0)
	s_barrier
; #define PG8_STAGE(bufoff, gbase, voff) do { _Pragma("unroll") for (int _i = 0; _i < 2; ++_i) \
;         __builtin_amdgcn_global_load_lds((const unsigned*)((const char*)(gbase) + (voff)[_i]), (PG8_LAS unsigned*)(lds + (bufoff) + ldsw + _i * 8192), 16, 0, 0); } while (0)
; #define PG8_LDA(dst, b, h) do { _Pragma("unroll") for (int m = 0; m < 4; ++m) _Pragma("unroll") for (int k = 0; k < 2; ++k) dst[m][k] = *(const PG8_LAS bf16x8*)(lds + PG8_SA(b, h) + aoff + m * 2048 + k * 1024); } while (0)
; #define PG8_LDB(dst, b, h) do { _Pragma("unroll") for (int n = 0; n < 2; ++n) _Pragma("unroll") for (int k = 0; k < 2; ++k) dst[n][k] = *(const PG8_LAS bf16x8*)(lds + PG8_SB(b, h) + boff + n * 2048 + k * 1024); } while (0)
; #define PG8_MMA(ai, bj, At, Bt) do { __builtin_amdgcn_s_setprio(1); _Pragma("unroll") for (int m = 0; m < 4; ++m) _Pragma("unroll") for (int n = 0; n < 2; ++n) _Pragma("unroll") for (int k = 0; k < 2; ++k) \
;         acc[ai][bj][m][n] = __builtin_amdgcn_mfma_f32_16x16x32_bf16(Bt[n][k], At[m][k], acc[ai][bj][m][n], 0, 0, 0); __builtin_amdgcn_s_setprio(0); } while (0)
; #define PG8_WAIT_V(n) asm volatile("s_waitcnt vmcnt(" #n ")" ::: "memory")
; #define PG8_WAIT_L(n) asm volatile("s_waitcnt lgkmcnt(" #n ")" ::: "memory")
; #define PG8_BAR __builtin_amdgcn_s_barrier()
; #define PG8_SCHED __builtin_amdgcn_sched_barrier(0)
; template <class Epi, class Sched, bool ALIGN_EPI = false, bool SP2 = false>
; __device__ __forceinline__ void gemm_phase(PG8_LAS unsigned char* lds, const Gemm g, const Sched& S, const Epi& E) {
;     ...
;             PG8_WAIT_V(8); PG8_WAIT_L(0); PG8_BAR; PG8_MMA(1, 0, At, B0); PG8_MMA(1, 1, At, B1); PG8_BAR; PG8_SCHED;
;             PG8_LDB(B0, 1, 0); PG8_LDB(B1, 1, 1); PG8_SCHED; PG8_LDA(At, 1, 0); PG8_STAGE(PG8_SA(0, 1), a2 + hstep, voffA);
;             PG8_WAIT_V(8); PG8_WAIT_L(0); PG8_BAR; PG8_MMA(0, 0, At, B0); PG8_MMA(0, 1, At, B1); PG8_BAR; PG8_SCHED;
;             PG8_LDA(At, 1, 1); PG8_STAGE(PG8_SB(1, 0), b3, voffB); PG8_STAGE(PG8_SB(1, 1), b3 + hstep, voffB); PG8_STAGE(PG8_SA(1, 0), a3, voffA);
	s_setprio 1
	s_waitcnt lgkmcnt(0)
	v_mfma_f32_16x16x32_bf16 v[62:65], v[146:149], v[188:191], v[62:65]
	v_mfma_f32_16x16x32_bf16 v[58:61], v[164:167], v[188:191], v[58:61]
	v_mfma_f32_16x16x32_bf16 v[46:49], v[146:149], v[196:199], v[46:49]
	v_mfma_f32_16x16x32_bf16 v[42:45], v[164:167], v[196:199], v[42:45]
	v_mfma_f32_16x16x32_bf16 v[30:33], v[146:149], v[208:211], v[30:33]
	v_mfma_f32_16x16x32_bf16 v[26:29], v[164:167], v[208:211], v[26:29]
	v_mfma_f32_16x16x32_bf16 v[14:17], v[146:149], v[216:219], v[14:17]
	v_mfma_f32_16x16x32_bf16 v[10:13], v[164:167], v[216:219], v[10:13]
	v_mfma_f32_16x16x32_bf16 v[62:65], v[158:161], v[192:195], v[62:65]
	v_mfma_f32_16x16x32_bf16 v[58:61], v[168:171], v[192:195], v[58:61]
	v_mfma_f32_16x16x32_bf16 v[46:49], v[158:161], v[200:203], v[46:49]
	v_mfma_f32_16x16x32_bf16 v[42:45], v[168:171], v[200:203], v[42:45]
	v_mfma_f32_16x16x32_bf16 v[30:33], v[158:161], v[212:215], v[30:33]
	v_mfma_f32_16x16x32_bf16 v[26:29], v[168:171], v[212:215], v[26:29]
	v_mfma_f32_16x16x32_bf16 v[14:17], v[158:161], v[220:223], v[14:17]
	v_mfma_f32_16x16x32_bf16 v[10:13], v[168:171], v[220:223], v[10:13]
	s_setprio 0
	s_setprio 1
	v_mfma_f32_16x16x32_bf16 v[54:57], v[172:175], v[188:191], v[54:57]
	v_mfma_f32_16x16x32_bf16 v[50:53], v[180:183], v[188:191], v[50:53]
	v_mfma_f32_16x16x32_bf16 v[38:41], v[172:175], v[196:199], v[38:41]
	v_mfma_f32_16x16x32_bf16 v[34:37], v[180:183], v[196:199], v[34:37]
	v_mfma_f32_16x16x32_bf16 v[22:25], v[172:175], v[208:211], v[22:25]
	v_mfma_f32_16x16x32_bf16 v[18:21], v[180:183], v[208:211], v[18:21]
	v_mfma_f32_16x16x32_bf16 v[6:9], v[172:175], v[216:219], v[6:9]
	v_mfma_f32_16x16x32_bf16 v[2:5], v[180:183], v[216:219], v[2:5]
	v_mfma_f32_16x16x32_bf16 v[54:57], v[176:179], v[192:195], v[54:57]
	v_mfma_f32_16x16x32_bf16 v[50:53], v[184:187], v[192:195], v[50:53]
	v_mfma_f32_16x16x32_bf16 v[38:41], v[176:179], v[200:203], v[38:41]
	v_mfma_f32_16x16x32_bf16 v[34:37], v[184:187], v[200:203], v[34:37]
	v_mfma_f32_16x16x32_bf16 v[22:25], v[176:179], v[212:215], v[22:25]
	v_mfma_f32_16x16x32_bf16 v[18:21], v[184:187], v[212:215], v[18:21]
	v_mfma_f32_16x16x32_bf16 v[6:9], v[176:179], v[220:223], v[6:9]
	v_mfma_f32_16x16x32_bf16 v[2:5], v[184:187], v[220:223], v[2:5]
	s_setprio 0
	s_barrier
	ds_read_b128 v[146:149], v154
	ds_read_b128 v[158:161], v154 offset:1024
	ds_read_b128 v[164:167], v154 offset:2048
	ds_read_b128 v[168:171], v154 offset:3072
	ds_read_b128 v[172:175], v155
	ds_read_b128 v[176:179], v155 offset:1024
	ds_read_b128 v[180:183], v155 offset:2048
	ds_read_b128 v[184:187], v155 offset:3072
	s_add_u32 s66, s66, 0x80000
	s_addc_u32 s67, s67, 0
	s_mov_b32 m0, s12
	ds_read_b128 v[188:191], v153 offset:32768
	ds_read_b128 v[192:195], v153 offset:33792
	ds_read_b128 v[196:199], v153 offset:34816
	ds_read_b128 v[200:203], v153 offset:35840
	ds_read_b128 v[208:211], v153 offset:36864
	ds_read_b128 v[212:215], v153 offset:37888
	ds_read_b128 v[216:219], v153 offset:38912
	ds_read_b128 v[220:223], v153 offset:39936
	global_load_lds_dwordx4 v130, s[66:67]
	s_mov_b32 m0, s13
	s_nop 0
	global_load_lds_dwordx4 v134, s[66:67]
	s_waitcnt vmcnt(8)
	s_waitcnt lgkmcnt(0)
	s_barrier
	s_setprio 1
	s_waitcnt lgkmcnt(0)
	v_mfma_f32_16x16x32_bf16 v[126:129], v[146:149], v[188:191], v[126:129]
	v_mfma_f32_16x16x32_bf16 v[122:125], v[164:167], v[188:191], v[122:125]
	v_mfma_f32_16x16x32_bf16 v[110:113], v[146:149], v[196:199], v[110:113]
	v_mfma_f32_16x16x32_bf16 v[106:109], v[164:167], v[196:199], v[106:109]
	v_mfma_f32_16x16x32_bf16 v[94:97], v[146:149], v[208:211], v[94:97]
	v_mfma_f32_16x16x32_bf16 v[90:93], v[164:167], v[208:211], v[90:93]
	v_mfma_f32_16x16x32_bf16 v[78:81], v[146:149], v[216:219], v[78:81]
	v_mfma_f32_16x16x32_bf16 v[74:77], v[164:167], v[216:219], v[74:77]
	v_mfma_f32_16x16x32_bf16 v[126:129], v[158:161], v[192:195], v[126:129]
	v_mfma_f32_16x16x32_bf16 v[122:125], v[168:171], v[192:195], v[122:125]
	v_mfma_f32_16x16x32_bf16 v[110:113], v[158:161], v[200:203], v[110:113]
	v_mfma_f32_16x16x32_bf16 v[106:109], v[168:171], v[200:203], v[106:109]
	v_mfma_f32_16x16x32_bf16 v[94:97], v[158:161], v[212:215], v[94:97]
	v_mfma_f32_16x16x32_bf16 v[90:93], v[168:171], v[212:215], v[90:93]
	v_mfma_f32_16x16x32_bf16 v[78:81], v[158:161], v[220:223], v[78:81]
	v_mfma_f32_16x16x32_bf16 v[74:77], v[168:171], v[220:223], v[74:77]
	s_setprio 0
	s_setprio 1
	v_mfma_f32_16x16x32_bf16 v[118:121], v[172:175], v[188:191], v[118:121]
	v_mfma_f32_16x16x32_bf16 v[114:117], v[180:183], v[188:191], v[114:117]
	v_mfma_f32_16x16x32_bf16 v[102:105], v[172:175], v[196:199], v[102:105]
	v_mfma_f32_16x16x32_bf16 v[98:101], v[180:183], v[196:199], v[98:101]
	v_mfma_f32_16x16x32_bf16 v[86:89], v[172:175], v[208:211], v[86:89]
	v_mfma_f32_16x16x32_bf16 v[82:85], v[180:183], v[208:211], v[82:85]
	v_mfma_f32_16x16x32_bf16 v[70:73], v[172:175], v[216:219], v[70:73]
	v_mfma_f32_16x16x32_bf16 v[66:69], v[180:183], v[216:219], v[66:69]
	v_mfma_f32_16x16x32_bf16 v[118:121], v[176:179], v[192:195], v[118:121]
	v_mfma_f32_16x16x32_bf16 v[114:117], v[184:187], v[192:195], v[114:117]
	v_mfma_f32_16x16x32_bf16 v[102:105], v[176:179], v[200:203], v[102:105]
	v_mfma_f32_16x16x32_bf16 v[98:101], v[184:187], v[200:203], v[98:101]
	v_mfma_f32_16x16x32_bf16 v[86:89], v[176:179], v[212:215], v[86:89]
	v_mfma_f32_16x16x32_bf16 v[82:85], v[184:187], v[212:215], v[82:85]
	v_mfma_f32_16x16x32_bf16 v[70:73], v[176:179], v[220:223], v[70:73]
	v_mfma_f32_16x16x32_bf16 v[66:69], v[184:187], v[220:223], v[66:69]
	s_setprio 0
	s_barrier
; #define PG8_STAGE(bufoff, gbase, voff) do { _Pragma("unroll") for (int _i = 0; _i < 2; ++_i) \
;         __builtin_amdgcn_global_load_lds((const unsigned*)((const char*)(gbase) + (voff)[_i]), (PG8_LAS unsigned*)(lds + (bufoff) + ldsw + _i * 8192), 16, 0, 0); } while (0)
; #define PG8_LDA(dst, b, h) do { _Pragma("unroll") for (int m = 0; m < 4; ++m) _Pragma("unroll") for (int k = 0; k < 2; ++k) dst[m][k] = *(const PG8_LAS bf16x8*)(lds + PG8_SA(b, h) + aoff + m * 2048 + k * 1024); } while (0)
; #define PG8_MMA(ai, bj, At, Bt) do { __builtin_amdgcn_s_setprio(1); _Pragma("unroll") for (int m = 0; m < 4; ++m) _Pragma("unroll") for (int n = 0; n < 2; ++n) _Pragma("unroll") for (int k = 0; k < 2; ++k) \
;         acc[ai][bj][m][n] = __builtin_amdgcn_mfma_f32_16x16x32_bf16(Bt[n][k], At[m][k], acc[ai][bj][m][n], 0, 0, 0); __builtin_amdgcn_s_setprio(0); } while (0)
; #define PG8_WAIT_V(n) asm volatile("s_waitcnt vmcnt(" #n ")" ::: "memory")
; #define PG8_WAIT_L(n) asm volatile("s_waitcnt lgkmcnt(" #n ")" ::: "memory")
; #define PG8_BAR __builtin_amdgcn_s_barrier()
; #define PG8_SCHED __builtin_amdgcn_sched_barrier(0)
; template <class Epi, class Sched, bool ALIGN_EPI = false, bool SP2 = false>
; __device__ __forceinline__ void gemm_phase(PG8_LAS unsigned char* lds, const Gemm g, const Sched& S, const Epi& E) {
;     ...
;         for (int t = 0; t < nt; t += 2) {
;             const bool last = (t == nt - 2);
;             const char* a1 = cA + (size_t)(t + 1) * kstep;
;             const char* a2 = last ? nA : cA + (size_t)(t + 2) * kstep; const char* b2 = last ? nB : cB + (size_t)(t + 2) * kstep;
;     ...
;             PG8_LDA(At, 1, 1); PG8_STAGE(PG8_SB(1, 0), b3, voffB); PG8_STAGE(PG8_SB(1, 1), b3 + hstep, voffB); PG8_STAGE(PG8_SA(1, 0), a3, voffA);
;             PG8_WAIT_V(8); PG8_WAIT_L(0); PG8_BAR; PG8_MMA(1, 0, At, B0); PG8_MMA(1, 1, At, B1); PG8_BAR; PG8_SCHED;
	s_add_i32 s66, s58, s2
	v_lshl_add_u64 v[204:205], v[204:205], 0, s[20:21]
	s_mov_b32 m0, s66
	ds_read_b128 v[188:191], v153 offset:49152
	ds_read_b128 v[192:195], v153 offset:50176
	ds_read_b128 v[196:199], v153 offset:51200
	ds_read_b128 v[200:203], v153 offset:52224
	ds_read_b128 v[208:211], v153 offset:53248
	ds_read_b128 v[212:215], v153 offset:54272
	ds_read_b128 v[216:219], v153 offset:55296
	ds_read_b128 v[220:223], v153 offset:56320
	global_load_lds_dwordx4 v[204:205], off
	s_add_i32 m0, s66, 0x2000
	s_add_u32 s64, s64, 0x80080
	v_lshl_add_u64 v[204:205], v[224:225], 0, s[20:21]
	s_addc_u32 s65, s65, 0
	s_add_i32 s66, s59, s2
	global_load_lds_dwordx4 v[204:205], off
	s_mov_b32 m0, s66
	s_nop 0
	global_load_lds_dwordx4 v132, s[64:65]
	s_add_i32 m0, s66, 0x2000
	s_nop 0
	global_load_lds_dwordx4 v136, s[64:65]
	v_lshl_add_u64 v[204:205], v[226:227], 0, s[20:21]
	s_mov_b32 m0, s14
	s_nop 0
	global_load_lds_dwordx4 v[204:205], off
	v_lshl_add_u64 v[204:205], v[228:229], 0, s[20:21]
	s_mov_b32 m0, s15
	s_nop 0
	global_load_lds_dwordx4 v[204:205], off
	s_waitcnt vmcnt(8)
	s_waitcnt lgkmcnt(0)
	s_barrier
	s_setprio 1
	s_waitcnt lgkmcnt(0)
	v_mfma_f32_16x16x32_bf16 v[62:65], v[146:149], v[188:191], v[62:65]
	v_mfma_f32_16x16x32_bf16 v[58:61], v[164:167], v[188:191], v[58:61]
	v_mfma_f32_16x16x32_bf16 v[46:49], v[146:149], v[196:199], v[46:49]
	v_mfma_f32_16x16x32_bf16 v[42:45], v[164:167], v[196:199], v[42:45]
	v_mfma_f32_16x16x32_bf16 v[30:33], v[146:149], v[208:211], v[30:33]
	v_mfma_f32_16x16x32_bf16 v[26:29], v[164:167], v[208:211], v[26:29]
	v_mfma_f32_16x16x32_bf16 v[14:17], v[146:149], v[216:219], v[14:17]
	v_mfma_f32_16x16x32_bf16 v[10:13], v[164:167], v[216:219], v[10:13]
	v_mfma_f32_16x16x32_bf16 v[62:65], v[158:161], v[192:195], v[62:65]
	v_mfma_f32_16x16x32_bf16 v[58:61], v[168:171], v[192:195], v[58:61]
	v_mfma_f32_16x16x32_bf16 v[46:49], v[158:161], v[200:203], v[46:49]
	v_mfma_f32_16x16x32_bf16 v[42:45], v[168:171], v[200:203], v[42:45]
	v_mfma_f32_16x16x32_bf16 v[30:33], v[158:161], v[212:215], v[30:33]
	v_mfma_f32_16x16x32_bf16 v[26:29], v[168:171], v[212:215], v[26:29]
	v_mfma_f32_16x16x32_bf16 v[14:17], v[158:161], v[220:223], v[14:17]
	v_mfma_f32_16x16x32_bf16 v[10:13], v[168:171], v[220:223], v[10:13]
	s_setprio 0
	s_setprio 1
	v_mfma_f32_16x16x32_bf16 v[54:57], v[172:175], v[188:191], v[54:57]
	v_mfma_f32_16x16x32_bf16 v[50:53], v[180:183], v[188:191], v[50:53]
	v_mfma_f32_16x16x32_bf16 v[38:41], v[172:175], v[196:199], v[38:41]
	v_mfma_f32_16x16x32_bf16 v[34:37], v[180:183], v[196:199], v[34:37]
	v_mfma_f32_16x16x32_bf16 v[22:25], v[172:175], v[208:211], v[22:25]
	v_mfma_f32_16x16x32_bf16 v[18:21], v[180:183], v[208:211], v[18:21]
	v_mfma_f32_16x16x32_bf16 v[6:9], v[172:175], v[216:219], v[6:9]
	v_mfma_f32_16x16x32_bf16 v[2:5], v[180:183], v[216:219], v[2:5]
	v_mfma_f32_16x16x32_bf16 v[54:57], v[176:179], v[192:195], v[54:57]
	v_mfma_f32_16x16x32_bf16 v[50:53], v[184:187], v[192:195], v[50:53]
	v_mfma_f32_16x16x32_bf16 v[38:41], v[176:179], v[200:203], v[38:41]
	v_mfma_f32_16x16x32_bf16 v[34:37], v[184:187], v[200:203], v[34:37]
	v_mfma_f32_16x16x32_bf16 v[22:25], v[176:179], v[212:215], v[22:25]
	v_mfma_f32_16x16x32_bf16 v[18:21], v[184:187], v[212:215], v[18:21]
	v_mfma_f32_16x16x32_bf16 v[6:9], v[176:179], v[220:223], v[6:9]
	v_mfma_f32_16x16x32_bf16 v[2:5], v[184:187], v[220:223], v[2:5]
	s_setprio 0
	s_barrier
	s_add_i32 s69, s69, 2
	s_add_u32 s50, s50, 0x100
	s_addc_u32 s51, s51, 0
	s_add_u32 s63, s63, 0x100
	s_addc_u32 s68, s68, 0
	s_cmp_gt_u32 s69, 29
	s_cbranch_scc0 .LBB0_824
	s_and_b64 vcc, exec, s[38:39]
	s_cbranch_vccz .LBB0_827
	s_barrier

; #define PG8_STAGE(bufoff, gbase, voff) do { _Pragma("unroll") for (int _i = 0; _i < 2; ++_i) \
;         __builtin_amdgcn_global_load_lds((const unsigned*)((const char*)(gbase) + (voff)[_i]), (PG8_LAS unsigned*)(lds + (bufoff) + ldsw + _i * 8192), 16, 0, 0); } while (0)
; #define PG8_LDA(dst, b, h) do { _Pragma("unroll") for (int m = 0; m < 4; ++m) _Pragma("unroll") for (int k = 0; k < 2; ++k) dst[m][k] = *(const PG8_LAS bf16x8*)(lds + PG8_SA(b, h) + aoff + m * 2048 + k * 1024); } while (0)
; #define PG8_LDB(dst, b, h) do { _Pragma("unroll") for (int n = 0; n < 2; ++n) _Pragma("unroll") for (int k = 0; k < 2; ++k) dst[n][k] = *(const PG8_LAS bf16x8*)(lds + PG8_SB(b, h) + boff + n * 2048 + k * 1024); } while (0)
; #define PG8_MMA(ai, bj, At, Bt) do { __builtin_amdgcn_s_setprio(1); _Pragma("unroll") for (int m = 0; m < 4; ++m) _Pragma("unroll") for (int n = 0; n < 2; ++n) _Pragma("unroll") for (int k = 0; k < 2; ++k) \
;         acc[ai][bj][m][n] = __builtin_amdgcn_mfma_f32_16x16x32_bf16(Bt[n][k], At[m][k], acc[ai][bj][m][n], 0, 0, 0); __builtin_amdgcn_s_setprio(0); } while (0)
; #define PG8_WAIT_V(n) asm volatile("s_waitcnt vmcnt(" #n ")" ::: "memory")
; #define PG8_BAR __builtin_amdgcn_s_barrier()
; template <class Epi, class Sched, bool ALIGN_EPI = false, bool SP2 = false>
; __device__ __forceinline__ void gemm_phase(PG8_LAS unsigned char* lds, const Gemm g, const Sched& S, const Epi& E) {
;     ...
;         for (int t = 0; t < nt; t += 2) {
;             const bool last = (t == nt - 2);
;             const char* a1 = cA + (size_t)(t + 1) * kstep;
;             const char* a2 = last ? nA : cA + (size_t)(t + 2) * kstep; const char* b2 = last ? nB : cB + (size_t)(t + 2) * kstep;
;             const char* a3 = a2 + kstep; const char* b3 = b2 + kstep;
;             if (last && has_next) S.a_ready(nxt);
;             if constexpr (SP2) {
;             PG8_LDB(B0, 0, 0); PG8_LDB(B1, 0, 1); PG8_SCHED; PG8_LDA(At, 0, 0); PG8_STAGE(PG8_SA(1, 1), a1 + hstep, voffA);
;             PG8_WAIT_V(8); PG8_WAIT_L(0); PG8_BAR; PG8_MMA(0, 0, At, B0); PG8_MMA(0, 1, At, B1); PG8_BAR; PG8_SCHED;
;             PG8_LDA(At, 0, 1); PG8_STAGE(PG8_SB(0, 0), b2, voffB); PG8_STAGE(PG8_SB(0, 1), b2 + hstep, voffB); PG8_STAGE(PG8_SA(0, 0), a2, voffA);
;             PG8_WAIT_V(8); PG8_WAIT_L(0); PG8_BAR; PG8_MMA(1, 0, At, B0); PG8_MMA(1, 1, At, B1); PG8_BAR; PG8_SCHED;
.LBB0_908:
	ds_read_b128 v[82:85], v207
	ds_read_b128 v[86:89], v207 offset:1024
	ds_read_b128 v[90:93], v207 offset:2048
	ds_read_b128 v[94:97], v207 offset:3072
	ds_read_b128 v[98:101], v208
	ds_read_b128 v[102:105], v208 offset:1024
	ds_read_b128 v[106:109], v208 offset:2048
	ds_read_b128 v[110:113], v208 offset:3072
	s_add_u32 s70, s68, 0xfff80080
	s_addc_u32 s71, s69, -1
	s_cmp_eq_u32 s86, 28
	s_cselect_b32 s73, s49, s71
	s_cselect_b32 s72, s82, s70
	s_cselect_b32 s71, s47, s85
	s_cselect_b32 s70, s83, s84
	s_add_i32 m0, s35, 0xc000
	ds_read_b128 v[186:189], v209
	ds_read_b128 v[190:193], v209 offset:1024
	ds_read_b128 v[194:197], v209 offset:2048
	ds_read_b128 v[198:201], v209 offset:3072
	ds_read_b128 v[202:205], v209 offset:4096
	ds_read_b128 v[216:219], v209 offset:5120
	ds_read_b128 v[220:223], v209 offset:6144
	ds_read_b128 v[224:227], v209 offset:7168
	global_load_lds_dwordx4 v178, s[68:69]
	s_add_i32 m0, s35, 0xe000
	s_nop 0
	global_load_lds_dwordx4 v180, s[68:69]
	s_waitcnt vmcnt(8)
	s_waitcnt lgkmcnt(0)
	s_barrier
	s_setprio 1
	s_waitcnt lgkmcnt(0)
	v_mfma_f32_16x16x32_bf16 v[158:161], v[82:85], v[186:189], v[158:161]
	v_mfma_f32_16x16x32_bf16 v[154:157], v[90:93], v[186:189], v[154:157]
	v_mfma_f32_16x16x32_bf16 v[142:145], v[82:85], v[194:197], v[142:145]
	v_mfma_f32_16x16x32_bf16 v[138:141], v[90:93], v[194:197], v[138:141]
	v_mfma_f32_16x16x32_bf16 v[126:129], v[82:85], v[202:205], v[126:129]
	v_mfma_f32_16x16x32_bf16 v[122:125], v[90:93], v[202:205], v[122:125]
	v_mfma_f32_16x16x32_bf16 v[78:81], v[82:85], v[220:223], v[78:81]
	v_mfma_f32_16x16x32_bf16 v[70:73], v[90:93], v[220:223], v[70:73]
	v_mfma_f32_16x16x32_bf16 v[158:161], v[86:89], v[190:193], v[158:161]
	v_mfma_f32_16x16x32_bf16 v[154:157], v[94:97], v[190:193], v[154:157]
	v_mfma_f32_16x16x32_bf16 v[142:145], v[86:89], v[198:201], v[142:145]
	v_mfma_f32_16x16x32_bf16 v[138:141], v[94:97], v[198:201], v[138:141]
	v_mfma_f32_16x16x32_bf16 v[126:129], v[86:89], v[216:219], v[126:129]
	v_mfma_f32_16x16x32_bf16 v[122:125], v[94:97], v[216:219], v[122:125]
	v_mfma_f32_16x16x32_bf16 v[78:81], v[86:89], v[224:227], v[78:81]
	v_mfma_f32_16x16x32_bf16 v[70:73], v[94:97], v[224:227], v[70:73]
	s_setprio 0
	s_setprio 1
	v_mfma_f32_16x16x32_bf16 v[150:153], v[98:101], v[186:189], v[150:153]
	v_mfma_f32_16x16x32_bf16 v[146:149], v[106:109], v[186:189], v[146:149]
	v_mfma_f32_16x16x32_bf16 v[134:137], v[98:101], v[194:197], v[134:137]
	v_mfma_f32_16x16x32_bf16 v[130:133], v[106:109], v[194:197], v[130:133]
	v_mfma_f32_16x16x32_bf16 v[118:121], v[98:101], v[202:205], v[118:121]
	v_mfma_f32_16x16x32_bf16 v[114:117], v[106:109], v[202:205], v[114:117]
	v_mfma_f32_16x16x32_bf16 v[74:77], v[98:101], v[220:223], v[74:77]
	v_mfma_f32_16x16x32_bf16 v[66:69], v[106:109], v[220:223], v[66:69]
	v_mfma_f32_16x16x32_bf16 v[150:153], v[102:105], v[190:193], v[150:153]
	v_mfma_f32_16x16x32_bf16 v[146:149], v[110:113], v[190:193], v[146:149]
	v_mfma_f32_16x16x32_bf16 v[134:137], v[102:105], v[198:201], v[134:137]
	v_mfma_f32_16x16x32_bf16 v[130:133], v[110:113], v[198:201], v[130:133]
	v_mfma_f32_16x16x32_bf16 v[118:121], v[102:105], v[216:219], v[118:121]
	v_mfma_f32_16x16x32_bf16 v[114:117], v[110:113], v[216:219], v[114:117]
	v_mfma_f32_16x16x32_bf16 v[74:77], v[102:105], v[224:227], v[74:77]
	v_mfma_f32_16x16x32_bf16 v[66:69], v[110:113], v[224:227], v[66:69]
	s_setprio 0
	s_barrier
	s_add_i32 s87, s75, s16
	v_lshl_add_u64 v[228:229], s[70:71], 0, v[170:171]
	s_mov_b32 m0, s87
	ds_read_b128 v[186:189], v209 offset:16384
	ds_read_b128 v[190:193], v209 offset:17408
	ds_read_b128 v[194:197], v209 offset:18432
	ds_read_b128 v[198:201], v209 offset:19456
	ds_read_b128 v[202:205], v209 offset:20480
	ds_read_b128 v[216:219], v209 offset:21504
	ds_read_b128 v[220:223], v209 offset:22528
	ds_read_b128 v[224:227], v209 offset:23552
	global_load_lds_dwordx4 v[228:229], off
	s_add_i32 m0, s87, 0x2000
	s_add_u32 s88, s70, 0x80000
	v_lshl_add_u64 v[230:231], s[70:71], 0, v[166:167]
	s_addc_u32 s89, s71, 0
	s_add_i32 s87, s76, s16
	global_load_lds_dwordx4 v[230:231], off
	s_mov_b32 m0, s87
	v_lshl_add_u64 v[234:235], s[72:73], 0, v[168:169]
	global_load_lds_dwordx4 v170, s[88:89]
	s_add_i32 m0, s87, 0x2000
	s_nop 0
	global_load_lds_dwordx4 v166, s[88:89]
	v_lshl_add_u64 v[232:233], s[72:73], 0, v[172:173]
	s_mov_b32 m0, s35
	s_nop 0
	global_load_lds_dwordx4 v[232:233], off
	s_mov_b32 m0, s57
	s_nop 0
	global_load_lds_dwordx4 v[234:235], off
	s_waitcnt vmcnt(8)
	s_waitcnt lgkmcnt(0)
	s_barrier
	s_setprio 1
	s_waitcnt lgkmcnt(0)
	v_mfma_f32_16x16x32_bf16 v[62:65], v[82:85], v[186:189], v[62:65]
	v_mfma_f32_16x16x32_bf16 v[58:61], v[90:93], v[186:189], v[58:61]
	v_mfma_f32_16x16x32_bf16 v[46:49], v[82:85], v[194:197], v[46:49]
	v_mfma_f32_16x16x32_bf16 v[42:45], v[90:93], v[194:197], v[42:45]
	v_mfma_f32_16x16x32_bf16 v[30:33], v[82:85], v[202:205], v[30:33]
	v_mfma_f32_16x16x32_bf16 v[26:29], v[90:93], v[202:205], v[26:29]
	v_mfma_f32_16x16x32_bf16 v[10:13], v[82:85], v[220:223], v[10:13]
	v_mfma_f32_16x16x32_bf16 v[6:9], v[90:93], v[220:223], v[6:9]
	v_mfma_f32_16x16x32_bf16 v[62:65], v[86:89], v[190:193], v[62:65]
	v_mfma_f32_16x16x32_bf16 v[58:61], v[94:97], v[190:193], v[58:61]
	v_mfma_f32_16x16x32_bf16 v[46:49], v[86:89], v[198:201], v[46:49]
	v_mfma_f32_16x16x32_bf16 v[42:45], v[94:97], v[198:201], v[42:45]
	v_mfma_f32_16x16x32_bf16 v[30:33], v[86:89], v[216:219], v[30:33]
	v_mfma_f32_16x16x32_bf16 v[26:29], v[94:97], v[216:219], v[26:29]
	v_mfma_f32_16x16x32_bf16 v[10:13], v[86:89], v[224:227], v[10:13]
	v_mfma_f32_16x16x32_bf16 v[6:9], v[94:97], v[224:227], v[6:9]
	s_setprio 0
	s_setprio 1
	v_mfma_f32_16x16x32_bf16 v[54:57], v[98:101], v[186:189], v[54:57]
	v_mfma_f32_16x16x32_bf16 v[50:53], v[106:109], v[186:189], v[50:53]
	v_mfma_f32_16x16x32_bf16 v[38:41], v[98:101], v[194:197], v[38:41]
	v_mfma_f32_16x16x32_bf16 v[34:37], v[106:109], v[194:197], v[34:37]
	v_mfma_f32_16x16x32_bf16 v[22:25], v[98:101], v[202:205], v[22:25]
	v_mfma_f32_16x16x32_bf16 v[18:21], v[106:109], v[202:205], v[18:21]
	v_mfma_f32_16x16x32_bf16 v[14:17], v[98:101], v[220:223], v[14:17]
	v_mfma_f32_16x16x32_bf16 v[2:5], v[106:109], v[220:223], v[2:5]
	v_mfma_f32_16x16x32_bf16 v[54:57], v[102:105], v[190:193], v[54:57]
	v_mfma_f32_16x16x32_bf16 v[50:53], v[110:113], v[190:193], v[50:53]
	v_mfma_f32_16x16x32_bf16 v[38:41], v[102:105], v[198:201], v[38:41]
	v_mfma_f32_16x16x32_bf16 v[34:37], v[110:113], v[198:201], v[34:37]
	v_mfma_f32_16x16x32_bf16 v[22:25], v[102:105], v[216:219], v[22:25]
	v_mfma_f32_16x16x32_bf16 v[18:21], v[110:113], v[216:219], v[18:21]
	v_mfma_f32_16x16x32_bf16 v[14:17], v[102:105], v[224:227], v[14:17]
	v_mfma_f32_16x16x32_bf16 v[2:5], v[110:113], v[224:227], v[2:5]
	s_setprio 0
	s_barrier
; #define PG8_STAGE(bufoff, gbase, voff) do { _Pragma("unroll") for (int _i = 0; _i < 2; ++_i) \
;         __builtin_amdgcn_global_load_lds((const unsigned*)((const char*)(gbase) + (voff)[_i]), (PG8_LAS unsigned*)(lds + (bufoff) + ldsw + _i * 8192), 16, 0, 0); } while (0)
; #define PG8_LDA(dst, b, h) do { _Pragma("unroll") for (int m = 0; m < 4; ++m) _Pragma("unroll") for (int k = 0; k < 2; ++k) dst[m][k] = *(const PG8_LAS bf16x8*)(lds + PG8_SA(b, h) + aoff + m * 2048 + k * 1024); } while (0)
; #define PG8_LDB(dst, b, h) do { _Pragma("unroll") for (int n = 0; n < 2; ++n) _Pragma("unroll") for (int k = 0; k < 2; ++k) dst[n][k] = *(const PG8_LAS bf16x8*)(lds + PG8_SB(b, h) + boff + n * 2048 + k * 1024); } while (0)
; #define PG8_MMA(ai, bj, At, Bt) do { __builtin_amdgcn_s_setprio(1); _Pragma("unroll") for (int m = 0; m < 4; ++m) _Pragma("unroll") for (int n = 0; n < 2; ++n) _Pragma("unroll") for (int k = 0; k < 2; ++k) \
;         acc[ai][bj][m][n] = __builtin_amdgcn_mfma_f32_16x16x32_bf16(Bt[n][k], At[m][k], acc[ai][bj][m][n], 0, 0, 0); __builtin_amdgcn_s_setprio(0); } while (0)
; #define PG8_WAIT_V(n) asm volatile("s_waitcnt vmcnt(" #n ")" ::: "memory")
; #define PG8_WAIT_L(n) asm volatile("s_waitcnt lgkmcnt(" #n ")" ::: "memory")
; #define PG8_BAR __builtin_amdgcn_s_barrier()
; #define PG8_SCHED __builtin_amdgcn_sched_barrier(0)
; template <class Epi, class Sched, bool ALIGN_EPI = false, bool SP2 = false>
; __device__ __forceinline__ void gemm_phase(PG8_LAS unsigned char* lds, const Gemm g, const Sched& S, const Epi& E) {
;     ...
;             PG8_LDB(B0, 1, 0); PG8_LDB(B1, 1, 1); PG8_SCHED; PG8_LDA(At, 1, 0); PG8_STAGE(PG8_SA(0, 1), a2 + hstep, voffA);
;             PG8_WAIT_V(8); PG8_WAIT_L(0); PG8_BAR; PG8_MMA(0, 0, At, B0); PG8_MMA(0, 1, At, B1); PG8_BAR; PG8_SCHED;
;             PG8_LDA(At, 1, 1); PG8_STAGE(PG8_SB(1, 0), b3, voffB); PG8_STAGE(PG8_SB(1, 1), b3 + hstep, voffB); PG8_STAGE(PG8_SA(1, 0), a3, voffA);
;             PG8_WAIT_V(8); PG8_WAIT_L(0); PG8_BAR; PG8_MMA(1, 0, At, B0); PG8_MMA(1, 1, At, B1); PG8_BAR; PG8_SCHED;
	ds_read_b128 v[82:85], v210
	ds_read_b128 v[86:89], v210 offset:1024
	ds_read_b128 v[90:93], v210 offset:2048
	ds_read_b128 v[94:97], v210 offset:3072
	ds_read_b128 v[98:101], v211
	ds_read_b128 v[102:105], v211 offset:1024
	ds_read_b128 v[106:109], v211 offset:2048
	ds_read_b128 v[110:113], v211 offset:3072
	s_add_u32 s72, s72, 0x80000
	s_addc_u32 s73, s73, 0
	s_mov_b32 m0, s58
	ds_read_b128 v[186:189], v209 offset:32768
	ds_read_b128 v[190:193], v209 offset:33792
	ds_read_b128 v[194:197], v209 offset:34816
	ds_read_b128 v[198:201], v209 offset:35840
	ds_read_b128 v[202:205], v209 offset:36864
	ds_read_b128 v[216:219], v209 offset:37888
	ds_read_b128 v[220:223], v209 offset:38912
	ds_read_b128 v[224:227], v209 offset:39936
	global_load_lds_dwordx4 v172, s[72:73]
	s_mov_b32 m0, s59
	s_nop 0
	global_load_lds_dwordx4 v168, s[72:73]
	s_waitcnt vmcnt(8)
	s_waitcnt lgkmcnt(0)
	s_barrier
	s_setprio 1
	s_waitcnt lgkmcnt(0)
	v_mfma_f32_16x16x32_bf16 v[158:161], v[82:85], v[186:189], v[158:161]
	v_mfma_f32_16x16x32_bf16 v[154:157], v[90:93], v[186:189], v[154:157]
	v_mfma_f32_16x16x32_bf16 v[142:145], v[82:85], v[194:197], v[142:145]
	v_mfma_f32_16x16x32_bf16 v[138:141], v[90:93], v[194:197], v[138:141]
	v_mfma_f32_16x16x32_bf16 v[126:129], v[82:85], v[202:205], v[126:129]
	v_mfma_f32_16x16x32_bf16 v[122:125], v[90:93], v[202:205], v[122:125]
	v_mfma_f32_16x16x32_bf16 v[78:81], v[82:85], v[220:223], v[78:81]
	v_mfma_f32_16x16x32_bf16 v[70:73], v[90:93], v[220:223], v[70:73]
	v_mfma_f32_16x16x32_bf16 v[158:161], v[86:89], v[190:193], v[158:161]
	v_mfma_f32_16x16x32_bf16 v[154:157], v[94:97], v[190:193], v[154:157]
	v_mfma_f32_16x16x32_bf16 v[142:145], v[86:89], v[198:201], v[142:145]
	v_mfma_f32_16x16x32_bf16 v[138:141], v[94:97], v[198:201], v[138:141]
	v_mfma_f32_16x16x32_bf16 v[126:129], v[86:89], v[216:219], v[126:129]
	v_mfma_f32_16x16x32_bf16 v[122:125], v[94:97], v[216:219], v[122:125]
	v_mfma_f32_16x16x32_bf16 v[78:81], v[86:89], v[224:227], v[78:81]
	v_mfma_f32_16x16x32_bf16 v[70:73], v[94:97], v[224:227], v[70:73]
	s_setprio 0
	s_setprio 1
	v_mfma_f32_16x16x32_bf16 v[150:153], v[98:101], v[186:189], v[150:153]
	v_mfma_f32_16x16x32_bf16 v[146:149], v[106:109], v[186:189], v[146:149]
	v_mfma_f32_16x16x32_bf16 v[134:137], v[98:101], v[194:197], v[134:137]
	v_mfma_f32_16x16x32_bf16 v[130:133], v[106:109], v[194:197], v[130:133]
	v_mfma_f32_16x16x32_bf16 v[118:121], v[98:101], v[202:205], v[118:121]
	v_mfma_f32_16x16x32_bf16 v[114:117], v[106:109], v[202:205], v[114:117]
	v_mfma_f32_16x16x32_bf16 v[74:77], v[98:101], v[220:223], v[74:77]
	v_mfma_f32_16x16x32_bf16 v[66:69], v[106:109], v[220:223], v[66:69]
	v_mfma_f32_16x16x32_bf16 v[150:153], v[102:105], v[190:193], v[150:153]
	v_mfma_f32_16x16x32_bf16 v[146:149], v[110:113], v[190:193], v[146:149]
	v_mfma_f32_16x16x32_bf16 v[134:137], v[102:105], v[198:201], v[134:137]
	v_mfma_f32_16x16x32_bf16 v[130:133], v[110:113], v[198:201], v[130:133]
	v_mfma_f32_16x16x32_bf16 v[118:121], v[102:105], v[216:219], v[118:121]
	v_mfma_f32_16x16x32_bf16 v[114:117], v[110:113], v[216:219], v[114:117]
	v_mfma_f32_16x16x32_bf16 v[74:77], v[102:105], v[224:227], v[74:77]
	v_mfma_f32_16x16x32_bf16 v[66:69], v[110:113], v[224:227], v[66:69]
	s_setprio 0
	s_barrier
	s_add_i32 s72, s77, s16
	v_lshl_add_u64 v[228:229], v[228:229], 0, s[28:29]
	s_mov_b32 m0, s72
	ds_read_b128 v[186:189], v209 offset:49152
	ds_read_b128 v[190:193], v209 offset:50176
	ds_read_b128 v[194:197], v209 offset:51200
	ds_read_b128 v[198:201], v209 offset:52224
	ds_read_b128 v[202:205], v209 offset:53248
	ds_read_b128 v[216:219], v209 offset:54272
	ds_read_b128 v[220:223], v209 offset:55296
	ds_read_b128 v[224:227], v209 offset:56320
	global_load_lds_dwordx4 v[228:229], off
	s_add_i32 m0, s72, 0x2000
	s_add_u32 s70, s70, 0x80080
	v_lshl_add_u64 v[228:229], v[230:231], 0, s[28:29]
	s_addc_u32 s71, s71, 0
	s_add_i32 s72, s78, s16
	global_load_lds_dwordx4 v[228:229], off
	s_mov_b32 m0, s72
	s_nop 0
	global_load_lds_dwordx4 v170, s[70:71]
	s_add_i32 m0, s72, 0x2000
	s_nop 0
	global_load_lds_dwordx4 v166, s[70:71]
	v_lshl_add_u64 v[228:229], v[232:233], 0, s[28:29]
	s_mov_b32 m0, s61
	s_nop 0
	global_load_lds_dwordx4 v[228:229], off
	v_lshl_add_u64 v[228:229], v[234:235], 0, s[28:29]
	s_mov_b32 m0, s62
	s_nop 0
	global_load_lds_dwordx4 v[228:229], off
	s_waitcnt vmcnt(8)
	s_waitcnt lgkmcnt(0)
	s_barrier
	s_setprio 1
	s_waitcnt lgkmcnt(0)
	v_mfma_f32_16x16x32_bf16 v[62:65], v[82:85], v[186:189], v[62:65]
	v_mfma_f32_16x16x32_bf16 v[58:61], v[90:93], v[186:189], v[58:61]
	v_mfma_f32_16x16x32_bf16 v[46:49], v[82:85], v[194:197], v[46:49]
	v_mfma_f32_16x16x32_bf16 v[42:45], v[90:93], v[194:197], v[42:45]
	v_mfma_f32_16x16x32_bf16 v[30:33], v[82:85], v[202:205], v[30:33]
	v_mfma_f32_16x16x32_bf16 v[26:29], v[90:93], v[202:205], v[26:29]
	v_mfma_f32_16x16x32_bf16 v[10:13], v[82:85], v[220:223], v[10:13]
	v_mfma_f32_16x16x32_bf16 v[6:9], v[90:93], v[220:223], v[6:9]
	v_mfma_f32_16x16x32_bf16 v[62:65], v[86:89], v[190:193], v[62:65]
	v_mfma_f32_16x16x32_bf16 v[58:61], v[94:97], v[190:193], v[58:61]
	v_mfma_f32_16x16x32_bf16 v[46:49], v[86:89], v[198:201], v[46:49]
	v_mfma_f32_16x16x32_bf16 v[42:45], v[94:97], v[198:201], v[42:45]
	v_mfma_f32_16x16x32_bf16 v[30:33], v[86:89], v[216:219], v[30:33]
	v_mfma_f32_16x16x32_bf16 v[26:29], v[94:97], v[216:219], v[26:29]
	v_mfma_f32_16x16x32_bf16 v[10:13], v[86:89], v[224:227], v[10:13]
	v_mfma_f32_16x16x32_bf16 v[6:9], v[94:97], v[224:227], v[6:9]
	s_setprio 0
	s_setprio 1
	v_mfma_f32_16x16x32_bf16 v[54:57], v[98:101], v[186:189], v[54:57]
	v_mfma_f32_16x16x32_bf16 v[50:53], v[106:109], v[186:189], v[50:53]
	v_mfma_f32_16x16x32_bf16 v[38:41], v[98:101], v[194:197], v[38:41]
	v_mfma_f32_16x16x32_bf16 v[34:37], v[106:109], v[194:197], v[34:37]
	v_mfma_f32_16x16x32_bf16 v[22:25], v[98:101], v[202:205], v[22:25]
	v_mfma_f32_16x16x32_bf16 v[18:21], v[106:109], v[202:205], v[18:21]
	v_mfma_f32_16x16x32_bf16 v[14:17], v[98:101], v[220:223], v[14:17]
	v_mfma_f32_16x16x32_bf16 v[2:5], v[106:109], v[220:223], v[2:5]
	v_mfma_f32_16x16x32_bf16 v[54:57], v[102:105], v[190:193], v[54:57]
	v_mfma_f32_16x16x32_bf16 v[50:53], v[110:113], v[190:193], v[50:53]
	v_mfma_f32_16x16x32_bf16 v[38:41], v[102:105], v[198:201], v[38:41]
	v_mfma_f32_16x16x32_bf16 v[34:37], v[110:113], v[198:201], v[34:37]
	v_mfma_f32_16x16x32_bf16 v[22:25], v[102:105], v[216:219], v[22:25]
	v_mfma_f32_16x16x32_bf16 v[18:21], v[110:113], v[216:219], v[18:21]
	v_mfma_f32_16x16x32_bf16 v[14:17], v[102:105], v[224:227], v[14:17]
	v_mfma_f32_16x16x32_bf16 v[2:5], v[110:113], v[224:227], v[2:5]
	s_setprio 0
	s_barrier
	s_add_i32 s86, s86, 2
	s_add_u32 s68, s68, 0x100
	s_addc_u32 s69, s69, 0
	s_add_u32 s84, s84, 0x100
	s_addc_u32 s85, s85, 0
	s_cmp_gt_u32 s86, 29
	s_cbranch_scc0 .LBB0_908
	s_and_b64 vcc, exec, s[38:39]
	s_cbranch_vccz .LBB0_911
	s_barrier

; #define PG8_STAGE(bufoff, gbase, voff) do { _Pragma("unroll") for (int _i = 0; _i < 2; ++_i) \
;         __builtin_amdgcn_global_load_lds((const unsigned*)((const char*)(gbase) + (voff)[_i]), (PG8_LAS unsigned*)(lds + (bufoff) + ldsw + _i * 8192), 16, 0, 0); } while (0)
; #define PG8_LDA(dst, b, h) do { _Pragma("unroll") for (int m = 0; m < 4; ++m) _Pragma("unroll") for (int k = 0; k < 2; ++k) dst[m][k] = *(const PG8_LAS bf16x8*)(lds + PG8_SA(b, h) + aoff + m * 2048 + k * 1024); } while (0)
; #define PG8_LDB(dst, b, h) do { _Pragma("unroll") for (int n = 0; n < 2; ++n) _Pragma("unroll") for (int k = 0; k < 2; ++k) dst[n][k] = *(const PG8_LAS bf16x8*)(lds + PG8_SB(b, h) + boff + n * 2048 + k * 1024); } while (0)
; #define PG8_MMA(ai, bj, At, Bt) do { __builtin_amdgcn_s_setprio(1); _Pragma("unroll") for (int m = 0; m < 4; ++m) _Pragma("unroll") for (int n = 0; n < 2; ++n) _Pragma("unroll") for (int k = 0; k < 2; ++k) \
;         acc[ai][bj][m][n] = __builtin_amdgcn_mfma_f32_16x16x32_bf16(Bt[n][k], At[m][k], acc[ai][bj][m][n], 0, 0, 0); __builtin_amdgcn_s_setprio(0); } while (0)
; #define PG8_WAIT_V(n) asm volatile("s_waitcnt vmcnt(" #n ")" ::: "memory")
; #define PG8_WAIT_L(n) asm volatile("s_waitcnt lgkmcnt(" #n ")" ::: "memory")
; #define PG8_BAR __builtin_amdgcn_s_barrier()
; template <class Epi, class Sched, bool ALIGN_EPI = false, bool SP2 = false>
; __device__ __forceinline__ void gemm_phase(PG8_LAS unsigned char* lds, const Gemm g, const Sched& S, const Epi& E) {
;     ...
;             const char* a1 = cA + (size_t)(t + 1) * kstep;
;             const char* a2 = last ? nA : cA + (size_t)(t + 2) * kstep; const char* b2 = last ? nB : cB + (size_t)(t + 2) * kstep;
;             const char* a3 = a2 + kstep; const char* b3 = b2 + kstep;
;             if (last && has_next) S.a_ready(nxt);
;             if constexpr (SP2) {
;             PG8_LDB(B0, 0, 0); PG8_LDB(B1, 0, 1); PG8_SCHED; PG8_LDA(At, 0, 0); PG8_STAGE(PG8_SA(1, 1), a1 + hstep, voffA);
;             PG8_WAIT_V(8); PG8_WAIT_L(0); PG8_BAR; PG8_MMA(0, 0, At, B0); PG8_MMA(0, 1, At, B1); PG8_BAR; PG8_SCHED;
;             PG8_LDA(At, 0, 1); PG8_STAGE(PG8_SB(0, 0), b2, voffB); PG8_STAGE(PG8_SB(0, 1), b2 + hstep, voffB); PG8_STAGE(PG8_SA(0, 0), a2, voffA);
;             PG8_WAIT_V(8); PG8_WAIT_L(0); PG8_BAR; PG8_MMA(1, 0, At, B0); PG8_MMA(1, 1, At, B1); PG8_BAR; PG8_SCHED;
.LBB0_994:
	ds_read_b128 v[146:149], v152
	ds_read_b128 v[158:161], v152 offset:1024
	ds_read_b128 v[166:169], v152 offset:2048
	ds_read_b128 v[170:173], v152 offset:3072
	ds_read_b128 v[174:177], v153
	ds_read_b128 v[178:181], v153 offset:1024
	ds_read_b128 v[182:185], v153 offset:2048
	ds_read_b128 v[186:189], v153 offset:3072
	s_add_u32 s38, s36, 0xffea0080
	s_addc_u32 s39, s37, -1
	s_cmpk_eq_i32 s63, 0x54
	s_cselect_b32 s41, s5, s39
	s_cselect_b32 s40, s4, s38
	s_cselect_b32 s39, s29, s62
	s_cselect_b32 s38, s28, s61
	s_add_i32 m0, s16, 0xc000
	ds_read_b128 v[190:193], v154
	ds_read_b128 v[194:197], v154 offset:1024
	ds_read_b128 v[198:201], v154 offset:2048
	ds_read_b128 v[202:205], v154 offset:3072
	ds_read_b128 v[208:211], v154 offset:4096
	ds_read_b128 v[212:215], v154 offset:5120
	ds_read_b128 v[216:219], v154 offset:6144
	ds_read_b128 v[220:223], v154 offset:7168
	global_load_lds_dwordx4 v138, s[36:37]
	s_add_i32 m0, s16, 0xe000
	s_nop 0
	global_load_lds_dwordx4 v140, s[36:37]
	s_waitcnt vmcnt(8)
	s_waitcnt lgkmcnt(0)
	s_barrier
	s_setprio 1
	s_waitcnt lgkmcnt(0)
	v_mfma_f32_16x16x32_bf16 v[126:129], v[146:149], v[190:193], v[126:129]
	v_mfma_f32_16x16x32_bf16 v[122:125], v[166:169], v[190:193], v[122:125]
	v_mfma_f32_16x16x32_bf16 v[110:113], v[146:149], v[198:201], v[110:113]
	v_mfma_f32_16x16x32_bf16 v[106:109], v[166:169], v[198:201], v[106:109]
	v_mfma_f32_16x16x32_bf16 v[94:97], v[146:149], v[208:211], v[94:97]
	v_mfma_f32_16x16x32_bf16 v[90:93], v[166:169], v[208:211], v[90:93]
	v_mfma_f32_16x16x32_bf16 v[78:81], v[146:149], v[216:219], v[78:81]
	v_mfma_f32_16x16x32_bf16 v[74:77], v[166:169], v[216:219], v[74:77]
	v_mfma_f32_16x16x32_bf16 v[126:129], v[158:161], v[194:197], v[126:129]
	v_mfma_f32_16x16x32_bf16 v[122:125], v[170:173], v[194:197], v[122:125]
	v_mfma_f32_16x16x32_bf16 v[110:113], v[158:161], v[202:205], v[110:113]
	v_mfma_f32_16x16x32_bf16 v[106:109], v[170:173], v[202:205], v[106:109]
	v_mfma_f32_16x16x32_bf16 v[94:97], v[158:161], v[212:215], v[94:97]
	v_mfma_f32_16x16x32_bf16 v[90:93], v[170:173], v[212:215], v[90:93]
	v_mfma_f32_16x16x32_bf16 v[78:81], v[158:161], v[220:223], v[78:81]
	v_mfma_f32_16x16x32_bf16 v[74:77], v[170:173], v[220:223], v[74:77]
	s_setprio 0
	s_setprio 1
	v_mfma_f32_16x16x32_bf16 v[118:121], v[174:177], v[190:193], v[118:121]
	v_mfma_f32_16x16x32_bf16 v[114:117], v[182:185], v[190:193], v[114:117]
	v_mfma_f32_16x16x32_bf16 v[102:105], v[174:177], v[198:201], v[102:105]
	v_mfma_f32_16x16x32_bf16 v[98:101], v[182:185], v[198:201], v[98:101]
	v_mfma_f32_16x16x32_bf16 v[86:89], v[174:177], v[208:211], v[86:89]
	v_mfma_f32_16x16x32_bf16 v[82:85], v[182:185], v[208:211], v[82:85]
	v_mfma_f32_16x16x32_bf16 v[70:73], v[174:177], v[216:219], v[70:73]
	v_mfma_f32_16x16x32_bf16 v[66:69], v[182:185], v[216:219], v[66:69]
	v_mfma_f32_16x16x32_bf16 v[118:121], v[178:181], v[194:197], v[118:121]
	v_mfma_f32_16x16x32_bf16 v[114:117], v[186:189], v[194:197], v[114:117]
	v_mfma_f32_16x16x32_bf16 v[102:105], v[178:181], v[202:205], v[102:105]
	v_mfma_f32_16x16x32_bf16 v[98:101], v[186:189], v[202:205], v[98:101]
	v_mfma_f32_16x16x32_bf16 v[86:89], v[178:181], v[212:215], v[86:89]
	v_mfma_f32_16x16x32_bf16 v[82:85], v[186:189], v[212:215], v[82:85]
	v_mfma_f32_16x16x32_bf16 v[70:73], v[178:181], v[220:223], v[70:73]
	v_mfma_f32_16x16x32_bf16 v[66:69], v[186:189], v[220:223], v[66:69]
	s_setprio 0
	s_barrier
	s_add_i32 s64, s47, s2
	v_lshl_add_u64 v[224:225], s[38:39], 0, v[132:133]
	s_mov_b32 m0, s64
	ds_read_b128 v[190:193], v154 offset:16384
	ds_read_b128 v[194:197], v154 offset:17408
	ds_read_b128 v[198:201], v154 offset:18432
	ds_read_b128 v[202:205], v154 offset:19456
	ds_read_b128 v[208:211], v154 offset:20480
	ds_read_b128 v[212:215], v154 offset:21504
	ds_read_b128 v[216:219], v154 offset:22528
	ds_read_b128 v[220:223], v154 offset:23552
	global_load_lds_dwordx4 v[224:225], off
	s_add_i32 m0, s64, 0x2000
	s_add_u32 s64, s38, 0x160000
	v_lshl_add_u64 v[226:227], s[38:39], 0, v[136:137]
	s_addc_u32 s65, s39, 0
	s_add_i32 s66, s48, s2
	global_load_lds_dwordx4 v[226:227], off
	s_mov_b32 m0, s66
	v_lshl_add_u64 v[230:231], s[40:41], 0, v[134:135]
	global_load_lds_dwordx4 v132, s[64:65]
	s_add_i32 m0, s66, 0x2000
	s_nop 0
	global_load_lds_dwordx4 v136, s[64:65]
	v_lshl_add_u64 v[228:229], s[40:41], 0, v[130:131]
	s_mov_b32 m0, s16
	s_nop 0
	global_load_lds_dwordx4 v[228:229], off
	s_mov_b32 m0, s17
	s_nop 0
	global_load_lds_dwordx4 v[230:231], off
	s_waitcnt vmcnt(8)
	s_waitcnt lgkmcnt(0)
	s_barrier
; #define PG8_STAGE(bufoff, gbase, voff) do { _Pragma("unroll") for (int _i = 0; _i < 2; ++_i) \
;         __builtin_amdgcn_global_load_lds((const unsigned*)((const char*)(gbase) + (voff)[_i]), (PG8_LAS unsigned*)(lds + (bufoff) + ldsw + _i * 8192), 16, 0, 0); } while (0)
; #define PG8_LDA(dst, b, h) do { _Pragma("unroll") for (int m = 0; m < 4; ++m) _Pragma("unroll") for (int k = 0; k < 2; ++k) dst[m][k] = *(const PG8_LAS bf16x8*)(lds + PG8_SA(b, h) + aoff + m * 2048 + k * 1024); } while (0)
; #define PG8_LDB(dst, b, h) do { _Pragma("unroll") for (int n = 0; n < 2; ++n) _Pragma("unroll") for (int k = 0; k < 2; ++k) dst[n][k] = *(const PG8_LAS bf16x8*)(lds + PG8_SB(b, h) + boff + n * 2048 + k * 1024); } while (0)
; #define PG8_MMA(ai, bj, At, Bt) do { __builtin_amdgcn_s_setprio(1); _Pragma("unroll") for (int m = 0; m < 4; ++m) _Pragma("unroll") for (int n = 0; n < 2; ++n) _Pragma("unroll") for (int k = 0; k < 2; ++k) \
;         acc[ai][bj][m][n] = __builtin_amdgcn_mfma_f32_16x16x32_bf16(Bt[n][k], At[m][k], acc[ai][bj][m][n], 0, 0, 0); __builtin_amdgcn_s_setprio(0); } while (0)
; #define PG8_WAIT_V(n) asm volatile("s_waitcnt vmcnt(" #n ")" ::: "memory")
; #define PG8_WAIT_L(n) asm volatile("s_waitcnt lgkmcnt(" #n ")" ::: "memory")
; #define PG8_BAR __builtin_amdgcn_s_barrier()
; #define PG8_SCHED __builtin_amdgcn_sched_barrier(0)
; template <class Epi, class Sched, bool ALIGN_EPI = false, bool SP2 = false>
; __device__ __forceinline__ void gemm_phase(PG8_LAS unsigned char* lds, const Gemm g, const Sched& S, const Epi& E) {
;     ...
;             PG8_WAIT_V(8); PG8_WAIT_L(0); PG8_BAR; PG8_MMA(1, 0, At, B0); PG8_MMA(1, 1, At, B1); PG8_BAR; PG8_SCHED;
;             PG8_LDB(B0, 1, 0); PG8_LDB(B1, 1, 1); PG8_SCHED; PG8_LDA(At, 1, 0); PG8_STAGE(PG8_SA(0, 1), a2 + hstep, voffA);
;             PG8_WAIT_V(8); PG8_WAIT_L(0); PG8_BAR; PG8_MMA(0, 0, At, B0); PG8_MMA(0, 1, At, B1); PG8_BAR; PG8_SCHED;
	s_setprio 1
	s_waitcnt lgkmcnt(0)
	v_mfma_f32_16x16x32_bf16 v[62:65], v[146:149], v[190:193], v[62:65]
	v_mfma_f32_16x16x32_bf16 v[58:61], v[166:169], v[190:193], v[58:61]
	v_mfma_f32_16x16x32_bf16 v[46:49], v[146:149], v[198:201], v[46:49]
	v_mfma_f32_16x16x32_bf16 v[42:45], v[166:169], v[198:201], v[42:45]
	v_mfma_f32_16x16x32_bf16 v[30:33], v[146:149], v[208:211], v[30:33]
	v_mfma_f32_16x16x32_bf16 v[26:29], v[166:169], v[208:211], v[26:29]
	v_mfma_f32_16x16x32_bf16 v[14:17], v[146:149], v[216:219], v[14:17]
	v_mfma_f32_16x16x32_bf16 v[10:13], v[166:169], v[216:219], v[10:13]
	v_mfma_f32_16x16x32_bf16 v[62:65], v[158:161], v[194:197], v[62:65]
	v_mfma_f32_16x16x32_bf16 v[58:61], v[170:173], v[194:197], v[58:61]
	v_mfma_f32_16x16x32_bf16 v[46:49], v[158:161], v[202:205], v[46:49]
	v_mfma_f32_16x16x32_bf16 v[42:45], v[170:173], v[202:205], v[42:45]
	v_mfma_f32_16x16x32_bf16 v[30:33], v[158:161], v[212:215], v[30:33]
	v_mfma_f32_16x16x32_bf16 v[26:29], v[170:173], v[212:215], v[26:29]
	v_mfma_f32_16x16x32_bf16 v[14:17], v[158:161], v[220:223], v[14:17]
	v_mfma_f32_16x16x32_bf16 v[10:13], v[170:173], v[220:223], v[10:13]
	s_setprio 0
	s_setprio 1
	v_mfma_f32_16x16x32_bf16 v[54:57], v[174:177], v[190:193], v[54:57]
	v_mfma_f32_16x16x32_bf16 v[50:53], v[182:185], v[190:193], v[50:53]
	v_mfma_f32_16x16x32_bf16 v[38:41], v[174:177], v[198:201], v[38:41]
	v_mfma_f32_16x16x32_bf16 v[34:37], v[182:185], v[198:201], v[34:37]
	v_mfma_f32_16x16x32_bf16 v[22:25], v[174:177], v[208:211], v[22:25]
	v_mfma_f32_16x16x32_bf16 v[18:21], v[182:185], v[208:211], v[18:21]
	v_mfma_f32_16x16x32_bf16 v[6:9], v[174:177], v[216:219], v[6:9]
	v_mfma_f32_16x16x32_bf16 v[2:5], v[182:185], v[216:219], v[2:5]
	v_mfma_f32_16x16x32_bf16 v[54:57], v[178:181], v[194:197], v[54:57]
	v_mfma_f32_16x16x32_bf16 v[50:53], v[186:189], v[194:197], v[50:53]
	v_mfma_f32_16x16x32_bf16 v[38:41], v[178:181], v[202:205], v[38:41]
	v_mfma_f32_16x16x32_bf16 v[34:37], v[186:189], v[202:205], v[34:37]
	v_mfma_f32_16x16x32_bf16 v[22:25], v[178:181], v[212:215], v[22:25]
	v_mfma_f32_16x16x32_bf16 v[18:21], v[186:189], v[212:215], v[18:21]
	v_mfma_f32_16x16x32_bf16 v[6:9], v[178:181], v[220:223], v[6:9]
	v_mfma_f32_16x16x32_bf16 v[2:5], v[186:189], v[220:223], v[2:5]
	s_setprio 0
	s_barrier
	ds_read_b128 v[146:149], v155
	ds_read_b128 v[158:161], v155 offset:1024
	ds_read_b128 v[166:169], v155 offset:2048
	ds_read_b128 v[170:173], v155 offset:3072
	ds_read_b128 v[174:177], v156
	ds_read_b128 v[178:181], v156 offset:1024
	ds_read_b128 v[182:185], v156 offset:2048
	ds_read_b128 v[186:189], v156 offset:3072
	s_add_u32 s40, s40, 0x160000
	s_addc_u32 s41, s41, 0
	s_mov_b32 m0, s33
	ds_read_b128 v[190:193], v154 offset:32768
	ds_read_b128 v[194:197], v154 offset:33792
	ds_read_b128 v[198:201], v154 offset:34816
	ds_read_b128 v[202:205], v154 offset:35840
	ds_read_b128 v[208:211], v154 offset:36864
	ds_read_b128 v[212:215], v154 offset:37888
	ds_read_b128 v[216:219], v154 offset:38912
	ds_read_b128 v[220:223], v154 offset:39936
	global_load_lds_dwordx4 v130, s[40:41]
	s_mov_b32 m0, s35
	s_nop 0
	global_load_lds_dwordx4 v134, s[40:41]
	s_waitcnt vmcnt(8)
	s_waitcnt lgkmcnt(0)
	s_barrier
	s_setprio 1
	s_waitcnt lgkmcnt(0)
	v_mfma_f32_16x16x32_bf16 v[126:129], v[146:149], v[190:193], v[126:129]
	v_mfma_f32_16x16x32_bf16 v[122:125], v[166:169], v[190:193], v[122:125]
	v_mfma_f32_16x16x32_bf16 v[110:113], v[146:149], v[198:201], v[110:113]
	v_mfma_f32_16x16x32_bf16 v[106:109], v[166:169], v[198:201], v[106:109]
	v_mfma_f32_16x16x32_bf16 v[94:97], v[146:149], v[208:211], v[94:97]
	v_mfma_f32_16x16x32_bf16 v[90:93], v[166:169], v[208:211], v[90:93]
	v_mfma_f32_16x16x32_bf16 v[78:81], v[146:149], v[216:219], v[78:81]
	v_mfma_f32_16x16x32_bf16 v[74:77], v[166:169], v[216:219], v[74:77]
	v_mfma_f32_16x16x32_bf16 v[126:129], v[158:161], v[194:197], v[126:129]
	v_mfma_f32_16x16x32_bf16 v[122:125], v[170:173], v[194:197], v[122:125]
	v_mfma_f32_16x16x32_bf16 v[110:113], v[158:161], v[202:205], v[110:113]
	v_mfma_f32_16x16x32_bf16 v[106:109], v[170:173], v[202:205], v[106:109]
	v_mfma_f32_16x16x32_bf16 v[94:97], v[158:161], v[212:215], v[94:97]
	v_mfma_f32_16x16x32_bf16 v[90:93], v[170:173], v[212:215], v[90:93]
	v_mfma_f32_16x16x32_bf16 v[78:81], v[158:161], v[220:223], v[78:81]
	v_mfma_f32_16x16x32_bf16 v[74:77], v[170:173], v[220:223], v[74:77]
	s_setprio 0
	s_setprio 1
	v_mfma_f32_16x16x32_bf16 v[118:121], v[174:177], v[190:193], v[118:121]
	v_mfma_f32_16x16x32_bf16 v[114:117], v[182:185], v[190:193], v[114:117]
	v_mfma_f32_16x16x32_bf16 v[102:105], v[174:177], v[198:201], v[102:105]
	v_mfma_f32_16x16x32_bf16 v[98:101], v[182:185], v[198:201], v[98:101]
	v_mfma_f32_16x16x32_bf16 v[86:89], v[174:177], v[208:211], v[86:89]
	v_mfma_f32_16x16x32_bf16 v[82:85], v[182:185], v[208:211], v[82:85]
	v_mfma_f32_16x16x32_bf16 v[70:73], v[174:177], v[216:219], v[70:73]
	v_mfma_f32_16x16x32_bf16 v[66:69], v[182:185], v[216:219], v[66:69]
	v_mfma_f32_16x16x32_bf16 v[118:121], v[178:181], v[194:197], v[118:121]
	v_mfma_f32_16x16x32_bf16 v[114:117], v[186:189], v[194:197], v[114:117]
	v_mfma_f32_16x16x32_bf16 v[102:105], v[178:181], v[202:205], v[102:105]
	v_mfma_f32_16x16x32_bf16 v[98:101], v[186:189], v[202:205], v[98:101]
	v_mfma_f32_16x16x32_bf16 v[86:89], v[178:181], v[212:215], v[86:89]
	v_mfma_f32_16x16x32_bf16 v[82:85], v[186:189], v[212:215], v[82:85]
	v_mfma_f32_16x16x32_bf16 v[70:73], v[178:181], v[220:223], v[70:73]
	v_mfma_f32_16x16x32_bf16 v[66:69], v[186:189], v[220:223], v[66:69]
	s_setprio 0
	s_barrier
; #define PG8_STAGE(bufoff, gbase, voff) do { _Pragma("unroll") for (int _i = 0; _i < 2; ++_i) \
;         __builtin_amdgcn_global_load_lds((const unsigned*)((const char*)(gbase) + (voff)[_i]), (PG8_LAS unsigned*)(lds + (bufoff) + ldsw + _i * 8192), 16, 0, 0); } while (0)
; #define PG8_LDA(dst, b, h) do { _Pragma("unroll") for (int m = 0; m < 4; ++m) _Pragma("unroll") for (int k = 0; k < 2; ++k) dst[m][k] = *(const PG8_LAS bf16x8*)(lds + PG8_SA(b, h) + aoff + m * 2048 + k * 1024); } while (0)
; #define PG8_MMA(ai, bj, At, Bt) do { __builtin_amdgcn_s_setprio(1); _Pragma("unroll") for (int m = 0; m < 4; ++m) _Pragma("unroll") for (int n = 0; n < 2; ++n) _Pragma("unroll") for (int k = 0; k < 2; ++k) \
;         acc[ai][bj][m][n] = __builtin_amdgcn_mfma_f32_16x16x32_bf16(Bt[n][k], At[m][k], acc[ai][bj][m][n], 0, 0, 0); __builtin_amdgcn_s_setprio(0); } while (0)
; #define PG8_WAIT_V(n) asm volatile("s_waitcnt vmcnt(" #n ")" ::: "memory")
; #define PG8_WAIT_L(n) asm volatile("s_waitcnt lgkmcnt(" #n ")" ::: "memory")
; #define PG8_BAR __builtin_amdgcn_s_barrier()
; #define PG8_SCHED __builtin_amdgcn_sched_barrier(0)
; template <class Epi, class Sched, bool ALIGN_EPI = false, bool SP2 = false>
; __device__ __forceinline__ void gemm_phase(PG8_LAS unsigned char* lds, const Gemm g, const Sched& S, const Epi& E) {
;     ...
;             PG8_LDA(At, 1, 1); PG8_STAGE(PG8_SB(1, 0), b3, voffB); PG8_STAGE(PG8_SB(1, 1), b3 + hstep, voffB); PG8_STAGE(PG8_SA(1, 0), a3, voffA);
;             PG8_WAIT_V(8); PG8_WAIT_L(0); PG8_BAR; PG8_MMA(1, 0, At, B0); PG8_MMA(1, 1, At, B1); PG8_BAR; PG8_SCHED;
	s_add_i32 s40, s49, s2
	v_lshl_add_u64 v[224:225], v[224:225], 0, s[14:15]
	s_mov_b32 m0, s40
	ds_read_b128 v[190:193], v154 offset:49152
	ds_read_b128 v[194:197], v154 offset:50176
	ds_read_b128 v[198:201], v154 offset:51200
	ds_read_b128 v[202:205], v154 offset:52224
	ds_read_b128 v[208:211], v154 offset:53248
	ds_read_b128 v[212:215], v154 offset:54272
	ds_read_b128 v[216:219], v154 offset:55296
	ds_read_b128 v[220:223], v154 offset:56320
	global_load_lds_dwordx4 v[224:225], off
	s_add_i32 m0, s40, 0x2000
	s_add_u32 s38, s38, 0x160080
	v_lshl_add_u64 v[224:225], v[226:227], 0, s[14:15]
	s_addc_u32 s39, s39, 0
	s_add_i32 s40, s50, s2
	global_load_lds_dwordx4 v[224:225], off
	s_mov_b32 m0, s40
	s_nop 0
	global_load_lds_dwordx4 v132, s[38:39]
	s_add_i32 m0, s40, 0x2000
	s_nop 0
	global_load_lds_dwordx4 v136, s[38:39]
	v_lshl_add_u64 v[224:225], v[228:229], 0, s[14:15]
	s_mov_b32 m0, s42
	s_nop 0
	global_load_lds_dwordx4 v[224:225], off
	v_lshl_add_u64 v[224:225], v[230:231], 0, s[14:15]
	s_mov_b32 m0, s43
	s_nop 0
	global_load_lds_dwordx4 v[224:225], off
	s_waitcnt vmcnt(8)
	s_waitcnt lgkmcnt(0)
	s_barrier
	s_setprio 1
	s_waitcnt lgkmcnt(0)
	v_mfma_f32_16x16x32_bf16 v[62:65], v[146:149], v[190:193], v[62:65]
	v_mfma_f32_16x16x32_bf16 v[58:61], v[166:169], v[190:193], v[58:61]
	v_mfma_f32_16x16x32_bf16 v[46:49], v[146:149], v[198:201], v[46:49]
	v_mfma_f32_16x16x32_bf16 v[42:45], v[166:169], v[198:201], v[42:45]
	v_mfma_f32_16x16x32_bf16 v[30:33], v[146:149], v[208:211], v[30:33]
	v_mfma_f32_16x16x32_bf16 v[26:29], v[166:169], v[208:211], v[26:29]
	v_mfma_f32_16x16x32_bf16 v[14:17], v[146:149], v[216:219], v[14:17]
	v_mfma_f32_16x16x32_bf16 v[10:13], v[166:169], v[216:219], v[10:13]
	v_mfma_f32_16x16x32_bf16 v[62:65], v[158:161], v[194:197], v[62:65]
	v_mfma_f32_16x16x32_bf16 v[58:61], v[170:173], v[194:197], v[58:61]
	v_mfma_f32_16x16x32_bf16 v[46:49], v[158:161], v[202:205], v[46:49]
	v_mfma_f32_16x16x32_bf16 v[42:45], v[170:173], v[202:205], v[42:45]
	v_mfma_f32_16x16x32_bf16 v[30:33], v[158:161], v[212:215], v[30:33]
	v_mfma_f32_16x16x32_bf16 v[26:29], v[170:173], v[212:215], v[26:29]
	v_mfma_f32_16x16x32_bf16 v[14:17], v[158:161], v[220:223], v[14:17]
	v_mfma_f32_16x16x32_bf16 v[10:13], v[170:173], v[220:223], v[10:13]
	s_setprio 0
	s_setprio 1
	v_mfma_f32_16x16x32_bf16 v[54:57], v[174:177], v[190:193], v[54:57]
	v_mfma_f32_16x16x32_bf16 v[50:53], v[182:185], v[190:193], v[50:53]
	v_mfma_f32_16x16x32_bf16 v[38:41], v[174:177], v[198:201], v[38:41]
	v_mfma_f32_16x16x32_bf16 v[34:37], v[182:185], v[198:201], v[34:37]
	v_mfma_f32_16x16x32_bf16 v[22:25], v[174:177], v[208:211], v[22:25]
	v_mfma_f32_16x16x32_bf16 v[18:21], v[182:185], v[208:211], v[18:21]
	v_mfma_f32_16x16x32_bf16 v[6:9], v[174:177], v[216:219], v[6:9]
	v_mfma_f32_16x16x32_bf16 v[2:5], v[182:185], v[216:219], v[2:5]
	v_mfma_f32_16x16x32_bf16 v[54:57], v[178:181], v[194:197], v[54:57]
	v_mfma_f32_16x16x32_bf16 v[50:53], v[186:189], v[194:197], v[50:53]
	v_mfma_f32_16x16x32_bf16 v[38:41], v[178:181], v[202:205], v[38:41]
	v_mfma_f32_16x16x32_bf16 v[34:37], v[186:189], v[202:205], v[34:37]
	v_mfma_f32_16x16x32_bf16 v[22:25], v[178:181], v[212:215], v[22:25]
	v_mfma_f32_16x16x32_bf16 v[18:21], v[186:189], v[212:215], v[18:21]
	v_mfma_f32_16x16x32_bf16 v[6:9], v[178:181], v[220:223], v[6:9]
	v_mfma_f32_16x16x32_bf16 v[2:5], v[186:189], v[220:223], v[2:5]
	s_setprio 0
	s_barrier
	s_add_i32 s63, s63, 2
	s_add_u32 s36, s36, 0x100
	s_addc_u32 s37, s37, 0
	s_add_u32 s61, s61, 0x100
	s_addc_u32 s62, s62, 0
	s_cmpk_gt_u32 s63, 0x55
	s_cbranch_scc0 .LBB0_994
	s_and_b64 vcc, exec, s[26:27]
	s_cbranch_vccz .LBB0_997
	s_barrier
